# no setprio in K-loops, static prio1 waves0-3, grid-barrier L1 invalidate moved to wave1 at arrival (overlaps the wait)
# speedup vs baseline: 1.0120x; 1.0120x over previous
; #define LAS __attribute__((address_space(3)))
; __device__ __forceinline__ unsigned xb_add(unsigned* p, unsigned v) { return __hip_atomic_fetch_add(p, v, __ATOMIC_RELAXED, __HIP_MEMORY_SCOPE_AGENT); }
; __device__ __forceinline__ unsigned xb_xcc_id() { return (unsigned)__builtin_amdgcn_s_getreg((3 << 11) | 20) & 0xFu; }
; __device__ __forceinline__ XcdBarrier xcd_barrier_post(unsigned* bar, volatile LAS unsigned* st) {
;     XcdBarrier b; b.bar = bar; b.x = xb_xcc_id(); b.st = st;
;     if (threadIdx.x == 0) (void)xb_add(&bar[XB_XCNT(b.x)], 1u);
;     return b;
; __global__ void __launch_bounds__(512, 2) mega_fwd(Params p) {
;     extern __shared__ __attribute__((aligned(16))) unsigned char lds_raw[];
;     LAS unsigned char* lds = (LAS unsigned char*)lds_raw;
;     const int lo = p.ph_lo, hi = p.ph_hi;
;     ...
;     unsigned char* ws = p.ws;
;     volatile LAS unsigned* stw = (volatile LAS unsigned*)(lds + LDS_STAGE);
;     if (threadIdx.x < 4) stw[threadIdx.x] = 0u;
;     __syncthreads();
;     XcdBarrier bar; bar.bar = (unsigned*)(ws + OFF_BAR); bar.x = 0; bar.st = stw;
;     if (hi - lo > 1) bar = xcd_barrier_post((unsigned*)(ws + OFF_BAR), stw);
_Z8mega_fwd6Params:
	s_load_dwordx8 s[88:95], s[0:1], 0x80
	v_readfirstlane_b32 s3, v0
	s_lshr_b32 s3, s3, 6
	s_cmp_ge_u32 s3, 4
	s_cbranch_scc1 .Lmy_prio_done
	s_setprio 1
.Lmy_prio_done:
	s_load_dwordx4 s[28:31], s[0:1], 0xa0
	s_load_dwordx2 s[34:35], s[0:1], 0xb0
	v_cmp_gt_u32_e32 vcc, 4, v0
	s_and_saveexec_b64 s[4:5], vcc
	v_lshl_add_u32 v1, v0, 2, 0
	v_add_u32_e32 v1, 0x20000, v1
	v_mov_b32_e32 v2, 0
	ds_write_b32 v1, v2
	s_or_b64 exec, exec, s[4:5]
	s_load_dwordx16 s[12:27], s[0:1], 0x0
	s_waitcnt lgkmcnt(0)
	s_add_u32 s60, s30, 0xb4b8000
	s_addc_u32 s61, s31, 0
	s_sub_i32 s3, s35, s34
	s_cmp_lt_i32 s3, 2
	s_mov_b32 s33, 0
	s_barrier
	s_cbranch_scc1 .LBB0_7
	s_getreg_b32 s3, hwreg(HW_REG_XCC_ID, 0, 4)
	s_and_b32 s33, s3, 15
	v_cmp_eq_u32_e32 vcc, 0, v0
	s_and_saveexec_b64 s[4:5], vcc
	s_cbranch_execz .LBB0_6
	s_mov_b64 s[6:7], exec
	v_mbcnt_lo_u32_b32 v1, s6, 0
	v_mbcnt_hi_u32_b32 v1, s7, v1
	v_cmp_eq_u32_e32 vcc, 0, v1
	s_and_b64 s[8:9], exec, vcc
	s_mov_b64 exec, s[8:9]
	s_cbranch_execz .LBB0_6
	s_lshl_b32 s3, s33, 8
	s_bcnt1_i32_b64 s6, s[6:7]
	v_mov_b32_e32 v1, s3
	v_mov_b32_e32 v2, s6
	global_atomic_add v1, v2, s[60:61] offset:1024

; __device__ __forceinline__ unsigned xb_add(unsigned* p, unsigned v) { return __hip_atomic_fetch_add(p, v, __ATOMIC_RELAXED, __HIP_MEMORY_SCOPE_AGENT); }
; __device__ __forceinline__ void xcd_barrier(const XcdBarrier& b) {
;     asm volatile("s_waitcnt vmcnt(0)" ::: "memory");
;     __syncthreads();
;     if (threadIdx.x == 0) {
;         unsigned* bar = b.bar;
;         __builtin_amdgcn_s_waitcnt(0);
;         unsigned nloc = b.st[0], nx = b.st[1];
;         if (nloc == 0u) { xcd_barrier_complete(bar, b.x, nloc, nx); b.st[0] = nloc; b.st[1] = nx; }
;         const unsigned old = xb_add(&bar[XB_XSUB(b.x)], 1u);
;         const unsigned gen = old / nloc;
;         if (old + 1u == (gen + 1u) * nloc) {
.LBB0_90:
	s_cmp_gt_i32 s35, 1
	s_cselect_b64 s[4:5], -1, 0
	s_and_b64 s[6:7], s[10:11], s[4:5]
	s_andn2_b64 vcc, exec, s[6:7]
	s_cbranch_vccnz .LBB0_140
	s_waitcnt vmcnt(0)
	v_cmp_eq_u32_e32 vcc, 0, v0
	s_waitcnt lgkmcnt(0)
	s_barrier
	v_readfirstlane_b32 s98, v0
	s_nop 3
	s_lshr_b32 s98, s98, 6
	s_cmp_lg_u32 s98, 1
	s_cbranch_scc1 .Lmy_noinv1
	buffer_inv sc1
	s_waitcnt vmcnt(0)
.Lmy_noinv1:
	s_and_saveexec_b64 s[6:7], vcc
	s_cbranch_execz .LBB0_139
	s_add_i32 s3, 0, 0x20000
	v_mov_b32_e32 v1, s3
	s_waitcnt vmcnt(0) expcnt(0) lgkmcnt(0)
	ds_read_b32 v3, v1
	s_add_i32 s3, 0, 0x20004
	v_mov_b32_e32 v1, s3
	ds_read_b32 v1, v1
	s_waitcnt lgkmcnt(1)
	v_cmp_ne_u32_e32 vcc, 0, v3
	s_cbranch_vccnz .LBB0_107
	s_load_dwordx2 s[12:13], s[0:1], 0xb8
	s_load_dword s3, s[0:1], 0xc0
	s_add_u32 s8, s30, 0xb4b8200
	s_addc_u32 s9, s31, 0
	s_add_u32 s10, s30, 0xb4b8400
	s_waitcnt lgkmcnt(0)
	s_mul_i32 s11, s13, s12
	s_mul_i32 s3, s11, s3
	s_addc_u32 s11, s31, 0
	s_add_u32 s12, s30, 0xb4b8500
	s_addc_u32 s13, s31, 0
	s_add_u32 s14, s30, 0xb4b8600
	s_addc_u32 s15, s31, 0
	s_add_u32 s62, s30, 0xb4b8700
	s_addc_u32 s63, s31, 0
	s_add_u32 s64, s30, 0xb4b8800
	s_addc_u32 s65, s31, 0
	s_add_u32 s66, s30, 0xb4b8900
	s_addc_u32 s67, s31, 0
	s_add_u32 s68, s30, 0xb4b8a00
	s_addc_u32 s69, s31, 0
	s_add_u32 s70, s30, 0xb4b8b00
	s_addc_u32 s71, s31, 0
	s_add_u32 s72, s30, 0xb4b8c00
	s_addc_u32 s73, s31, 0
	s_add_u32 s74, s30, 0xb4b8d00
	s_addc_u32 s75, s31, 0
	s_add_u32 s76, s30, 0xb4b8e00
	s_addc_u32 s77, s31, 0
	s_add_u32 s78, s30, 0xb4b8f00
	s_addc_u32 s79, s31, 0
	s_add_u32 s80, s30, 0xb4b9000
	s_addc_u32 s81, s31, 0
	s_add_u32 s82, s30, 0xb4b9100
	s_addc_u32 s83, s31, 0
	s_add_u32 s84, s30, 0xb4b9200
	s_addc_u32 s85, s31, 0
	s_add_u32 s86, s30, 0xb4b9300
	s_addc_u32 s87, s31, 0
	s_mov_b32 s52, 1
	v_mov_b32_e32 v17, 0
	s_branch .LBB0_95

; __device__ __forceinline__ unsigned xb_ld(unsigned* p)              { return __hip_atomic_load(p, __ATOMIC_RELAXED, __HIP_MEMORY_SCOPE_AGENT); }
; __device__ __forceinline__ unsigned xb_add(unsigned* p, unsigned v) { return __hip_atomic_fetch_add(p, v, __ATOMIC_RELAXED, __HIP_MEMORY_SCOPE_AGENT); }
; #define XB_SPIN(cond, bar) do { unsigned _sp = 0; while (cond) { __builtin_amdgcn_s_sleep(1); \
;     if ((++_sp & 255u) == 0u) { if (xb_ld(&(bar)[XB_TMO])) break; if (_sp > XB_SPIN_CAP) { atomicAdd(&(bar)[XB_TMO], 1u); break; } } } } while (0)
; __device__ __forceinline__ void xcd_barrier(const XcdBarrier& b) {
;     ...
;             __builtin_amdgcn_fence(__ATOMIC_RELEASE, "agent");
;             asm volatile("s_waitcnt vmcnt(0)" ::: "memory");
;             const unsigned og = xb_add(&bar[XB_TOP], 1u);
;             const unsigned tg = og / nx;
;             if (og + 1u == (tg + 1u) * nx) xb_add(&bar[XB_TOPGEN], 1u);
;             else XB_SPIN(xb_ld(&bar[XB_TOPGEN]) == tg, bar);
;             __builtin_amdgcn_fence(__ATOMIC_ACQUIRE, "agent");
;             asm volatile("s_waitcnt vmcnt(0)" ::: "memory");
;         } else {
;             XB_SPIN(xb_ld(&bar[XB_TOPGEN]) == gen, bar);
;             __builtin_amdgcn_fence(__ATOMIC_ACQUIRE, "agent");
;             asm volatile("s_waitcnt vmcnt(0)" ::: "memory");
.LBB0_120:
	s_or_b64 exec, exec, s[10:11]
	s_waitcnt vmcnt(0)
	s_waitcnt vmcnt(0)

; __device__ __forceinline__ unsigned xb_ld(unsigned* p)              { return __hip_atomic_load(p, __ATOMIC_RELAXED, __HIP_MEMORY_SCOPE_AGENT); }
; __device__ __forceinline__ unsigned xb_add(unsigned* p, unsigned v) { return __hip_atomic_fetch_add(p, v, __ATOMIC_RELAXED, __HIP_MEMORY_SCOPE_AGENT); }
; #define XB_SPIN(cond, bar) do { unsigned _sp = 0; while (cond) { __builtin_amdgcn_s_sleep(1); \
;     if ((++_sp & 255u) == 0u) { if (xb_ld(&(bar)[XB_TMO])) break; if (_sp > XB_SPIN_CAP) { atomicAdd(&(bar)[XB_TMO], 1u); break; } } } } while (0)
; __device__ __forceinline__ void xcd_barrier(const XcdBarrier& b) {
;     ...
;             __builtin_amdgcn_fence(__ATOMIC_RELEASE, "agent");
;             asm volatile("s_waitcnt vmcnt(0)" ::: "memory");
;             const unsigned og = xb_add(&bar[XB_TOP], 1u);
;             const unsigned tg = og / nx;
;             if (og + 1u == (tg + 1u) * nx) xb_add(&bar[XB_TOPGEN], 1u);
;             else XB_SPIN(xb_ld(&bar[XB_TOPGEN]) == tg, bar);
;             __builtin_amdgcn_fence(__ATOMIC_ACQUIRE, "agent");
;             asm volatile("s_waitcnt vmcnt(0)" ::: "memory");
;         } else {
;             XB_SPIN(xb_ld(&bar[XB_TOPGEN]) == gen, bar);
;             __builtin_amdgcn_fence(__ATOMIC_ACQUIRE, "agent");
;             asm volatile("s_waitcnt vmcnt(0)" ::: "memory");
.LBB0_138:
	s_or_b64 exec, exec, s[8:9]
	s_waitcnt vmcnt(0)
	s_waitcnt vmcnt(0)

; #define PG8_STAGEA(bufoff, gbase) PG8_STAGE_(bufoff, gbase, voffA)
; #define PG8_STAGEB(bufoff, gbase) PG8_STAGE_(bufoff, gbase, voffB)
; #define PG8_LDA(dst, b, h) do { _Pragma("unroll") for (int m = 0; m < 4; ++m) _Pragma("unroll") for (int k = 0; k < 2; ++k) dst[m][k] = *(const LAS bf16x8*)(lds + PG8_SA(b, h) + aoff + m * 2048 + k * 1024); } while (0)
; #define PG8_LDB(dst, b, h) do { _Pragma("unroll") for (int n = 0; n < 2; ++n) _Pragma("unroll") for (int k = 0; k < 2; ++k) dst[n][k] = *(const LAS bf16x8*)(lds + PG8_SB(b, h) + boff + n * 2048 + k * 1024); } while (0)
; #define PG8_MMA(ai, bj, At, Bt_) do { __builtin_amdgcn_s_setprio(1); _Pragma("unroll") for (int m = 0; m < 4; ++m) _Pragma("unroll") for (int n = 0; n < 2; ++n) _Pragma("unroll") for (int k = 0; k < 2; ++k) \
;         acc[ai][bj][m][n] = __builtin_amdgcn_mfma_f32_16x16x32_bf16(Bt_[n][k], At[m][k], acc[ai][bj][m][n], 0, 0, 0); __builtin_amdgcn_s_setprio(0); } while (0)
; #define PG8_WAIT_V(n) asm volatile("s_waitcnt vmcnt(" #n ")" ::: "memory")
; #define PG8_WAIT_L(n) asm volatile("s_waitcnt lgkmcnt(" #n ")" ::: "memory")
; #define PG8_BAR __builtin_amdgcn_s_barrier()
; template <int EK, int SK = -1>
; __device__ __forceinline__ void gemm_phase(LAS unsigned char* lds, const bf16_t* A, const bf16_t* Bt, int nM, int N, int K, const EpiArgs& E) {
;     ...
;         const bool has_next = S.next(ui + 1, nxt);
;         const char* nA = has_next ? (const char*)A + (size_t)nxt.pm * tstep : cA; const char* nB = has_next ? (const char*)Bt + (size_t)nxt.pn * tstep : cB;
;         for (int t = 0; t < nt; t += 2) {
;             const bool last = (t == nt - 2);
;             const char* a1 = cA + (size_t)(t + 1) * kstep;
;             const char* a2 = last ? nA : cA + (size_t)(t + 2) * kstep; const char* b2 = last ? nB : cB + (size_t)(t + 2) * kstep;
;             const char* a3 = a2 + kstep; const char* b3 = b2 + kstep;
;             PG8_LDB(B0, 0, 0); PG8_LDB(B1, 0, 1); PG8_SCHED; PG8_LDA(At, 0, 0); PG8_STAGEA(PG8_SA(1, 1), a1 + hstep);
;             PG8_WAIT_V(8); PG8_WAIT_L(0); PG8_BAR; PG8_MMA(0, 0, At, B0); PG8_MMA(0, 1, At, B1); PG8_BAR; PG8_SCHED;
;             PG8_LDA(At, 0, 1); PG8_STAGEB(PG8_SB(0, 0), b2); PG8_STAGEB(PG8_SB(0, 1), b2 + hstep); PG8_STAGEA(PG8_SA(0, 0), a2);
;             PG8_WAIT_V(8); PG8_WAIT_L(0); PG8_BAR; PG8_MMA(1, 0, At, B0); PG8_MMA(1, 1, At, B1); PG8_BAR; PG8_SCHED;
.LBB0_198:
	v_add_u32_e32 v150, s54, v152
	ds_read_b128 v[156:159], v150
	ds_read_b128 v[160:163], v150 offset:1024
	ds_read_b128 v[164:167], v150 offset:2048
	ds_read_b128 v[168:171], v150 offset:3072
	v_add_u32_e32 v150, s55, v152
	s_add_u32 s82, s70, s78
	ds_read_b128 v[172:175], v150
	ds_read_b128 v[176:179], v150 offset:1024
	ds_read_b128 v[180:183], v150 offset:2048
	ds_read_b128 v[184:187], v150 offset:3072
	s_addc_u32 s83, s71, s79
	s_add_u32 s82, s82, 0x100
	s_addc_u32 s83, s83, 0
	s_add_u32 s93, s58, s78
	s_addc_u32 s94, s59, s79
	s_cmpk_eq_i32 s78, 0x700
	s_cselect_b32 s85, s75, s83
	s_cselect_b32 s84, s90, s82
	s_cselect_b32 s83, s73, s94
	s_cselect_b32 s82, s91, s93
	v_lshl_add_u64 v[150:151], v[146:147], 0, s[78:79]
	s_add_i32 m0, s67, 0xc000
	ds_read_b128 v[188:191], v155
	ds_read_b128 v[192:195], v155 offset:1024
	ds_read_b128 v[196:199], v155 offset:2048
	ds_read_b128 v[200:203], v155 offset:3072
	ds_read_b128 v[204:207], v155 offset:4096
	ds_read_b128 v[208:211], v155 offset:5120
	ds_read_b128 v[212:215], v155 offset:6144
	ds_read_b128 v[216:219], v155 offset:7168
	global_load_lds_dwordx4 v[150:151], off
	v_lshl_add_u64 v[150:151], v[148:149], 0, s[78:79]
	s_add_i32 m0, s67, 0xe000
	s_nop 0
	global_load_lds_dwordx4 v[150:151], off
	s_waitcnt vmcnt(8)
	s_waitcnt lgkmcnt(0)
	s_barrier
	s_waitcnt lgkmcnt(0)
	v_mfma_f32_16x16x32_bf16 v[110:113], v[156:159], v[188:191], v[110:113]
	v_mfma_f32_16x16x32_bf16 v[106:109], v[164:167], v[188:191], v[106:109]
	v_mfma_f32_16x16x32_bf16 v[102:105], v[156:159], v[196:199], v[102:105]
	v_mfma_f32_16x16x32_bf16 v[98:101], v[164:167], v[196:199], v[98:101]
	v_mfma_f32_16x16x32_bf16 v[94:97], v[156:159], v[204:207], v[94:97]
	v_mfma_f32_16x16x32_bf16 v[90:93], v[164:167], v[204:207], v[90:93]
	v_mfma_f32_16x16x32_bf16 v[86:89], v[156:159], v[212:215], v[86:89]
	v_mfma_f32_16x16x32_bf16 v[82:85], v[164:167], v[212:215], v[82:85]
	v_mfma_f32_16x16x32_bf16 v[110:113], v[160:163], v[192:195], v[110:113]
	v_mfma_f32_16x16x32_bf16 v[106:109], v[168:171], v[192:195], v[106:109]
	v_mfma_f32_16x16x32_bf16 v[102:105], v[160:163], v[200:203], v[102:105]
	v_mfma_f32_16x16x32_bf16 v[98:101], v[168:171], v[200:203], v[98:101]
	v_mfma_f32_16x16x32_bf16 v[94:97], v[160:163], v[208:211], v[94:97]
	v_mfma_f32_16x16x32_bf16 v[90:93], v[168:171], v[208:211], v[90:93]
	v_mfma_f32_16x16x32_bf16 v[86:89], v[160:163], v[216:219], v[86:89]
	v_mfma_f32_16x16x32_bf16 v[82:85], v[168:171], v[216:219], v[82:85]
	v_mfma_f32_16x16x32_bf16 v[78:81], v[172:175], v[188:191], v[78:81]
	v_mfma_f32_16x16x32_bf16 v[74:77], v[180:183], v[188:191], v[74:77]
	v_mfma_f32_16x16x32_bf16 v[70:73], v[172:175], v[196:199], v[70:73]
	v_mfma_f32_16x16x32_bf16 v[66:69], v[180:183], v[196:199], v[66:69]
	v_mfma_f32_16x16x32_bf16 v[62:65], v[172:175], v[204:207], v[62:65]
	v_mfma_f32_16x16x32_bf16 v[58:61], v[180:183], v[204:207], v[58:61]
	v_mfma_f32_16x16x32_bf16 v[54:57], v[172:175], v[212:215], v[54:57]
	v_mfma_f32_16x16x32_bf16 v[50:53], v[180:183], v[212:215], v[50:53]
	v_mfma_f32_16x16x32_bf16 v[78:81], v[176:179], v[192:195], v[78:81]
	v_mfma_f32_16x16x32_bf16 v[74:77], v[184:187], v[192:195], v[74:77]
	v_mfma_f32_16x16x32_bf16 v[70:73], v[176:179], v[200:203], v[70:73]
	v_mfma_f32_16x16x32_bf16 v[66:69], v[184:187], v[200:203], v[66:69]
	v_mfma_f32_16x16x32_bf16 v[62:65], v[176:179], v[208:211], v[62:65]
	v_mfma_f32_16x16x32_bf16 v[58:61], v[184:187], v[208:211], v[58:61]
	v_mfma_f32_16x16x32_bf16 v[54:57], v[176:179], v[216:219], v[54:57]
	v_mfma_f32_16x16x32_bf16 v[50:53], v[184:187], v[216:219], v[50:53]
	s_barrier
	s_add_i32 s93, s54, s87
	v_lshl_add_u64 v[150:151], s[82:83], 0, v[132:133]
	s_mov_b32 m0, s93
	ds_read_b128 v[188:191], v155 offset:16384
	ds_read_b128 v[192:195], v155 offset:17408
	ds_read_b128 v[196:199], v155 offset:18432
	ds_read_b128 v[200:203], v155 offset:19456
	ds_read_b128 v[204:207], v155 offset:20480
	ds_read_b128 v[208:211], v155 offset:21504
	ds_read_b128 v[212:215], v155 offset:22528
	ds_read_b128 v[216:219], v155 offset:23552
	global_load_lds_dwordx4 v[150:151], off
	s_add_i32 m0, s93, 0x2000
	s_add_u32 s94, s82, 0x40000
	v_lshl_add_u64 v[220:221], s[82:83], 0, v[136:137]
	s_addc_u32 s95, s83, 0
	s_add_i32 s93, s55, s87
	global_load_lds_dwordx4 v[220:221], off
	v_lshl_add_u64 v[222:223], s[94:95], 0, v[132:133]
	s_mov_b32 m0, s93
	v_lshl_add_u64 v[224:225], s[84:85], 0, v[134:135]
	global_load_lds_dwordx4 v[222:223], off
	v_lshl_add_u64 v[222:223], s[94:95], 0, v[136:137]
	s_add_i32 m0, s93, 0x2000
	s_nop 0
	global_load_lds_dwordx4 v[222:223], off
	v_lshl_add_u64 v[222:223], s[84:85], 0, v[130:131]
	s_mov_b32 m0, s67
	s_nop 0
	global_load_lds_dwordx4 v[222:223], off
	s_mov_b32 m0, s69
	s_nop 0
	global_load_lds_dwordx4 v[224:225], off
	s_waitcnt vmcnt(8)
	s_waitcnt lgkmcnt(0)
	s_barrier
; #define PG8_STAGEA(bufoff, gbase) PG8_STAGE_(bufoff, gbase, voffA)
; #define PG8_LDA(dst, b, h) do { _Pragma("unroll") for (int m = 0; m < 4; ++m) _Pragma("unroll") for (int k = 0; k < 2; ++k) dst[m][k] = *(const LAS bf16x8*)(lds + PG8_SA(b, h) + aoff + m * 2048 + k * 1024); } while (0)
; #define PG8_LDB(dst, b, h) do { _Pragma("unroll") for (int n = 0; n < 2; ++n) _Pragma("unroll") for (int k = 0; k < 2; ++k) dst[n][k] = *(const LAS bf16x8*)(lds + PG8_SB(b, h) + boff + n * 2048 + k * 1024); } while (0)
; #define PG8_MMA(ai, bj, At, Bt_) do { __builtin_amdgcn_s_setprio(1); _Pragma("unroll") for (int m = 0; m < 4; ++m) _Pragma("unroll") for (int n = 0; n < 2; ++n) _Pragma("unroll") for (int k = 0; k < 2; ++k) \
;         acc[ai][bj][m][n] = __builtin_amdgcn_mfma_f32_16x16x32_bf16(Bt_[n][k], At[m][k], acc[ai][bj][m][n], 0, 0, 0); __builtin_amdgcn_s_setprio(0); } while (0)
; #define PG8_WAIT_V(n) asm volatile("s_waitcnt vmcnt(" #n ")" ::: "memory")
; #define PG8_WAIT_L(n) asm volatile("s_waitcnt lgkmcnt(" #n ")" ::: "memory")
; #define PG8_BAR __builtin_amdgcn_s_barrier()
; #define PG8_SCHED __builtin_amdgcn_sched_barrier(0)
; template <int EK, int SK = -1>
; __device__ __forceinline__ void gemm_phase(LAS unsigned char* lds, const bf16_t* A, const bf16_t* Bt, int nM, int N, int K, const EpiArgs& E) {
;     ...
;             PG8_WAIT_V(8); PG8_WAIT_L(0); PG8_BAR; PG8_MMA(1, 0, At, B0); PG8_MMA(1, 1, At, B1); PG8_BAR; PG8_SCHED;
;             PG8_LDB(B0, 1, 0); PG8_LDB(B1, 1, 1); PG8_SCHED; PG8_LDA(At, 1, 0); PG8_STAGEA(PG8_SA(0, 1), a2 + hstep);
;             PG8_WAIT_V(8); PG8_WAIT_L(0); PG8_BAR; PG8_MMA(0, 0, At, B0); PG8_MMA(0, 1, At, B1); PG8_BAR; PG8_SCHED;
	s_waitcnt lgkmcnt(0)
	v_mfma_f32_16x16x32_bf16 v[46:49], v[156:159], v[188:191], v[46:49]
	v_mfma_f32_16x16x32_bf16 v[42:45], v[164:167], v[188:191], v[42:45]
	v_mfma_f32_16x16x32_bf16 v[38:41], v[156:159], v[196:199], v[38:41]
	v_mfma_f32_16x16x32_bf16 v[34:37], v[164:167], v[196:199], v[34:37]
	v_mfma_f32_16x16x32_bf16 v[30:33], v[156:159], v[204:207], v[30:33]
	v_mfma_f32_16x16x32_bf16 v[26:29], v[164:167], v[204:207], v[26:29]
	v_mfma_f32_16x16x32_bf16 v[22:25], v[156:159], v[212:215], v[22:25]
	v_mfma_f32_16x16x32_bf16 v[18:21], v[164:167], v[212:215], v[18:21]
	v_mfma_f32_16x16x32_bf16 v[46:49], v[160:163], v[192:195], v[46:49]
	v_mfma_f32_16x16x32_bf16 v[42:45], v[168:171], v[192:195], v[42:45]
	v_mfma_f32_16x16x32_bf16 v[38:41], v[160:163], v[200:203], v[38:41]
	v_mfma_f32_16x16x32_bf16 v[34:37], v[168:171], v[200:203], v[34:37]
	v_mfma_f32_16x16x32_bf16 v[30:33], v[160:163], v[208:211], v[30:33]
	v_mfma_f32_16x16x32_bf16 v[26:29], v[168:171], v[208:211], v[26:29]
	v_mfma_f32_16x16x32_bf16 v[22:25], v[160:163], v[216:219], v[22:25]
	v_mfma_f32_16x16x32_bf16 v[18:21], v[168:171], v[216:219], v[18:21]
	v_mfma_f32_16x16x32_bf16 v[14:17], v[172:175], v[188:191], v[14:17]
	v_mfma_f32_16x16x32_bf16 v[10:13], v[180:183], v[188:191], v[10:13]
	v_mfma_f32_16x16x32_bf16 v[6:9], v[172:175], v[196:199], v[6:9]
	v_mfma_f32_16x16x32_bf16 v[2:5], v[180:183], v[196:199], v[2:5]
	v_mfma_f32_16x16x32_bf16 v[114:117], v[172:175], v[204:207], v[114:117]
	v_mfma_f32_16x16x32_bf16 v[118:121], v[180:183], v[204:207], v[118:121]
	v_mfma_f32_16x16x32_bf16 v[122:125], v[172:175], v[212:215], v[122:125]
	v_mfma_f32_16x16x32_bf16 v[126:129], v[180:183], v[212:215], v[126:129]
	v_mfma_f32_16x16x32_bf16 v[14:17], v[176:179], v[192:195], v[14:17]
	v_mfma_f32_16x16x32_bf16 v[10:13], v[184:187], v[192:195], v[10:13]
	v_mfma_f32_16x16x32_bf16 v[6:9], v[176:179], v[200:203], v[6:9]
	v_mfma_f32_16x16x32_bf16 v[2:5], v[184:187], v[200:203], v[2:5]
	v_mfma_f32_16x16x32_bf16 v[114:117], v[176:179], v[208:211], v[114:117]
	v_mfma_f32_16x16x32_bf16 v[118:121], v[184:187], v[208:211], v[118:121]
	v_mfma_f32_16x16x32_bf16 v[122:125], v[176:179], v[216:219], v[122:125]
	v_mfma_f32_16x16x32_bf16 v[126:129], v[184:187], v[216:219], v[126:129]
	s_barrier
	s_add_i32 s93, 0, 0x18000
	s_add_i32 s94, 0, 0x1c000
	v_add_u32_e32 v168, s93, v152
	v_add_u32_e32 v184, s94, v152
	ds_read_b128 v[156:159], v168
	ds_read_b128 v[160:163], v168 offset:1024
	ds_read_b128 v[164:167], v168 offset:2048
	ds_read_b128 v[168:171], v168 offset:3072
	ds_read_b128 v[172:175], v184
	ds_read_b128 v[176:179], v184 offset:1024
	ds_read_b128 v[180:183], v184 offset:2048
	ds_read_b128 v[184:187], v184 offset:3072
	s_add_u32 s84, s84, 0x40000
	s_addc_u32 s85, s85, 0
	s_mov_b32 m0, s88
	v_lshl_add_u64 v[226:227], s[84:85], 0, v[130:131]
	ds_read_b128 v[188:191], v155 offset:32768
	ds_read_b128 v[192:195], v155 offset:33792
	ds_read_b128 v[196:199], v155 offset:34816
	ds_read_b128 v[200:203], v155 offset:35840
	ds_read_b128 v[204:207], v155 offset:36864
	ds_read_b128 v[208:211], v155 offset:37888
	ds_read_b128 v[212:215], v155 offset:38912
	ds_read_b128 v[216:219], v155 offset:39936
	global_load_lds_dwordx4 v[226:227], off
	v_lshl_add_u64 v[226:227], s[84:85], 0, v[134:135]
	s_mov_b32 m0, s89
	s_nop 0
	global_load_lds_dwordx4 v[226:227], off
	s_waitcnt vmcnt(8)
	s_waitcnt lgkmcnt(0)
	s_barrier
	s_waitcnt lgkmcnt(0)
	v_mfma_f32_16x16x32_bf16 v[110:113], v[156:159], v[188:191], v[110:113]
	v_mfma_f32_16x16x32_bf16 v[106:109], v[164:167], v[188:191], v[106:109]
	v_mfma_f32_16x16x32_bf16 v[102:105], v[156:159], v[196:199], v[102:105]
	v_mfma_f32_16x16x32_bf16 v[98:101], v[164:167], v[196:199], v[98:101]
	v_mfma_f32_16x16x32_bf16 v[94:97], v[156:159], v[204:207], v[94:97]
	v_mfma_f32_16x16x32_bf16 v[90:93], v[164:167], v[204:207], v[90:93]
	v_mfma_f32_16x16x32_bf16 v[86:89], v[156:159], v[212:215], v[86:89]
	v_mfma_f32_16x16x32_bf16 v[82:85], v[164:167], v[212:215], v[82:85]
	v_mfma_f32_16x16x32_bf16 v[110:113], v[160:163], v[192:195], v[110:113]
	v_mfma_f32_16x16x32_bf16 v[106:109], v[168:171], v[192:195], v[106:109]
	v_mfma_f32_16x16x32_bf16 v[102:105], v[160:163], v[200:203], v[102:105]
	v_mfma_f32_16x16x32_bf16 v[98:101], v[168:171], v[200:203], v[98:101]
	v_mfma_f32_16x16x32_bf16 v[94:97], v[160:163], v[208:211], v[94:97]
	v_mfma_f32_16x16x32_bf16 v[90:93], v[168:171], v[208:211], v[90:93]
	v_mfma_f32_16x16x32_bf16 v[86:89], v[160:163], v[216:219], v[86:89]
	v_mfma_f32_16x16x32_bf16 v[82:85], v[168:171], v[216:219], v[82:85]
	v_mfma_f32_16x16x32_bf16 v[78:81], v[172:175], v[188:191], v[78:81]
	v_mfma_f32_16x16x32_bf16 v[74:77], v[180:183], v[188:191], v[74:77]
	v_mfma_f32_16x16x32_bf16 v[70:73], v[172:175], v[196:199], v[70:73]
	v_mfma_f32_16x16x32_bf16 v[66:69], v[180:183], v[196:199], v[66:69]
	v_mfma_f32_16x16x32_bf16 v[62:65], v[172:175], v[204:207], v[62:65]
	v_mfma_f32_16x16x32_bf16 v[58:61], v[180:183], v[204:207], v[58:61]
	v_mfma_f32_16x16x32_bf16 v[54:57], v[172:175], v[212:215], v[54:57]
	v_mfma_f32_16x16x32_bf16 v[50:53], v[180:183], v[212:215], v[50:53]
	v_mfma_f32_16x16x32_bf16 v[78:81], v[176:179], v[192:195], v[78:81]
	v_mfma_f32_16x16x32_bf16 v[74:77], v[184:187], v[192:195], v[74:77]
	v_mfma_f32_16x16x32_bf16 v[70:73], v[176:179], v[200:203], v[70:73]
	v_mfma_f32_16x16x32_bf16 v[66:69], v[184:187], v[200:203], v[66:69]
	v_mfma_f32_16x16x32_bf16 v[62:65], v[176:179], v[208:211], v[62:65]
	v_mfma_f32_16x16x32_bf16 v[58:61], v[184:187], v[208:211], v[58:61]
	v_mfma_f32_16x16x32_bf16 v[54:57], v[176:179], v[216:219], v[54:57]
	v_mfma_f32_16x16x32_bf16 v[50:53], v[184:187], v[216:219], v[50:53]
	s_barrier
; #define PG8_STAGEA(bufoff, gbase) PG8_STAGE_(bufoff, gbase, voffA)
; #define PG8_STAGEB(bufoff, gbase) PG8_STAGE_(bufoff, gbase, voffB)
; #define PG8_LDA(dst, b, h) do { _Pragma("unroll") for (int m = 0; m < 4; ++m) _Pragma("unroll") for (int k = 0; k < 2; ++k) dst[m][k] = *(const LAS bf16x8*)(lds + PG8_SA(b, h) + aoff + m * 2048 + k * 1024); } while (0)
; #define PG8_MMA(ai, bj, At, Bt_) do { __builtin_amdgcn_s_setprio(1); _Pragma("unroll") for (int m = 0; m < 4; ++m) _Pragma("unroll") for (int n = 0; n < 2; ++n) _Pragma("unroll") for (int k = 0; k < 2; ++k) \
;         acc[ai][bj][m][n] = __builtin_amdgcn_mfma_f32_16x16x32_bf16(Bt_[n][k], At[m][k], acc[ai][bj][m][n], 0, 0, 0); __builtin_amdgcn_s_setprio(0); } while (0)
; #define PG8_WAIT_V(n) asm volatile("s_waitcnt vmcnt(" #n ")" ::: "memory")
; #define PG8_WAIT_L(n) asm volatile("s_waitcnt lgkmcnt(" #n ")" ::: "memory")
; #define PG8_BAR __builtin_amdgcn_s_barrier()
; #define PG8_SCHED __builtin_amdgcn_sched_barrier(0)
; template <int EK, int SK = -1>
; __device__ __forceinline__ void gemm_phase(LAS unsigned char* lds, const bf16_t* A, const bf16_t* Bt, int nM, int N, int K, const EpiArgs& E) {
;     ...
;             PG8_LDA(At, 1, 1); PG8_STAGEB(PG8_SB(1, 0), b3); PG8_STAGEB(PG8_SB(1, 1), b3 + hstep); PG8_STAGEA(PG8_SA(1, 0), a3);
;             PG8_WAIT_V(8); PG8_WAIT_L(0); PG8_BAR; PG8_MMA(1, 0, At, B0); PG8_MMA(1, 1, At, B1); PG8_BAR; PG8_SCHED;
;         }
	s_add_i32 s84, s93, s87
	v_lshl_add_u64 v[150:151], v[150:151], 0, s[10:11]
	s_mov_b32 m0, s84
	ds_read_b128 v[188:191], v155 offset:49152
	ds_read_b128 v[192:195], v155 offset:50176
	ds_read_b128 v[196:199], v155 offset:51200
	ds_read_b128 v[200:203], v155 offset:52224
	ds_read_b128 v[204:207], v155 offset:53248
	ds_read_b128 v[208:211], v155 offset:54272
	ds_read_b128 v[212:215], v155 offset:55296
	ds_read_b128 v[216:219], v155 offset:56320
	global_load_lds_dwordx4 v[150:151], off
	s_add_i32 m0, s84, 0x2000
	s_add_u32 s82, s82, 0x40080
	v_lshl_add_u64 v[150:151], v[220:221], 0, s[10:11]
	s_addc_u32 s83, s83, 0
	s_add_i32 s84, s94, s87
	global_load_lds_dwordx4 v[150:151], off
	v_lshl_add_u64 v[150:151], s[82:83], 0, v[132:133]
	s_mov_b32 m0, s84
	s_nop 0
	global_load_lds_dwordx4 v[150:151], off
	v_lshl_add_u64 v[150:151], s[82:83], 0, v[136:137]
	s_add_i32 m0, s84, 0x2000
	s_nop 0
	global_load_lds_dwordx4 v[150:151], off
	v_lshl_add_u64 v[150:151], v[222:223], 0, s[10:11]
	s_mov_b32 m0, s52
	s_nop 0
	global_load_lds_dwordx4 v[150:151], off
	v_lshl_add_u64 v[150:151], v[224:225], 0, s[10:11]
	s_mov_b32 m0, s53
	s_nop 0
	global_load_lds_dwordx4 v[150:151], off
	s_waitcnt vmcnt(8)
	s_waitcnt lgkmcnt(0)
	s_barrier
	s_waitcnt lgkmcnt(0)
	v_mfma_f32_16x16x32_bf16 v[46:49], v[156:159], v[188:191], v[46:49]
	v_mfma_f32_16x16x32_bf16 v[42:45], v[164:167], v[188:191], v[42:45]
	v_mfma_f32_16x16x32_bf16 v[38:41], v[156:159], v[196:199], v[38:41]
	v_mfma_f32_16x16x32_bf16 v[34:37], v[164:167], v[196:199], v[34:37]
	v_mfma_f32_16x16x32_bf16 v[30:33], v[156:159], v[204:207], v[30:33]
	v_mfma_f32_16x16x32_bf16 v[26:29], v[164:167], v[204:207], v[26:29]
	v_mfma_f32_16x16x32_bf16 v[22:25], v[156:159], v[212:215], v[22:25]
	v_mfma_f32_16x16x32_bf16 v[18:21], v[164:167], v[212:215], v[18:21]
	v_mfma_f32_16x16x32_bf16 v[46:49], v[160:163], v[192:195], v[46:49]
	v_mfma_f32_16x16x32_bf16 v[42:45], v[168:171], v[192:195], v[42:45]
	v_mfma_f32_16x16x32_bf16 v[38:41], v[160:163], v[200:203], v[38:41]
	v_mfma_f32_16x16x32_bf16 v[34:37], v[168:171], v[200:203], v[34:37]
	v_mfma_f32_16x16x32_bf16 v[30:33], v[160:163], v[208:211], v[30:33]
	v_mfma_f32_16x16x32_bf16 v[26:29], v[168:171], v[208:211], v[26:29]
	v_mfma_f32_16x16x32_bf16 v[22:25], v[160:163], v[216:219], v[22:25]
	v_mfma_f32_16x16x32_bf16 v[18:21], v[168:171], v[216:219], v[18:21]
	v_mfma_f32_16x16x32_bf16 v[14:17], v[172:175], v[188:191], v[14:17]
	v_mfma_f32_16x16x32_bf16 v[10:13], v[180:183], v[188:191], v[10:13]
	v_mfma_f32_16x16x32_bf16 v[6:9], v[172:175], v[196:199], v[6:9]
	v_mfma_f32_16x16x32_bf16 v[2:5], v[180:183], v[196:199], v[2:5]
	v_mfma_f32_16x16x32_bf16 v[114:117], v[172:175], v[204:207], v[114:117]
	v_mfma_f32_16x16x32_bf16 v[118:121], v[180:183], v[204:207], v[118:121]
	v_mfma_f32_16x16x32_bf16 v[122:125], v[172:175], v[212:215], v[122:125]
	v_mfma_f32_16x16x32_bf16 v[126:129], v[180:183], v[212:215], v[126:129]
	v_mfma_f32_16x16x32_bf16 v[14:17], v[176:179], v[192:195], v[14:17]
	v_mfma_f32_16x16x32_bf16 v[10:13], v[184:187], v[192:195], v[10:13]
	v_mfma_f32_16x16x32_bf16 v[6:9], v[176:179], v[200:203], v[6:9]
	v_mfma_f32_16x16x32_bf16 v[2:5], v[184:187], v[200:203], v[2:5]
	v_mfma_f32_16x16x32_bf16 v[114:117], v[176:179], v[208:211], v[114:117]
	v_mfma_f32_16x16x32_bf16 v[118:121], v[184:187], v[208:211], v[118:121]
	v_mfma_f32_16x16x32_bf16 v[122:125], v[176:179], v[216:219], v[122:125]
	v_mfma_f32_16x16x32_bf16 v[126:129], v[184:187], v[216:219], v[126:129]
	s_barrier
	s_add_i32 s92, s92, 2
	s_add_u32 s78, s78, 0x100
	s_addc_u32 s79, s79, 0
	s_cmp_gt_u32 s92, 13
	s_cbranch_scc0 .LBB0_198
	s_and_b64 vcc, exec, s[12:13]
	s_cbranch_vccz .LBB0_201
	s_barrier

; __device__ __forceinline__ unsigned xb_add(unsigned* p, unsigned v) { return __hip_atomic_fetch_add(p, v, __ATOMIC_RELAXED, __HIP_MEMORY_SCOPE_AGENT); }
; __device__ __forceinline__ void xcd_barrier(const XcdBarrier& b) {
;     asm volatile("s_waitcnt vmcnt(0)" ::: "memory");
;     __syncthreads();
;     if (threadIdx.x == 0) {
;         unsigned* bar = b.bar;
;         __builtin_amdgcn_s_waitcnt(0);
;         unsigned nloc = b.st[0], nx = b.st[1];
;         if (nloc == 0u) { xcd_barrier_complete(bar, b.x, nloc, nx); b.st[0] = nloc; b.st[1] = nx; }
;         const unsigned old = xb_add(&bar[XB_XSUB(b.x)], 1u);
;         const unsigned gen = old / nloc;
;         if (old + 1u == (gen + 1u) * nloc) {
.LBB0_206:
	s_cmp_gt_i32 s35, 2
	s_cselect_b64 s[4:5], -1, 0
	s_and_b64 s[6:7], s[14:15], s[4:5]
	s_andn2_b64 vcc, exec, s[6:7]
	s_cbranch_vccnz .LBB0_256
	s_waitcnt vmcnt(0)
	v_cmp_eq_u32_e32 vcc, 0, v0
	s_waitcnt vmcnt(0) lgkmcnt(0)
	s_barrier
	v_readfirstlane_b32 s98, v0
	s_nop 3
	s_lshr_b32 s98, s98, 6
	s_cmp_lg_u32 s98, 1
	s_cbranch_scc1 .Lmy_noinv2
	buffer_inv sc1
	s_waitcnt vmcnt(0)
.Lmy_noinv2:
	s_and_saveexec_b64 s[6:7], vcc
	s_cbranch_execz .LBB0_255
	s_add_i32 s3, 0, 0x20000
	v_mov_b32_e32 v1, s3
	s_waitcnt vmcnt(0) expcnt(0) lgkmcnt(0)
	ds_read_b32 v3, v1
	s_add_i32 s3, 0, 0x20004
	v_mov_b32_e32 v1, s3
	ds_read_b32 v1, v1
	s_waitcnt lgkmcnt(1)
	v_cmp_ne_u32_e32 vcc, 0, v3
	s_cbranch_vccnz .LBB0_223
	s_load_dwordx2 s[12:13], s[0:1], 0xb8
	s_load_dword s3, s[0:1], 0xc0
	s_add_u32 s8, s30, 0xb4b8200
	s_addc_u32 s9, s31, 0
	s_add_u32 s10, s30, 0xb4b8400
	s_waitcnt lgkmcnt(0)
	s_mul_i32 s11, s13, s12
	s_mul_i32 s3, s11, s3
	s_addc_u32 s11, s31, 0
	s_add_u32 s12, s30, 0xb4b8500
	s_addc_u32 s13, s31, 0
	s_add_u32 s14, s30, 0xb4b8600
	s_addc_u32 s15, s31, 0
	s_add_u32 s66, s30, 0xb4b8700
	s_addc_u32 s67, s31, 0
	s_add_u32 s68, s30, 0xb4b8800
	s_addc_u32 s69, s31, 0
	s_add_u32 s70, s30, 0xb4b8900
	s_addc_u32 s71, s31, 0
	s_add_u32 s72, s30, 0xb4b8a00
	s_addc_u32 s73, s31, 0
	s_add_u32 s74, s30, 0xb4b8b00
	s_addc_u32 s75, s31, 0
	s_add_u32 s76, s30, 0xb4b8c00
	s_addc_u32 s77, s31, 0
	s_add_u32 s78, s30, 0xb4b8d00
	s_addc_u32 s79, s31, 0
	s_add_u32 s80, s30, 0xb4b8e00
	s_addc_u32 s81, s31, 0
	s_add_u32 s82, s30, 0xb4b8f00
	s_addc_u32 s83, s31, 0
	s_add_u32 s84, s30, 0xb4b9000
	s_addc_u32 s85, s31, 0
	s_add_u32 s86, s30, 0xb4b9100
	s_mov_b64 s[36:37], s[88:89]
	s_addc_u32 s87, s31, 0
	s_mov_b64 s[38:39], s[90:91]
	s_mov_b64 s[40:41], s[92:93]
	s_mov_b64 s[42:43], s[94:95]
	s_add_u32 s88, s30, 0xb4b9200
	s_addc_u32 s89, s31, 0
	s_add_u32 s90, s30, 0xb4b9300
	s_addc_u32 s91, s31, 0
	s_mov_b32 s52, 1
	v_mov_b32_e32 v17, 0
	s_branch .LBB0_211

; __device__ __forceinline__ unsigned xb_add(unsigned* p, unsigned v) { return __hip_atomic_fetch_add(p, v, __ATOMIC_RELAXED, __HIP_MEMORY_SCOPE_AGENT); }
; __device__ __forceinline__ void xcd_barrier(const XcdBarrier& b) {
;     asm volatile("s_waitcnt vmcnt(0)" ::: "memory");
;     __syncthreads();
;     if (threadIdx.x == 0) {
;         unsigned* bar = b.bar;
;         __builtin_amdgcn_s_waitcnt(0);
;         unsigned nloc = b.st[0], nx = b.st[1];
;         if (nloc == 0u) { xcd_barrier_complete(bar, b.x, nloc, nx); b.st[0] = nloc; b.st[1] = nx; }
;         const unsigned old = xb_add(&bar[XB_XSUB(b.x)], 1u);
;         const unsigned gen = old / nloc;
;         if (old + 1u == (gen + 1u) * nloc) {
.LBB0_333:
	s_cmp_gt_i32 s35, 3
	s_cselect_b64 s[4:5], -1, 0
	s_and_b64 s[6:7], s[14:15], s[4:5]
	s_andn2_b64 vcc, exec, s[6:7]
	s_cbranch_vccnz .LBB0_383
	s_waitcnt vmcnt(0)
	v_cmp_eq_u32_e32 vcc, 0, v0
	s_waitcnt vmcnt(0) lgkmcnt(0)
	s_barrier
	v_readfirstlane_b32 s98, v0
	s_nop 3
	s_lshr_b32 s98, s98, 6
	s_cmp_lg_u32 s98, 1
	s_cbranch_scc1 .Lmy_noinv3
	buffer_inv sc1
	s_waitcnt vmcnt(0)
.Lmy_noinv3:
	s_and_saveexec_b64 s[6:7], vcc
	s_cbranch_execz .LBB0_382
	s_add_i32 s3, 0, 0x20000
	v_mov_b32_e32 v1, s3
	s_waitcnt vmcnt(0) expcnt(0) lgkmcnt(0)
	ds_read_b32 v3, v1
	s_add_i32 s3, 0, 0x20004
	v_mov_b32_e32 v1, s3
	ds_read_b32 v1, v1
	s_waitcnt lgkmcnt(1)
	v_cmp_ne_u32_e32 vcc, 0, v3
	s_cbranch_vccnz .LBB0_350
	s_load_dwordx2 s[12:13], s[0:1], 0xb8
	s_load_dword s3, s[0:1], 0xc0
	s_add_u32 s8, s30, 0xb4b8200
	s_addc_u32 s9, s31, 0
	s_add_u32 s10, s30, 0xb4b8400
	s_waitcnt lgkmcnt(0)
	s_mul_i32 s11, s13, s12
	s_mul_i32 s3, s11, s3
	s_addc_u32 s11, s31, 0
	s_add_u32 s12, s30, 0xb4b8500
	s_addc_u32 s13, s31, 0
	s_add_u32 s14, s30, 0xb4b8600
	s_addc_u32 s15, s31, 0
	s_add_u32 s16, s30, 0xb4b8700
	s_addc_u32 s17, s31, 0
	s_add_u32 s18, s30, 0xb4b8800
	s_addc_u32 s19, s31, 0
	s_add_u32 s38, s30, 0xb4b8900
	s_addc_u32 s39, s31, 0
	s_add_u32 s40, s30, 0xb4b8a00
	s_addc_u32 s41, s31, 0
	s_add_u32 s68, s30, 0xb4b8b00
	s_addc_u32 s69, s31, 0
	s_add_u32 s70, s30, 0xb4b8c00
	s_addc_u32 s71, s31, 0
	s_add_u32 s72, s30, 0xb4b8d00
	s_addc_u32 s73, s31, 0
	s_add_u32 s74, s30, 0xb4b8e00
	s_addc_u32 s75, s31, 0
	s_add_u32 s76, s30, 0xb4b8f00
	s_addc_u32 s77, s31, 0
	s_add_u32 s78, s30, 0xb4b9000
	s_addc_u32 s79, s31, 0
	s_add_u32 s80, s30, 0xb4b9100
	s_addc_u32 s81, s31, 0
	s_add_u32 s82, s30, 0xb4b9200
	s_addc_u32 s83, s31, 0
	s_mov_b64 s[44:45], s[88:89]
	s_add_u32 s84, s30, 0xb4b9300
	s_mov_b64 s[46:47], s[90:91]
	s_mov_b64 s[48:49], s[92:93]
	s_mov_b64 s[50:51], s[94:95]
	s_addc_u32 s85, s31, 0
	s_mov_b32 s52, 1
	v_mov_b32_e32 v17, 0
	s_branch .LBB0_338

; #define PG8_STAGEA(bufoff, gbase) PG8_STAGE_(bufoff, gbase, voffA)
; #define PG8_STAGEB(bufoff, gbase) PG8_STAGE_(bufoff, gbase, voffB)
; #define PG8_LDA(dst, b, h) do { _Pragma("unroll") for (int m = 0; m < 4; ++m) _Pragma("unroll") for (int k = 0; k < 2; ++k) dst[m][k] = *(const LAS bf16x8*)(lds + PG8_SA(b, h) + aoff + m * 2048 + k * 1024); } while (0)
; #define PG8_LDB(dst, b, h) do { _Pragma("unroll") for (int n = 0; n < 2; ++n) _Pragma("unroll") for (int k = 0; k < 2; ++k) dst[n][k] = *(const LAS bf16x8*)(lds + PG8_SB(b, h) + boff + n * 2048 + k * 1024); } while (0)
; #define PG8_MMA(ai, bj, At, Bt_) do { __builtin_amdgcn_s_setprio(1); _Pragma("unroll") for (int m = 0; m < 4; ++m) _Pragma("unroll") for (int n = 0; n < 2; ++n) _Pragma("unroll") for (int k = 0; k < 2; ++k) \
;         acc[ai][bj][m][n] = __builtin_amdgcn_mfma_f32_16x16x32_bf16(Bt_[n][k], At[m][k], acc[ai][bj][m][n], 0, 0, 0); __builtin_amdgcn_s_setprio(0); } while (0)
; #define PG8_WAIT_V(n) asm volatile("s_waitcnt vmcnt(" #n ")" ::: "memory")
; #define PG8_WAIT_L(n) asm volatile("s_waitcnt lgkmcnt(" #n ")" ::: "memory")
; #define PG8_BAR __builtin_amdgcn_s_barrier()
; template <int EK, int SK = -1>
; __device__ __forceinline__ void gemm_phase(LAS unsigned char* lds, const bf16_t* A, const bf16_t* Bt, int nM, int N, int K, const EpiArgs& E) {
;     ...
;         const bool has_next = S.next(ui + 1, nxt);
;         const char* nA = has_next ? (const char*)A + (size_t)nxt.pm * tstep : cA; const char* nB = has_next ? (const char*)Bt + (size_t)nxt.pn * tstep : cB;
;         for (int t = 0; t < nt; t += 2) {
;             const bool last = (t == nt - 2);
;             const char* a1 = cA + (size_t)(t + 1) * kstep;
;             const char* a2 = last ? nA : cA + (size_t)(t + 2) * kstep; const char* b2 = last ? nB : cB + (size_t)(t + 2) * kstep;
;             const char* a3 = a2 + kstep; const char* b3 = b2 + kstep;
;             PG8_LDB(B0, 0, 0); PG8_LDB(B1, 0, 1); PG8_SCHED; PG8_LDA(At, 0, 0); PG8_STAGEA(PG8_SA(1, 1), a1 + hstep);
;             PG8_WAIT_V(8); PG8_WAIT_L(0); PG8_BAR; PG8_MMA(0, 0, At, B0); PG8_MMA(0, 1, At, B1); PG8_BAR; PG8_SCHED;
;             PG8_LDA(At, 0, 1); PG8_STAGEB(PG8_SB(0, 0), b2); PG8_STAGEB(PG8_SB(0, 1), b2 + hstep); PG8_STAGEA(PG8_SA(0, 0), a2);
;             PG8_WAIT_V(8); PG8_WAIT_L(0); PG8_BAR; PG8_MMA(1, 0, At, B0); PG8_MMA(1, 1, At, B1); PG8_BAR; PG8_SCHED;
.LBB0_413:
	v_add_u32_e32 v150, s95, v152
	ds_read_b128 v[156:159], v150
	ds_read_b128 v[160:163], v150 offset:1024
	ds_read_b128 v[164:167], v150 offset:2048
	ds_read_b128 v[168:171], v150 offset:3072
	v_add_u32_e32 v150, s96, v152
	s_add_u32 s59, s18, s80
	ds_read_b128 v[172:175], v150
	ds_read_b128 v[176:179], v150 offset:1024
	ds_read_b128 v[180:183], v150 offset:2048
	ds_read_b128 v[184:187], v150 offset:3072
	s_addc_u32 s73, s19, s81
	s_add_u32 s59, s59, 0x100
	s_addc_u32 s73, s73, 0
	s_add_u32 s75, s53, s80
	s_addc_u32 s82, s54, s81
	s_cmpk_eq_i32 s80, 0x700
	s_cselect_b32 s85, s40, s73
	s_cselect_b32 s84, s55, s59
	s_cselect_b32 s83, s56, s82
	s_cselect_b32 s82, s57, s75
	v_lshl_add_u64 v[150:151], v[146:147], 0, s[80:81]
	s_add_i32 m0, s15, 0xc000
	ds_read_b128 v[188:191], v154
	ds_read_b128 v[192:195], v154 offset:1024
	ds_read_b128 v[196:199], v154 offset:2048
	ds_read_b128 v[200:203], v154 offset:3072
	ds_read_b128 v[204:207], v154 offset:4096
	ds_read_b128 v[208:211], v154 offset:5120
	ds_read_b128 v[212:215], v154 offset:6144
	ds_read_b128 v[216:219], v154 offset:7168
	global_load_lds_dwordx4 v[150:151], off
	v_lshl_add_u64 v[150:151], v[148:149], 0, s[80:81]
	s_add_i32 m0, s15, 0xe000
	s_nop 0
	global_load_lds_dwordx4 v[150:151], off
	s_waitcnt vmcnt(8)
	s_waitcnt lgkmcnt(0)
	s_barrier
	s_waitcnt lgkmcnt(0)
	v_mfma_f32_16x16x32_bf16 v[126:129], v[156:159], v[188:191], v[126:129]
	v_mfma_f32_16x16x32_bf16 v[122:125], v[164:167], v[188:191], v[122:125]
	v_mfma_f32_16x16x32_bf16 v[118:121], v[156:159], v[196:199], v[118:121]
	v_mfma_f32_16x16x32_bf16 v[114:117], v[164:167], v[196:199], v[114:117]
	v_mfma_f32_16x16x32_bf16 v[110:113], v[156:159], v[204:207], v[110:113]
	v_mfma_f32_16x16x32_bf16 v[106:109], v[164:167], v[204:207], v[106:109]
	v_mfma_f32_16x16x32_bf16 v[102:105], v[156:159], v[212:215], v[102:105]
	v_mfma_f32_16x16x32_bf16 v[98:101], v[164:167], v[212:215], v[98:101]
	v_mfma_f32_16x16x32_bf16 v[126:129], v[160:163], v[192:195], v[126:129]
	v_mfma_f32_16x16x32_bf16 v[122:125], v[168:171], v[192:195], v[122:125]
	v_mfma_f32_16x16x32_bf16 v[118:121], v[160:163], v[200:203], v[118:121]
	v_mfma_f32_16x16x32_bf16 v[114:117], v[168:171], v[200:203], v[114:117]
	v_mfma_f32_16x16x32_bf16 v[110:113], v[160:163], v[208:211], v[110:113]
	v_mfma_f32_16x16x32_bf16 v[106:109], v[168:171], v[208:211], v[106:109]
	v_mfma_f32_16x16x32_bf16 v[102:105], v[160:163], v[216:219], v[102:105]
	v_mfma_f32_16x16x32_bf16 v[98:101], v[168:171], v[216:219], v[98:101]
	v_mfma_f32_16x16x32_bf16 v[94:97], v[172:175], v[188:191], v[94:97]
	v_mfma_f32_16x16x32_bf16 v[90:93], v[180:183], v[188:191], v[90:93]
	v_mfma_f32_16x16x32_bf16 v[86:89], v[172:175], v[196:199], v[86:89]
	v_mfma_f32_16x16x32_bf16 v[82:85], v[180:183], v[196:199], v[82:85]
	v_mfma_f32_16x16x32_bf16 v[78:81], v[172:175], v[204:207], v[78:81]
	v_mfma_f32_16x16x32_bf16 v[74:77], v[180:183], v[204:207], v[74:77]
	v_mfma_f32_16x16x32_bf16 v[70:73], v[172:175], v[212:215], v[70:73]
	v_mfma_f32_16x16x32_bf16 v[66:69], v[180:183], v[212:215], v[66:69]
	v_mfma_f32_16x16x32_bf16 v[94:97], v[176:179], v[192:195], v[94:97]
	v_mfma_f32_16x16x32_bf16 v[90:93], v[184:187], v[192:195], v[90:93]
	v_mfma_f32_16x16x32_bf16 v[86:89], v[176:179], v[200:203], v[86:89]
	v_mfma_f32_16x16x32_bf16 v[82:85], v[184:187], v[200:203], v[82:85]
	v_mfma_f32_16x16x32_bf16 v[78:81], v[176:179], v[208:211], v[78:81]
	v_mfma_f32_16x16x32_bf16 v[74:77], v[184:187], v[208:211], v[74:77]
	v_mfma_f32_16x16x32_bf16 v[70:73], v[176:179], v[216:219], v[70:73]
	v_mfma_f32_16x16x32_bf16 v[66:69], v[184:187], v[216:219], v[66:69]
	s_barrier
	s_add_i32 s59, s95, s88
	v_lshl_add_u64 v[150:151], s[82:83], 0, v[132:133]
	s_mov_b32 m0, s59
	ds_read_b128 v[188:191], v154 offset:16384
	ds_read_b128 v[192:195], v154 offset:17408
	ds_read_b128 v[196:199], v154 offset:18432
	ds_read_b128 v[200:203], v154 offset:19456
	ds_read_b128 v[204:207], v154 offset:20480
	ds_read_b128 v[208:211], v154 offset:21504
	ds_read_b128 v[212:215], v154 offset:22528
	ds_read_b128 v[216:219], v154 offset:23552
	global_load_lds_dwordx4 v[150:151], off
	s_add_i32 m0, s59, 0x2000
	s_add_u32 vcc_lo, s82, 0x40000
	v_lshl_add_u64 v[220:221], s[82:83], 0, v[136:137]
	s_addc_u32 vcc_hi, s83, 0
	s_add_i32 s59, s96, s88
	global_load_lds_dwordx4 v[220:221], off
	v_lshl_add_u64 v[222:223], vcc, 0, v[132:133]
	s_mov_b32 m0, s59
	v_lshl_add_u64 v[224:225], s[84:85], 0, v[134:135]
	global_load_lds_dwordx4 v[222:223], off
	v_lshl_add_u64 v[222:223], vcc, 0, v[136:137]
	s_add_i32 m0, s59, 0x2000
	s_nop 0
	global_load_lds_dwordx4 v[222:223], off
	v_lshl_add_u64 v[222:223], s[84:85], 0, v[130:131]
	s_mov_b32 m0, s15
	s_nop 0
	global_load_lds_dwordx4 v[222:223], off
	s_mov_b32 m0, s17
	s_nop 0
	global_load_lds_dwordx4 v[224:225], off
	s_waitcnt vmcnt(8)
	s_waitcnt lgkmcnt(0)
	s_barrier
; #define PG8_STAGEA(bufoff, gbase) PG8_STAGE_(bufoff, gbase, voffA)
; #define PG8_LDA(dst, b, h) do { _Pragma("unroll") for (int m = 0; m < 4; ++m) _Pragma("unroll") for (int k = 0; k < 2; ++k) dst[m][k] = *(const LAS bf16x8*)(lds + PG8_SA(b, h) + aoff + m * 2048 + k * 1024); } while (0)
; #define PG8_LDB(dst, b, h) do { _Pragma("unroll") for (int n = 0; n < 2; ++n) _Pragma("unroll") for (int k = 0; k < 2; ++k) dst[n][k] = *(const LAS bf16x8*)(lds + PG8_SB(b, h) + boff + n * 2048 + k * 1024); } while (0)
; #define PG8_MMA(ai, bj, At, Bt_) do { __builtin_amdgcn_s_setprio(1); _Pragma("unroll") for (int m = 0; m < 4; ++m) _Pragma("unroll") for (int n = 0; n < 2; ++n) _Pragma("unroll") for (int k = 0; k < 2; ++k) \
;         acc[ai][bj][m][n] = __builtin_amdgcn_mfma_f32_16x16x32_bf16(Bt_[n][k], At[m][k], acc[ai][bj][m][n], 0, 0, 0); __builtin_amdgcn_s_setprio(0); } while (0)
; #define PG8_WAIT_V(n) asm volatile("s_waitcnt vmcnt(" #n ")" ::: "memory")
; #define PG8_WAIT_L(n) asm volatile("s_waitcnt lgkmcnt(" #n ")" ::: "memory")
; #define PG8_BAR __builtin_amdgcn_s_barrier()
; #define PG8_SCHED __builtin_amdgcn_sched_barrier(0)
; template <int EK, int SK = -1>
; __device__ __forceinline__ void gemm_phase(LAS unsigned char* lds, const bf16_t* A, const bf16_t* Bt, int nM, int N, int K, const EpiArgs& E) {
;     ...
;             PG8_WAIT_V(8); PG8_WAIT_L(0); PG8_BAR; PG8_MMA(1, 0, At, B0); PG8_MMA(1, 1, At, B1); PG8_BAR; PG8_SCHED;
;             PG8_LDB(B0, 1, 0); PG8_LDB(B1, 1, 1); PG8_SCHED; PG8_LDA(At, 1, 0); PG8_STAGEA(PG8_SA(0, 1), a2 + hstep);
;             PG8_WAIT_V(8); PG8_WAIT_L(0); PG8_BAR; PG8_MMA(0, 0, At, B0); PG8_MMA(0, 1, At, B1); PG8_BAR; PG8_SCHED;
	s_waitcnt lgkmcnt(0)
	v_mfma_f32_16x16x32_bf16 v[62:65], v[156:159], v[188:191], v[62:65]
	v_mfma_f32_16x16x32_bf16 v[58:61], v[164:167], v[188:191], v[58:61]
	v_mfma_f32_16x16x32_bf16 v[54:57], v[156:159], v[196:199], v[54:57]
	v_mfma_f32_16x16x32_bf16 v[50:53], v[164:167], v[196:199], v[50:53]
	v_mfma_f32_16x16x32_bf16 v[46:49], v[156:159], v[204:207], v[46:49]
	v_mfma_f32_16x16x32_bf16 v[42:45], v[164:167], v[204:207], v[42:45]
	v_mfma_f32_16x16x32_bf16 v[38:41], v[156:159], v[212:215], v[38:41]
	v_mfma_f32_16x16x32_bf16 v[34:37], v[164:167], v[212:215], v[34:37]
	v_mfma_f32_16x16x32_bf16 v[62:65], v[160:163], v[192:195], v[62:65]
	v_mfma_f32_16x16x32_bf16 v[58:61], v[168:171], v[192:195], v[58:61]
	v_mfma_f32_16x16x32_bf16 v[54:57], v[160:163], v[200:203], v[54:57]
	v_mfma_f32_16x16x32_bf16 v[50:53], v[168:171], v[200:203], v[50:53]
	v_mfma_f32_16x16x32_bf16 v[46:49], v[160:163], v[208:211], v[46:49]
	v_mfma_f32_16x16x32_bf16 v[42:45], v[168:171], v[208:211], v[42:45]
	v_mfma_f32_16x16x32_bf16 v[38:41], v[160:163], v[216:219], v[38:41]
	v_mfma_f32_16x16x32_bf16 v[34:37], v[168:171], v[216:219], v[34:37]
	v_mfma_f32_16x16x32_bf16 v[30:33], v[172:175], v[188:191], v[30:33]
	v_mfma_f32_16x16x32_bf16 v[26:29], v[180:183], v[188:191], v[26:29]
	v_mfma_f32_16x16x32_bf16 v[22:25], v[172:175], v[196:199], v[22:25]
	v_mfma_f32_16x16x32_bf16 v[18:21], v[180:183], v[196:199], v[18:21]
	v_mfma_f32_16x16x32_bf16 v[14:17], v[172:175], v[204:207], v[14:17]
	v_mfma_f32_16x16x32_bf16 v[10:13], v[180:183], v[204:207], v[10:13]
	v_mfma_f32_16x16x32_bf16 v[6:9], v[172:175], v[212:215], v[6:9]
	v_mfma_f32_16x16x32_bf16 v[2:5], v[180:183], v[212:215], v[2:5]
	v_mfma_f32_16x16x32_bf16 v[30:33], v[176:179], v[192:195], v[30:33]
	v_mfma_f32_16x16x32_bf16 v[26:29], v[184:187], v[192:195], v[26:29]
	v_mfma_f32_16x16x32_bf16 v[22:25], v[176:179], v[200:203], v[22:25]
	v_mfma_f32_16x16x32_bf16 v[18:21], v[184:187], v[200:203], v[18:21]
	v_mfma_f32_16x16x32_bf16 v[14:17], v[176:179], v[208:211], v[14:17]
	v_mfma_f32_16x16x32_bf16 v[10:13], v[184:187], v[208:211], v[10:13]
	v_mfma_f32_16x16x32_bf16 v[6:9], v[176:179], v[216:219], v[6:9]
	v_mfma_f32_16x16x32_bf16 v[2:5], v[184:187], v[216:219], v[2:5]
	s_barrier
	s_add_i32 s59, 0, 0x18000
	s_add_i32 s73, 0, 0x1c000
	v_add_u32_e32 v168, s59, v152
	v_add_u32_e32 v184, s73, v152
	ds_read_b128 v[156:159], v168
	ds_read_b128 v[160:163], v168 offset:1024
	ds_read_b128 v[164:167], v168 offset:2048
	ds_read_b128 v[168:171], v168 offset:3072
	ds_read_b128 v[172:175], v184
	ds_read_b128 v[176:179], v184 offset:1024
	ds_read_b128 v[180:183], v184 offset:2048
	ds_read_b128 v[184:187], v184 offset:3072
	s_add_u32 s84, s84, 0x40000
	s_addc_u32 s85, s85, 0
	s_mov_b32 m0, s89
	v_lshl_add_u64 v[226:227], s[84:85], 0, v[130:131]
	ds_read_b128 v[188:191], v154 offset:32768
	ds_read_b128 v[192:195], v154 offset:33792
	ds_read_b128 v[196:199], v154 offset:34816
	ds_read_b128 v[200:203], v154 offset:35840
	ds_read_b128 v[204:207], v154 offset:36864
	ds_read_b128 v[208:211], v154 offset:37888
	ds_read_b128 v[212:215], v154 offset:38912
	ds_read_b128 v[216:219], v154 offset:39936
	global_load_lds_dwordx4 v[226:227], off
	v_lshl_add_u64 v[226:227], s[84:85], 0, v[134:135]
	s_mov_b32 m0, s90
	s_nop 0
	global_load_lds_dwordx4 v[226:227], off
	s_waitcnt vmcnt(8)
	s_waitcnt lgkmcnt(0)
	s_barrier
	s_waitcnt lgkmcnt(0)
	v_mfma_f32_16x16x32_bf16 v[126:129], v[156:159], v[188:191], v[126:129]
	v_mfma_f32_16x16x32_bf16 v[122:125], v[164:167], v[188:191], v[122:125]
	v_mfma_f32_16x16x32_bf16 v[118:121], v[156:159], v[196:199], v[118:121]
	v_mfma_f32_16x16x32_bf16 v[114:117], v[164:167], v[196:199], v[114:117]
	v_mfma_f32_16x16x32_bf16 v[110:113], v[156:159], v[204:207], v[110:113]
	v_mfma_f32_16x16x32_bf16 v[106:109], v[164:167], v[204:207], v[106:109]
	v_mfma_f32_16x16x32_bf16 v[102:105], v[156:159], v[212:215], v[102:105]
	v_mfma_f32_16x16x32_bf16 v[98:101], v[164:167], v[212:215], v[98:101]
	v_mfma_f32_16x16x32_bf16 v[126:129], v[160:163], v[192:195], v[126:129]
	v_mfma_f32_16x16x32_bf16 v[122:125], v[168:171], v[192:195], v[122:125]
	v_mfma_f32_16x16x32_bf16 v[118:121], v[160:163], v[200:203], v[118:121]
	v_mfma_f32_16x16x32_bf16 v[114:117], v[168:171], v[200:203], v[114:117]
	v_mfma_f32_16x16x32_bf16 v[110:113], v[160:163], v[208:211], v[110:113]
	v_mfma_f32_16x16x32_bf16 v[106:109], v[168:171], v[208:211], v[106:109]
	v_mfma_f32_16x16x32_bf16 v[102:105], v[160:163], v[216:219], v[102:105]
	v_mfma_f32_16x16x32_bf16 v[98:101], v[168:171], v[216:219], v[98:101]
	v_mfma_f32_16x16x32_bf16 v[94:97], v[172:175], v[188:191], v[94:97]
	v_mfma_f32_16x16x32_bf16 v[90:93], v[180:183], v[188:191], v[90:93]
	v_mfma_f32_16x16x32_bf16 v[86:89], v[172:175], v[196:199], v[86:89]
	v_mfma_f32_16x16x32_bf16 v[82:85], v[180:183], v[196:199], v[82:85]
	v_mfma_f32_16x16x32_bf16 v[78:81], v[172:175], v[204:207], v[78:81]
	v_mfma_f32_16x16x32_bf16 v[74:77], v[180:183], v[204:207], v[74:77]
	v_mfma_f32_16x16x32_bf16 v[70:73], v[172:175], v[212:215], v[70:73]
	v_mfma_f32_16x16x32_bf16 v[66:69], v[180:183], v[212:215], v[66:69]
	v_mfma_f32_16x16x32_bf16 v[94:97], v[176:179], v[192:195], v[94:97]
	v_mfma_f32_16x16x32_bf16 v[90:93], v[184:187], v[192:195], v[90:93]
	v_mfma_f32_16x16x32_bf16 v[86:89], v[176:179], v[200:203], v[86:89]
	v_mfma_f32_16x16x32_bf16 v[82:85], v[184:187], v[200:203], v[82:85]
	v_mfma_f32_16x16x32_bf16 v[78:81], v[176:179], v[208:211], v[78:81]
	v_mfma_f32_16x16x32_bf16 v[74:77], v[184:187], v[208:211], v[74:77]
	v_mfma_f32_16x16x32_bf16 v[70:73], v[176:179], v[216:219], v[70:73]
	v_mfma_f32_16x16x32_bf16 v[66:69], v[184:187], v[216:219], v[66:69]
	s_barrier
; #define PG8_STAGEA(bufoff, gbase) PG8_STAGE_(bufoff, gbase, voffA)
; #define PG8_STAGEB(bufoff, gbase) PG8_STAGE_(bufoff, gbase, voffB)
; #define PG8_LDA(dst, b, h) do { _Pragma("unroll") for (int m = 0; m < 4; ++m) _Pragma("unroll") for (int k = 0; k < 2; ++k) dst[m][k] = *(const LAS bf16x8*)(lds + PG8_SA(b, h) + aoff + m * 2048 + k * 1024); } while (0)
; #define PG8_MMA(ai, bj, At, Bt_) do { __builtin_amdgcn_s_setprio(1); _Pragma("unroll") for (int m = 0; m < 4; ++m) _Pragma("unroll") for (int n = 0; n < 2; ++n) _Pragma("unroll") for (int k = 0; k < 2; ++k) \
;         acc[ai][bj][m][n] = __builtin_amdgcn_mfma_f32_16x16x32_bf16(Bt_[n][k], At[m][k], acc[ai][bj][m][n], 0, 0, 0); __builtin_amdgcn_s_setprio(0); } while (0)
; #define PG8_WAIT_V(n) asm volatile("s_waitcnt vmcnt(" #n ")" ::: "memory")
; #define PG8_WAIT_L(n) asm volatile("s_waitcnt lgkmcnt(" #n ")" ::: "memory")
; #define PG8_BAR __builtin_amdgcn_s_barrier()
; #define PG8_SCHED __builtin_amdgcn_sched_barrier(0)
; template <int EK, int SK = -1>
; __device__ __forceinline__ void gemm_phase(LAS unsigned char* lds, const bf16_t* A, const bf16_t* Bt, int nM, int N, int K, const EpiArgs& E) {
;     ...
;             PG8_LDA(At, 1, 1); PG8_STAGEB(PG8_SB(1, 0), b3); PG8_STAGEB(PG8_SB(1, 1), b3 + hstep); PG8_STAGEA(PG8_SA(1, 0), a3);
;             PG8_WAIT_V(8); PG8_WAIT_L(0); PG8_BAR; PG8_MMA(1, 0, At, B0); PG8_MMA(1, 1, At, B1); PG8_BAR; PG8_SCHED;
;         }
	s_add_i32 s59, s59, s88
	v_lshl_add_u64 v[150:151], v[150:151], 0, s[68:69]
	s_mov_b32 m0, s59
	ds_read_b128 v[188:191], v154 offset:49152
	ds_read_b128 v[192:195], v154 offset:50176
	ds_read_b128 v[196:199], v154 offset:51200
	ds_read_b128 v[200:203], v154 offset:52224
	ds_read_b128 v[204:207], v154 offset:53248
	ds_read_b128 v[208:211], v154 offset:54272
	ds_read_b128 v[212:215], v154 offset:55296
	ds_read_b128 v[216:219], v154 offset:56320
	global_load_lds_dwordx4 v[150:151], off
	s_add_i32 m0, s59, 0x2000
	s_add_u32 s82, s82, 0x40080
	v_lshl_add_u64 v[150:151], v[220:221], 0, s[68:69]
	s_addc_u32 s83, s83, 0
	s_add_i32 s59, s73, s88
	global_load_lds_dwordx4 v[150:151], off
	v_lshl_add_u64 v[150:151], s[82:83], 0, v[132:133]
	s_mov_b32 m0, s59
	s_nop 0
	global_load_lds_dwordx4 v[150:151], off
	v_lshl_add_u64 v[150:151], s[82:83], 0, v[136:137]
	s_add_i32 m0, s59, 0x2000
	s_nop 0
	global_load_lds_dwordx4 v[150:151], off
	v_lshl_add_u64 v[150:151], v[222:223], 0, s[68:69]
	s_mov_b32 m0, s93
	s_nop 0
	global_load_lds_dwordx4 v[150:151], off
	v_lshl_add_u64 v[150:151], v[224:225], 0, s[68:69]
	s_mov_b32 m0, s94
	s_nop 0
	global_load_lds_dwordx4 v[150:151], off
	s_waitcnt vmcnt(8)
	s_waitcnt lgkmcnt(0)
	s_barrier
	s_waitcnt lgkmcnt(0)
	v_mfma_f32_16x16x32_bf16 v[62:65], v[156:159], v[188:191], v[62:65]
	v_mfma_f32_16x16x32_bf16 v[58:61], v[164:167], v[188:191], v[58:61]
	v_mfma_f32_16x16x32_bf16 v[54:57], v[156:159], v[196:199], v[54:57]
	v_mfma_f32_16x16x32_bf16 v[50:53], v[164:167], v[196:199], v[50:53]
	v_mfma_f32_16x16x32_bf16 v[46:49], v[156:159], v[204:207], v[46:49]
	v_mfma_f32_16x16x32_bf16 v[42:45], v[164:167], v[204:207], v[42:45]
	v_mfma_f32_16x16x32_bf16 v[38:41], v[156:159], v[212:215], v[38:41]
	v_mfma_f32_16x16x32_bf16 v[34:37], v[164:167], v[212:215], v[34:37]
	v_mfma_f32_16x16x32_bf16 v[62:65], v[160:163], v[192:195], v[62:65]
	v_mfma_f32_16x16x32_bf16 v[58:61], v[168:171], v[192:195], v[58:61]
	v_mfma_f32_16x16x32_bf16 v[54:57], v[160:163], v[200:203], v[54:57]
	v_mfma_f32_16x16x32_bf16 v[50:53], v[168:171], v[200:203], v[50:53]
	v_mfma_f32_16x16x32_bf16 v[46:49], v[160:163], v[208:211], v[46:49]
	v_mfma_f32_16x16x32_bf16 v[42:45], v[168:171], v[208:211], v[42:45]
	v_mfma_f32_16x16x32_bf16 v[38:41], v[160:163], v[216:219], v[38:41]
	v_mfma_f32_16x16x32_bf16 v[34:37], v[168:171], v[216:219], v[34:37]
	v_mfma_f32_16x16x32_bf16 v[30:33], v[172:175], v[188:191], v[30:33]
	v_mfma_f32_16x16x32_bf16 v[26:29], v[180:183], v[188:191], v[26:29]
	v_mfma_f32_16x16x32_bf16 v[22:25], v[172:175], v[196:199], v[22:25]
	v_mfma_f32_16x16x32_bf16 v[18:21], v[180:183], v[196:199], v[18:21]
	v_mfma_f32_16x16x32_bf16 v[14:17], v[172:175], v[204:207], v[14:17]
	v_mfma_f32_16x16x32_bf16 v[10:13], v[180:183], v[204:207], v[10:13]
	v_mfma_f32_16x16x32_bf16 v[6:9], v[172:175], v[212:215], v[6:9]
	v_mfma_f32_16x16x32_bf16 v[2:5], v[180:183], v[212:215], v[2:5]
	v_mfma_f32_16x16x32_bf16 v[30:33], v[176:179], v[192:195], v[30:33]
	v_mfma_f32_16x16x32_bf16 v[26:29], v[184:187], v[192:195], v[26:29]
	v_mfma_f32_16x16x32_bf16 v[22:25], v[176:179], v[200:203], v[22:25]
	v_mfma_f32_16x16x32_bf16 v[18:21], v[184:187], v[200:203], v[18:21]
	v_mfma_f32_16x16x32_bf16 v[14:17], v[176:179], v[208:211], v[14:17]
	v_mfma_f32_16x16x32_bf16 v[10:13], v[184:187], v[208:211], v[10:13]
	v_mfma_f32_16x16x32_bf16 v[6:9], v[176:179], v[216:219], v[6:9]
	v_mfma_f32_16x16x32_bf16 v[2:5], v[184:187], v[216:219], v[2:5]
	s_barrier
	s_add_i32 s58, s58, 2
	s_add_u32 s80, s80, 0x100
	s_addc_u32 s81, s81, 0
	s_cmp_gt_u32 s58, 13
	s_cbranch_scc0 .LBB0_413
	s_and_b64 vcc, exec, s[70:71]
	s_cbranch_vccz .LBB0_416
	s_barrier

; __device__ __forceinline__ unsigned xb_add(unsigned* p, unsigned v) { return __hip_atomic_fetch_add(p, v, __ATOMIC_RELAXED, __HIP_MEMORY_SCOPE_AGENT); }
; __device__ __forceinline__ void xcd_barrier(const XcdBarrier& b) {
;     asm volatile("s_waitcnt vmcnt(0)" ::: "memory");
;     __syncthreads();
;     if (threadIdx.x == 0) {
;         unsigned* bar = b.bar;
;         __builtin_amdgcn_s_waitcnt(0);
;         unsigned nloc = b.st[0], nx = b.st[1];
;         if (nloc == 0u) { xcd_barrier_complete(bar, b.x, nloc, nx); b.st[0] = nloc; b.st[1] = nx; }
;         const unsigned old = xb_add(&bar[XB_XSUB(b.x)], 1u);
;         const unsigned gen = old / nloc;
;         if (old + 1u == (gen + 1u) * nloc) {
.LBB0_437:
	s_cmp_gt_i32 s35, 4
	s_cselect_b64 s[4:5], -1, 0
	s_and_b64 s[6:7], s[10:11], s[4:5]
	s_andn2_b64 vcc, exec, s[6:7]
	s_cbranch_vccnz .LBB0_487
	s_waitcnt vmcnt(0)
	v_cmp_eq_u32_e32 vcc, 0, v0
	s_waitcnt vmcnt(0) lgkmcnt(0)
	s_barrier
	v_readfirstlane_b32 s98, v0
	s_nop 3
	s_lshr_b32 s98, s98, 6
	s_cmp_lg_u32 s98, 1
	s_cbranch_scc1 .Lmy_noinv4
	buffer_inv sc1
	s_waitcnt vmcnt(0)
.Lmy_noinv4:
	s_and_saveexec_b64 s[6:7], vcc
	s_cbranch_execz .LBB0_486
	s_add_i32 s3, 0, 0x20000
	v_mov_b32_e32 v1, s3
	s_waitcnt vmcnt(0) expcnt(0) lgkmcnt(0)
	ds_read_b32 v3, v1
	s_add_i32 s3, 0, 0x20004
	v_mov_b32_e32 v1, s3
	ds_read_b32 v1, v1
	s_waitcnt lgkmcnt(1)
	v_cmp_ne_u32_e32 vcc, 0, v3
	s_cbranch_vccnz .LBB0_454
	s_load_dwordx2 s[14:15], s[0:1], 0xb8
	s_load_dword s3, s[0:1], 0xc0
	s_add_u32 s8, s30, 0xb4b8200
	s_addc_u32 s9, s31, 0
	s_add_u32 s10, s30, 0xb4b8400
	s_waitcnt lgkmcnt(0)
	s_mul_i32 s11, s15, s14
	s_mul_i32 s3, s11, s3
	s_addc_u32 s11, s31, 0
	s_add_u32 s14, s30, 0xb4b8500
	s_addc_u32 s15, s31, 0
	s_add_u32 s16, s30, 0xb4b8600
	s_addc_u32 s17, s31, 0
	s_add_u32 s18, s30, 0xb4b8700
	s_addc_u32 s19, s31, 0
	s_add_u32 s38, s30, 0xb4b8800
	s_addc_u32 s39, s31, 0
	s_add_u32 s40, s30, 0xb4b8900
	s_addc_u32 s41, s31, 0
	s_add_u32 s68, s30, 0xb4b8a00
	s_addc_u32 s69, s31, 0
	s_add_u32 s70, s30, 0xb4b8b00
	s_addc_u32 s71, s31, 0
	s_add_u32 s72, s30, 0xb4b8c00
	s_addc_u32 s73, s31, 0
	s_add_u32 s74, s30, 0xb4b8d00
	s_addc_u32 s75, s31, 0
	s_add_u32 s76, s30, 0xb4b8e00
	s_addc_u32 s77, s31, 0
	s_add_u32 s78, s30, 0xb4b8f00
	s_addc_u32 s79, s31, 0
	s_add_u32 s80, s30, 0xb4b9000
	s_addc_u32 s81, s31, 0
	s_add_u32 s82, s30, 0xb4b9100
	s_addc_u32 s83, s31, 0
	s_add_u32 s84, s30, 0xb4b9200
	s_addc_u32 s85, s31, 0
	s_mov_b64 s[44:45], s[88:89]
	s_add_u32 s86, s30, 0xb4b9300
	s_mov_b64 s[46:47], s[90:91]
	s_mov_b64 s[48:49], s[92:93]
	s_mov_b64 s[50:51], s[94:95]
	s_addc_u32 s87, s31, 0
	s_mov_b32 s52, 1
	v_mov_b32_e32 v17, 0
	s_branch .LBB0_442

; #define PG8_STAGEA(bufoff, gbase) PG8_STAGE_(bufoff, gbase, voffA)
; #define PG8_STAGEB(bufoff, gbase) PG8_STAGE_(bufoff, gbase, voffB)
; #define PG8_LDA(dst, b, h) do { _Pragma("unroll") for (int m = 0; m < 4; ++m) _Pragma("unroll") for (int k = 0; k < 2; ++k) dst[m][k] = *(const LAS bf16x8*)(lds + PG8_SA(b, h) + aoff + m * 2048 + k * 1024); } while (0)
; #define PG8_LDB(dst, b, h) do { _Pragma("unroll") for (int n = 0; n < 2; ++n) _Pragma("unroll") for (int k = 0; k < 2; ++k) dst[n][k] = *(const LAS bf16x8*)(lds + PG8_SB(b, h) + boff + n * 2048 + k * 1024); } while (0)
; #define PG8_MMA(ai, bj, At, Bt_) do { __builtin_amdgcn_s_setprio(1); _Pragma("unroll") for (int m = 0; m < 4; ++m) _Pragma("unroll") for (int n = 0; n < 2; ++n) _Pragma("unroll") for (int k = 0; k < 2; ++k) \
;         acc[ai][bj][m][n] = __builtin_amdgcn_mfma_f32_16x16x32_bf16(Bt_[n][k], At[m][k], acc[ai][bj][m][n], 0, 0, 0); __builtin_amdgcn_s_setprio(0); } while (0)
; #define PG8_WAIT_V(n) asm volatile("s_waitcnt vmcnt(" #n ")" ::: "memory")
; #define PG8_WAIT_L(n) asm volatile("s_waitcnt lgkmcnt(" #n ")" ::: "memory")
; #define PG8_BAR __builtin_amdgcn_s_barrier()
; template <int EK, int SK = -1>
; __device__ __forceinline__ void gemm_phase(LAS unsigned char* lds, const bf16_t* A, const bf16_t* Bt, int nM, int N, int K, const EpiArgs& E) {
;     ...
;         const bool has_next = S.next(ui + 1, nxt);
;         const char* nA = has_next ? (const char*)A + (size_t)nxt.pm * tstep : cA; const char* nB = has_next ? (const char*)Bt + (size_t)nxt.pn * tstep : cB;
;         for (int t = 0; t < nt; t += 2) {
;             const bool last = (t == nt - 2);
;             const char* a1 = cA + (size_t)(t + 1) * kstep;
;             const char* a2 = last ? nA : cA + (size_t)(t + 2) * kstep; const char* b2 = last ? nB : cB + (size_t)(t + 2) * kstep;
;             const char* a3 = a2 + kstep; const char* b3 = b2 + kstep;
;             PG8_LDB(B0, 0, 0); PG8_LDB(B1, 0, 1); PG8_SCHED; PG8_LDA(At, 0, 0); PG8_STAGEA(PG8_SA(1, 1), a1 + hstep);
;             PG8_WAIT_V(8); PG8_WAIT_L(0); PG8_BAR; PG8_MMA(0, 0, At, B0); PG8_MMA(0, 1, At, B1); PG8_BAR; PG8_SCHED;
;             PG8_LDA(At, 0, 1); PG8_STAGEB(PG8_SB(0, 0), b2); PG8_STAGEB(PG8_SB(0, 1), b2 + hstep); PG8_STAGEA(PG8_SA(0, 0), a2);
;             PG8_WAIT_V(8); PG8_WAIT_L(0); PG8_BAR; PG8_MMA(1, 0, At, B0); PG8_MMA(1, 1, At, B1); PG8_BAR; PG8_SCHED;
.LBB0_538:
	v_add_u32_e32 v154, s88, v159
	ds_read_b128 v[150:153], v154
	ds_read_b128 v[164:167], v154 offset:1024
	ds_read_b128 v[168:171], v154 offset:2048
	ds_read_b128 v[172:175], v154 offset:3072
	v_add_u32_e32 v154, s89, v159
	s_add_u32 s69, s38, s74
	ds_read_b128 v[176:179], v154
	ds_read_b128 v[180:183], v154 offset:1024
	ds_read_b128 v[184:187], v154 offset:2048
	ds_read_b128 v[188:191], v154 offset:3072
	s_addc_u32 s76, s39, s75
	s_add_u32 s69, s69, 0x100
	s_addc_u32 s76, s76, 0
	s_add_u32 s91, s54, s74
	s_addc_u32 s77, s55, s75
	s_cmpk_eq_i32 s74, 0x700
	s_cselect_b32 s79, s56, s76
	s_cselect_b32 s78, s57, s69
	s_cselect_b32 s77, s41, s77
	s_cselect_b32 s76, s58, s91
	v_lshl_add_u64 v[154:155], v[146:147], 0, s[74:75]
	s_add_i32 m0, s15, 0xc000
	ds_read_b128 v[192:195], v162
	ds_read_b128 v[196:199], v162 offset:1024
	ds_read_b128 v[200:203], v162 offset:2048
	ds_read_b128 v[204:207], v162 offset:3072
	ds_read_b128 v[208:211], v162 offset:4096
	ds_read_b128 v[212:215], v162 offset:5120
	ds_read_b128 v[216:219], v162 offset:6144
	ds_read_b128 v[220:223], v162 offset:7168
	global_load_lds_dwordx4 v[154:155], off
	v_lshl_add_u64 v[154:155], v[148:149], 0, s[74:75]
	s_add_i32 m0, s15, 0xe000
	s_nop 0
	global_load_lds_dwordx4 v[154:155], off
	s_waitcnt vmcnt(8)
	s_waitcnt lgkmcnt(0)
	s_barrier
	s_waitcnt lgkmcnt(0)
	v_mfma_f32_16x16x32_bf16 v[110:113], v[150:153], v[192:195], v[110:113]
	v_mfma_f32_16x16x32_bf16 v[106:109], v[168:171], v[192:195], v[106:109]
	v_mfma_f32_16x16x32_bf16 v[102:105], v[150:153], v[200:203], v[102:105]
	v_mfma_f32_16x16x32_bf16 v[98:101], v[168:171], v[200:203], v[98:101]
	v_mfma_f32_16x16x32_bf16 v[94:97], v[150:153], v[208:211], v[94:97]
	v_mfma_f32_16x16x32_bf16 v[90:93], v[168:171], v[208:211], v[90:93]
	v_mfma_f32_16x16x32_bf16 v[86:89], v[150:153], v[216:219], v[86:89]
	v_mfma_f32_16x16x32_bf16 v[82:85], v[168:171], v[216:219], v[82:85]
	v_mfma_f32_16x16x32_bf16 v[110:113], v[164:167], v[196:199], v[110:113]
	v_mfma_f32_16x16x32_bf16 v[106:109], v[172:175], v[196:199], v[106:109]
	v_mfma_f32_16x16x32_bf16 v[102:105], v[164:167], v[204:207], v[102:105]
	v_mfma_f32_16x16x32_bf16 v[98:101], v[172:175], v[204:207], v[98:101]
	v_mfma_f32_16x16x32_bf16 v[94:97], v[164:167], v[212:215], v[94:97]
	v_mfma_f32_16x16x32_bf16 v[90:93], v[172:175], v[212:215], v[90:93]
	v_mfma_f32_16x16x32_bf16 v[86:89], v[164:167], v[220:223], v[86:89]
	v_mfma_f32_16x16x32_bf16 v[82:85], v[172:175], v[220:223], v[82:85]
	v_mfma_f32_16x16x32_bf16 v[78:81], v[176:179], v[192:195], v[78:81]
	v_mfma_f32_16x16x32_bf16 v[74:77], v[184:187], v[192:195], v[74:77]
	v_mfma_f32_16x16x32_bf16 v[70:73], v[176:179], v[200:203], v[70:73]
	v_mfma_f32_16x16x32_bf16 v[66:69], v[184:187], v[200:203], v[66:69]
	v_mfma_f32_16x16x32_bf16 v[62:65], v[176:179], v[208:211], v[62:65]
	v_mfma_f32_16x16x32_bf16 v[58:61], v[184:187], v[208:211], v[58:61]
	v_mfma_f32_16x16x32_bf16 v[54:57], v[176:179], v[216:219], v[54:57]
	v_mfma_f32_16x16x32_bf16 v[50:53], v[184:187], v[216:219], v[50:53]
	v_mfma_f32_16x16x32_bf16 v[78:81], v[180:183], v[196:199], v[78:81]
	v_mfma_f32_16x16x32_bf16 v[74:77], v[188:191], v[196:199], v[74:77]
	v_mfma_f32_16x16x32_bf16 v[70:73], v[180:183], v[204:207], v[70:73]
	v_mfma_f32_16x16x32_bf16 v[66:69], v[188:191], v[204:207], v[66:69]
	v_mfma_f32_16x16x32_bf16 v[62:65], v[180:183], v[212:215], v[62:65]
	v_mfma_f32_16x16x32_bf16 v[58:61], v[188:191], v[212:215], v[58:61]
	v_mfma_f32_16x16x32_bf16 v[54:57], v[180:183], v[220:223], v[54:57]
	v_mfma_f32_16x16x32_bf16 v[50:53], v[188:191], v[220:223], v[50:53]
	s_barrier
	s_add_i32 s69, s88, s83
	v_lshl_add_u64 v[154:155], s[76:77], 0, v[132:133]
	s_mov_b32 m0, s69
	ds_read_b128 v[192:195], v162 offset:16384
	ds_read_b128 v[196:199], v162 offset:17408
	ds_read_b128 v[200:203], v162 offset:18432
	ds_read_b128 v[204:207], v162 offset:19456
	ds_read_b128 v[208:211], v162 offset:20480
	ds_read_b128 v[212:215], v162 offset:21504
	ds_read_b128 v[216:219], v162 offset:22528
	ds_read_b128 v[220:223], v162 offset:23552
	global_load_lds_dwordx4 v[154:155], off
	s_add_i32 m0, s69, 0x2000
	s_add_u32 s92, s76, 0x40000
	v_lshl_add_u64 v[224:225], s[76:77], 0, v[136:137]
	s_addc_u32 s93, s77, 0
	s_add_i32 s69, s89, s83
	global_load_lds_dwordx4 v[224:225], off
	v_lshl_add_u64 v[226:227], s[92:93], 0, v[132:133]
	s_mov_b32 m0, s69
	v_lshl_add_u64 v[228:229], s[78:79], 0, v[134:135]
	global_load_lds_dwordx4 v[226:227], off
	v_lshl_add_u64 v[226:227], s[92:93], 0, v[136:137]
	s_add_i32 m0, s69, 0x2000
	s_nop 0
	global_load_lds_dwordx4 v[226:227], off
	v_lshl_add_u64 v[226:227], s[78:79], 0, v[130:131]
	s_mov_b32 m0, s15
	s_nop 0
	global_load_lds_dwordx4 v[226:227], off
	s_mov_b32 m0, s17
	s_nop 0
	global_load_lds_dwordx4 v[228:229], off
	s_waitcnt vmcnt(8)
	s_waitcnt lgkmcnt(0)
	s_barrier
; #define PG8_STAGEA(bufoff, gbase) PG8_STAGE_(bufoff, gbase, voffA)
; #define PG8_LDA(dst, b, h) do { _Pragma("unroll") for (int m = 0; m < 4; ++m) _Pragma("unroll") for (int k = 0; k < 2; ++k) dst[m][k] = *(const LAS bf16x8*)(lds + PG8_SA(b, h) + aoff + m * 2048 + k * 1024); } while (0)
; #define PG8_LDB(dst, b, h) do { _Pragma("unroll") for (int n = 0; n < 2; ++n) _Pragma("unroll") for (int k = 0; k < 2; ++k) dst[n][k] = *(const LAS bf16x8*)(lds + PG8_SB(b, h) + boff + n * 2048 + k * 1024); } while (0)
; #define PG8_MMA(ai, bj, At, Bt_) do { __builtin_amdgcn_s_setprio(1); _Pragma("unroll") for (int m = 0; m < 4; ++m) _Pragma("unroll") for (int n = 0; n < 2; ++n) _Pragma("unroll") for (int k = 0; k < 2; ++k) \
;         acc[ai][bj][m][n] = __builtin_amdgcn_mfma_f32_16x16x32_bf16(Bt_[n][k], At[m][k], acc[ai][bj][m][n], 0, 0, 0); __builtin_amdgcn_s_setprio(0); } while (0)
; #define PG8_WAIT_V(n) asm volatile("s_waitcnt vmcnt(" #n ")" ::: "memory")
; #define PG8_WAIT_L(n) asm volatile("s_waitcnt lgkmcnt(" #n ")" ::: "memory")
; #define PG8_BAR __builtin_amdgcn_s_barrier()
; #define PG8_SCHED __builtin_amdgcn_sched_barrier(0)
; template <int EK, int SK = -1>
; __device__ __forceinline__ void gemm_phase(LAS unsigned char* lds, const bf16_t* A, const bf16_t* Bt, int nM, int N, int K, const EpiArgs& E) {
;     ...
;             PG8_WAIT_V(8); PG8_WAIT_L(0); PG8_BAR; PG8_MMA(1, 0, At, B0); PG8_MMA(1, 1, At, B1); PG8_BAR; PG8_SCHED;
;             PG8_LDB(B0, 1, 0); PG8_LDB(B1, 1, 1); PG8_SCHED; PG8_LDA(At, 1, 0); PG8_STAGEA(PG8_SA(0, 1), a2 + hstep);
;             PG8_WAIT_V(8); PG8_WAIT_L(0); PG8_BAR; PG8_MMA(0, 0, At, B0); PG8_MMA(0, 1, At, B1); PG8_BAR; PG8_SCHED;
	s_waitcnt lgkmcnt(0)
	v_mfma_f32_16x16x32_bf16 v[46:49], v[150:153], v[192:195], v[46:49]
	v_mfma_f32_16x16x32_bf16 v[42:45], v[168:171], v[192:195], v[42:45]
	v_mfma_f32_16x16x32_bf16 v[38:41], v[150:153], v[200:203], v[38:41]
	v_mfma_f32_16x16x32_bf16 v[34:37], v[168:171], v[200:203], v[34:37]
	v_mfma_f32_16x16x32_bf16 v[30:33], v[150:153], v[208:211], v[30:33]
	v_mfma_f32_16x16x32_bf16 v[26:29], v[168:171], v[208:211], v[26:29]
	v_mfma_f32_16x16x32_bf16 v[22:25], v[150:153], v[216:219], v[22:25]
	v_mfma_f32_16x16x32_bf16 v[18:21], v[168:171], v[216:219], v[18:21]
	v_mfma_f32_16x16x32_bf16 v[46:49], v[164:167], v[196:199], v[46:49]
	v_mfma_f32_16x16x32_bf16 v[42:45], v[172:175], v[196:199], v[42:45]
	v_mfma_f32_16x16x32_bf16 v[38:41], v[164:167], v[204:207], v[38:41]
	v_mfma_f32_16x16x32_bf16 v[34:37], v[172:175], v[204:207], v[34:37]
	v_mfma_f32_16x16x32_bf16 v[30:33], v[164:167], v[212:215], v[30:33]
	v_mfma_f32_16x16x32_bf16 v[26:29], v[172:175], v[212:215], v[26:29]
	v_mfma_f32_16x16x32_bf16 v[22:25], v[164:167], v[220:223], v[22:25]
	v_mfma_f32_16x16x32_bf16 v[18:21], v[172:175], v[220:223], v[18:21]
	v_mfma_f32_16x16x32_bf16 v[14:17], v[176:179], v[192:195], v[14:17]
	v_mfma_f32_16x16x32_bf16 v[10:13], v[184:187], v[192:195], v[10:13]
	v_mfma_f32_16x16x32_bf16 v[6:9], v[176:179], v[200:203], v[6:9]
	v_mfma_f32_16x16x32_bf16 v[2:5], v[184:187], v[200:203], v[2:5]
	v_mfma_f32_16x16x32_bf16 v[114:117], v[176:179], v[208:211], v[114:117]
	v_mfma_f32_16x16x32_bf16 v[118:121], v[184:187], v[208:211], v[118:121]
	v_mfma_f32_16x16x32_bf16 v[122:125], v[176:179], v[216:219], v[122:125]
	v_mfma_f32_16x16x32_bf16 v[126:129], v[184:187], v[216:219], v[126:129]
	v_mfma_f32_16x16x32_bf16 v[14:17], v[180:183], v[196:199], v[14:17]
	v_mfma_f32_16x16x32_bf16 v[10:13], v[188:191], v[196:199], v[10:13]
	v_mfma_f32_16x16x32_bf16 v[6:9], v[180:183], v[204:207], v[6:9]
	v_mfma_f32_16x16x32_bf16 v[2:5], v[188:191], v[204:207], v[2:5]
	v_mfma_f32_16x16x32_bf16 v[114:117], v[180:183], v[212:215], v[114:117]
	v_mfma_f32_16x16x32_bf16 v[118:121], v[188:191], v[212:215], v[118:121]
	v_mfma_f32_16x16x32_bf16 v[122:125], v[180:183], v[220:223], v[122:125]
	v_mfma_f32_16x16x32_bf16 v[126:129], v[188:191], v[220:223], v[126:129]
	s_barrier
	s_add_i32 s69, 0, 0x18000
	v_add_u32_e32 v163, s69, v159
	s_add_i32 s91, 0, 0x1c000
	ds_read_b128 v[150:153], v163
	ds_read_b128 v[164:167], v163 offset:1024
	ds_read_b128 v[168:171], v163 offset:2048
	ds_read_b128 v[172:175], v163 offset:3072
	v_add_u32_e32 v163, s91, v159
	ds_read_b128 v[176:179], v163
	ds_read_b128 v[180:183], v163 offset:1024
	ds_read_b128 v[184:187], v163 offset:2048
	ds_read_b128 v[188:191], v163 offset:3072
	s_add_u32 s78, s78, 0x40000
	s_addc_u32 s79, s79, 0
	s_mov_b32 m0, s84
	v_lshl_add_u64 v[230:231], s[78:79], 0, v[130:131]
	ds_read_b128 v[192:195], v162 offset:32768
	ds_read_b128 v[196:199], v162 offset:33792
	ds_read_b128 v[200:203], v162 offset:34816
	ds_read_b128 v[204:207], v162 offset:35840
	ds_read_b128 v[208:211], v162 offset:36864
	ds_read_b128 v[212:215], v162 offset:37888
	ds_read_b128 v[216:219], v162 offset:38912
	ds_read_b128 v[220:223], v162 offset:39936
	global_load_lds_dwordx4 v[230:231], off
	v_lshl_add_u64 v[230:231], s[78:79], 0, v[134:135]
	s_mov_b32 m0, s85
	s_nop 0
	global_load_lds_dwordx4 v[230:231], off
	s_waitcnt vmcnt(8)
	s_waitcnt lgkmcnt(0)
	s_barrier
	s_waitcnt lgkmcnt(0)
	v_mfma_f32_16x16x32_bf16 v[110:113], v[150:153], v[192:195], v[110:113]
	v_mfma_f32_16x16x32_bf16 v[106:109], v[168:171], v[192:195], v[106:109]
	v_mfma_f32_16x16x32_bf16 v[102:105], v[150:153], v[200:203], v[102:105]
	v_mfma_f32_16x16x32_bf16 v[98:101], v[168:171], v[200:203], v[98:101]
	v_mfma_f32_16x16x32_bf16 v[94:97], v[150:153], v[208:211], v[94:97]
	v_mfma_f32_16x16x32_bf16 v[90:93], v[168:171], v[208:211], v[90:93]
	v_mfma_f32_16x16x32_bf16 v[86:89], v[150:153], v[216:219], v[86:89]
	v_mfma_f32_16x16x32_bf16 v[82:85], v[168:171], v[216:219], v[82:85]
	v_mfma_f32_16x16x32_bf16 v[110:113], v[164:167], v[196:199], v[110:113]
	v_mfma_f32_16x16x32_bf16 v[106:109], v[172:175], v[196:199], v[106:109]
	v_mfma_f32_16x16x32_bf16 v[102:105], v[164:167], v[204:207], v[102:105]
	v_mfma_f32_16x16x32_bf16 v[98:101], v[172:175], v[204:207], v[98:101]
	v_mfma_f32_16x16x32_bf16 v[94:97], v[164:167], v[212:215], v[94:97]
	v_mfma_f32_16x16x32_bf16 v[90:93], v[172:175], v[212:215], v[90:93]
	v_mfma_f32_16x16x32_bf16 v[86:89], v[164:167], v[220:223], v[86:89]
	v_mfma_f32_16x16x32_bf16 v[82:85], v[172:175], v[220:223], v[82:85]
	v_mfma_f32_16x16x32_bf16 v[78:81], v[176:179], v[192:195], v[78:81]
	v_mfma_f32_16x16x32_bf16 v[74:77], v[184:187], v[192:195], v[74:77]
	v_mfma_f32_16x16x32_bf16 v[70:73], v[176:179], v[200:203], v[70:73]
	v_mfma_f32_16x16x32_bf16 v[66:69], v[184:187], v[200:203], v[66:69]
	v_mfma_f32_16x16x32_bf16 v[62:65], v[176:179], v[208:211], v[62:65]
	v_mfma_f32_16x16x32_bf16 v[58:61], v[184:187], v[208:211], v[58:61]
	v_mfma_f32_16x16x32_bf16 v[54:57], v[176:179], v[216:219], v[54:57]
	v_mfma_f32_16x16x32_bf16 v[50:53], v[184:187], v[216:219], v[50:53]
	v_mfma_f32_16x16x32_bf16 v[78:81], v[180:183], v[196:199], v[78:81]
	v_mfma_f32_16x16x32_bf16 v[74:77], v[188:191], v[196:199], v[74:77]
	v_mfma_f32_16x16x32_bf16 v[70:73], v[180:183], v[204:207], v[70:73]
	v_mfma_f32_16x16x32_bf16 v[66:69], v[188:191], v[204:207], v[66:69]
	v_mfma_f32_16x16x32_bf16 v[62:65], v[180:183], v[212:215], v[62:65]
	v_mfma_f32_16x16x32_bf16 v[58:61], v[188:191], v[212:215], v[58:61]
	v_mfma_f32_16x16x32_bf16 v[54:57], v[180:183], v[220:223], v[54:57]
	v_mfma_f32_16x16x32_bf16 v[50:53], v[188:191], v[220:223], v[50:53]
	s_barrier
; #define PG8_STAGEA(bufoff, gbase) PG8_STAGE_(bufoff, gbase, voffA)
; #define PG8_STAGEB(bufoff, gbase) PG8_STAGE_(bufoff, gbase, voffB)
; #define PG8_LDA(dst, b, h) do { _Pragma("unroll") for (int m = 0; m < 4; ++m) _Pragma("unroll") for (int k = 0; k < 2; ++k) dst[m][k] = *(const LAS bf16x8*)(lds + PG8_SA(b, h) + aoff + m * 2048 + k * 1024); } while (0)
; #define PG8_MMA(ai, bj, At, Bt_) do { __builtin_amdgcn_s_setprio(1); _Pragma("unroll") for (int m = 0; m < 4; ++m) _Pragma("unroll") for (int n = 0; n < 2; ++n) _Pragma("unroll") for (int k = 0; k < 2; ++k) \
;         acc[ai][bj][m][n] = __builtin_amdgcn_mfma_f32_16x16x32_bf16(Bt_[n][k], At[m][k], acc[ai][bj][m][n], 0, 0, 0); __builtin_amdgcn_s_setprio(0); } while (0)
; #define PG8_WAIT_V(n) asm volatile("s_waitcnt vmcnt(" #n ")" ::: "memory")
; #define PG8_WAIT_L(n) asm volatile("s_waitcnt lgkmcnt(" #n ")" ::: "memory")
; #define PG8_BAR __builtin_amdgcn_s_barrier()
; #define PG8_SCHED __builtin_amdgcn_sched_barrier(0)
; template <int EK, int SK = -1>
; __device__ __forceinline__ void gemm_phase(LAS unsigned char* lds, const bf16_t* A, const bf16_t* Bt, int nM, int N, int K, const EpiArgs& E) {
;     ...
;             PG8_LDA(At, 1, 1); PG8_STAGEB(PG8_SB(1, 0), b3); PG8_STAGEB(PG8_SB(1, 1), b3 + hstep); PG8_STAGEA(PG8_SA(1, 0), a3);
;             PG8_WAIT_V(8); PG8_WAIT_L(0); PG8_BAR; PG8_MMA(1, 0, At, B0); PG8_MMA(1, 1, At, B1); PG8_BAR; PG8_SCHED;
;         }
	s_add_i32 s69, s69, s83
	v_lshl_add_u64 v[154:155], v[154:155], 0, s[10:11]
	s_mov_b32 m0, s69
	ds_read_b128 v[192:195], v162 offset:49152
	ds_read_b128 v[196:199], v162 offset:50176
	ds_read_b128 v[200:203], v162 offset:51200
	ds_read_b128 v[204:207], v162 offset:52224
	ds_read_b128 v[208:211], v162 offset:53248
	ds_read_b128 v[212:215], v162 offset:54272
	ds_read_b128 v[216:219], v162 offset:55296
	ds_read_b128 v[220:223], v162 offset:56320
	global_load_lds_dwordx4 v[154:155], off
	s_add_i32 m0, s69, 0x2000
	s_add_u32 s76, s76, 0x40080
	v_lshl_add_u64 v[154:155], v[224:225], 0, s[10:11]
	s_addc_u32 s77, s77, 0
	s_add_i32 s69, s91, s83
	global_load_lds_dwordx4 v[154:155], off
	v_lshl_add_u64 v[154:155], s[76:77], 0, v[132:133]
	s_mov_b32 m0, s69
	s_nop 0
	global_load_lds_dwordx4 v[154:155], off
	v_lshl_add_u64 v[154:155], s[76:77], 0, v[136:137]
	s_add_i32 m0, s69, 0x2000
	s_nop 0
	global_load_lds_dwordx4 v[154:155], off
	v_lshl_add_u64 v[154:155], v[226:227], 0, s[10:11]
	s_mov_b32 m0, s86
	s_nop 0
	global_load_lds_dwordx4 v[154:155], off
	v_lshl_add_u64 v[154:155], v[228:229], 0, s[10:11]
	s_mov_b32 m0, s87
	s_nop 0
	global_load_lds_dwordx4 v[154:155], off
	s_waitcnt vmcnt(8)
	s_waitcnt lgkmcnt(0)
	s_barrier
	s_waitcnt lgkmcnt(0)
	v_mfma_f32_16x16x32_bf16 v[46:49], v[150:153], v[192:195], v[46:49]
	v_mfma_f32_16x16x32_bf16 v[42:45], v[168:171], v[192:195], v[42:45]
	v_mfma_f32_16x16x32_bf16 v[38:41], v[150:153], v[200:203], v[38:41]
	v_mfma_f32_16x16x32_bf16 v[34:37], v[168:171], v[200:203], v[34:37]
	v_mfma_f32_16x16x32_bf16 v[30:33], v[150:153], v[208:211], v[30:33]
	v_mfma_f32_16x16x32_bf16 v[26:29], v[168:171], v[208:211], v[26:29]
	v_mfma_f32_16x16x32_bf16 v[22:25], v[150:153], v[216:219], v[22:25]
	v_mfma_f32_16x16x32_bf16 v[18:21], v[168:171], v[216:219], v[18:21]
	v_mfma_f32_16x16x32_bf16 v[46:49], v[164:167], v[196:199], v[46:49]
	v_mfma_f32_16x16x32_bf16 v[42:45], v[172:175], v[196:199], v[42:45]
	v_mfma_f32_16x16x32_bf16 v[38:41], v[164:167], v[204:207], v[38:41]
	v_mfma_f32_16x16x32_bf16 v[34:37], v[172:175], v[204:207], v[34:37]
	v_mfma_f32_16x16x32_bf16 v[30:33], v[164:167], v[212:215], v[30:33]
	v_mfma_f32_16x16x32_bf16 v[26:29], v[172:175], v[212:215], v[26:29]
	v_mfma_f32_16x16x32_bf16 v[22:25], v[164:167], v[220:223], v[22:25]
	v_mfma_f32_16x16x32_bf16 v[18:21], v[172:175], v[220:223], v[18:21]
	v_mfma_f32_16x16x32_bf16 v[14:17], v[176:179], v[192:195], v[14:17]
	v_mfma_f32_16x16x32_bf16 v[10:13], v[184:187], v[192:195], v[10:13]
	v_mfma_f32_16x16x32_bf16 v[6:9], v[176:179], v[200:203], v[6:9]
	v_mfma_f32_16x16x32_bf16 v[2:5], v[184:187], v[200:203], v[2:5]
	v_mfma_f32_16x16x32_bf16 v[114:117], v[176:179], v[208:211], v[114:117]
	v_mfma_f32_16x16x32_bf16 v[118:121], v[184:187], v[208:211], v[118:121]
	v_mfma_f32_16x16x32_bf16 v[122:125], v[176:179], v[216:219], v[122:125]
	v_mfma_f32_16x16x32_bf16 v[126:129], v[184:187], v[216:219], v[126:129]
	v_mfma_f32_16x16x32_bf16 v[14:17], v[180:183], v[196:199], v[14:17]
	v_mfma_f32_16x16x32_bf16 v[10:13], v[188:191], v[196:199], v[10:13]
	v_mfma_f32_16x16x32_bf16 v[6:9], v[180:183], v[204:207], v[6:9]
	v_mfma_f32_16x16x32_bf16 v[2:5], v[188:191], v[204:207], v[2:5]
	v_mfma_f32_16x16x32_bf16 v[114:117], v[180:183], v[212:215], v[114:117]
	v_mfma_f32_16x16x32_bf16 v[118:121], v[188:191], v[212:215], v[118:121]
	v_mfma_f32_16x16x32_bf16 v[122:125], v[180:183], v[220:223], v[122:125]
	v_mfma_f32_16x16x32_bf16 v[126:129], v[188:191], v[220:223], v[126:129]
	s_barrier
	s_add_i32 s59, s59, 2
	s_add_u32 s74, s74, 0x100
	s_addc_u32 s75, s75, 0
	s_cmp_gt_u32 s59, 13
	s_cbranch_scc0 .LBB0_538
	s_and_b64 vcc, exec, s[12:13]
	s_cbranch_vccz .LBB0_541
	s_barrier

; __device__ __forceinline__ unsigned xb_add(unsigned* p, unsigned v) { return __hip_atomic_fetch_add(p, v, __ATOMIC_RELAXED, __HIP_MEMORY_SCOPE_AGENT); }
; __device__ __forceinline__ void xcd_barrier(const XcdBarrier& b) {
;     asm volatile("s_waitcnt vmcnt(0)" ::: "memory");
;     __syncthreads();
;     if (threadIdx.x == 0) {
;         unsigned* bar = b.bar;
;         __builtin_amdgcn_s_waitcnt(0);
;         unsigned nloc = b.st[0], nx = b.st[1];
;         if (nloc == 0u) { xcd_barrier_complete(bar, b.x, nloc, nx); b.st[0] = nloc; b.st[1] = nx; }
;         const unsigned old = xb_add(&bar[XB_XSUB(b.x)], 1u);
;         const unsigned gen = old / nloc;
;         if (old + 1u == (gen + 1u) * nloc) {
.LBB0_709:
	s_waitcnt lgkmcnt(0)
	s_load_dwordx16 s[36:51], s[0:1], 0x40
	s_cmp_gt_i32 s35, 5
	s_cselect_b64 s[4:5], -1, 0
	s_and_b64 s[6:7], s[18:19], s[4:5]
	s_andn2_b64 vcc, exec, s[6:7]
	s_cbranch_vccnz .LBB0_759
	s_waitcnt vmcnt(0)
	v_cmp_eq_u32_e32 vcc, 0, v0
	s_waitcnt vmcnt(0) lgkmcnt(0)
	s_barrier
	v_readfirstlane_b32 s98, v0
	s_nop 3
	s_lshr_b32 s98, s98, 6
	s_cmp_lg_u32 s98, 1
	s_cbranch_scc1 .Lmy_noinv5
	buffer_inv sc1
	s_waitcnt vmcnt(0)
.Lmy_noinv5:
	s_and_saveexec_b64 s[6:7], vcc
	s_cbranch_execz .LBB0_758
	s_add_i32 s3, 0, 0x20000
	v_mov_b32_e32 v1, s3
	s_waitcnt vmcnt(0) expcnt(0) lgkmcnt(0)
	ds_read_b32 v3, v1
	s_add_i32 s3, 0, 0x20004
	v_mov_b32_e32 v1, s3
	ds_read_b32 v1, v1
	s_waitcnt lgkmcnt(1)
	v_cmp_ne_u32_e32 vcc, 0, v3
	s_cbranch_vccnz .LBB0_726
	s_load_dwordx2 s[12:13], s[0:1], 0xb8
	s_load_dword s3, s[0:1], 0xc0
	s_add_u32 s8, s30, 0xb4b8200
	s_addc_u32 s9, s31, 0
	s_add_u32 s10, s30, 0xb4b8400
	s_waitcnt lgkmcnt(0)
	s_mul_i32 s11, s13, s12
	s_mul_i32 s3, s11, s3
	s_addc_u32 s11, s31, 0
	s_add_u32 s12, s30, 0xb4b8500
	s_addc_u32 s13, s31, 0
	s_add_u32 s14, s30, 0xb4b8600
	s_addc_u32 s15, s31, 0
	s_add_u32 s16, s30, 0xb4b8700
	s_addc_u32 s17, s31, 0
	s_add_u32 s18, s30, 0xb4b8800
	s_addc_u32 s19, s31, 0
	s_add_u32 s20, s30, 0xb4b8900
	s_addc_u32 s21, s31, 0
	s_add_u32 s22, s30, 0xb4b8a00
	s_addc_u32 s23, s31, 0
	s_add_u32 s26, s30, 0xb4b8b00
	s_addc_u32 s27, s31, 0
	s_add_u32 s36, s30, 0xb4b8c00
	s_addc_u32 s37, s31, 0
	s_add_u32 s38, s30, 0xb4b8d00
	s_addc_u32 s39, s31, 0
	s_add_u32 s40, s30, 0xb4b8e00
	s_addc_u32 s41, s31, 0
	s_add_u32 s42, s30, 0xb4b8f00
	s_addc_u32 s43, s31, 0
	s_add_u32 s44, s30, 0xb4b9000
	s_addc_u32 s45, s31, 0
	s_add_u32 s52, s30, 0xb4b9100
	s_addc_u32 s53, s31, 0
	s_add_u32 s54, s30, 0xb4b9200
	s_addc_u32 s55, s31, 0
	s_add_u32 s56, s30, 0xb4b9300
	s_addc_u32 s57, s31, 0
	s_mov_b32 s72, 1
	v_mov_b32_e32 v17, 0
	s_branch .LBB0_714

; #define PG8_STAGEA(bufoff, gbase) PG8_STAGE_(bufoff, gbase, voffA)
; #define PG8_STAGEB(bufoff, gbase) PG8_STAGE_(bufoff, gbase, voffB)
; #define PG8_LDA(dst, b, h) do { _Pragma("unroll") for (int m = 0; m < 4; ++m) _Pragma("unroll") for (int k = 0; k < 2; ++k) dst[m][k] = *(const LAS bf16x8*)(lds + PG8_SA(b, h) + aoff + m * 2048 + k * 1024); } while (0)
; #define PG8_LDB(dst, b, h) do { _Pragma("unroll") for (int n = 0; n < 2; ++n) _Pragma("unroll") for (int k = 0; k < 2; ++k) dst[n][k] = *(const LAS bf16x8*)(lds + PG8_SB(b, h) + boff + n * 2048 + k * 1024); } while (0)
; #define PG8_MMA(ai, bj, At, Bt_) do { __builtin_amdgcn_s_setprio(1); _Pragma("unroll") for (int m = 0; m < 4; ++m) _Pragma("unroll") for (int n = 0; n < 2; ++n) _Pragma("unroll") for (int k = 0; k < 2; ++k) \
;         acc[ai][bj][m][n] = __builtin_amdgcn_mfma_f32_16x16x32_bf16(Bt_[n][k], At[m][k], acc[ai][bj][m][n], 0, 0, 0); __builtin_amdgcn_s_setprio(0); } while (0)
; #define PG8_WAIT_V(n) asm volatile("s_waitcnt vmcnt(" #n ")" ::: "memory")
; #define PG8_WAIT_L(n) asm volatile("s_waitcnt lgkmcnt(" #n ")" ::: "memory")
; #define PG8_BAR __builtin_amdgcn_s_barrier()
; template <int EK, int SK = -1>
; __device__ __forceinline__ void gemm_phase(LAS unsigned char* lds, const bf16_t* A, const bf16_t* Bt, int nM, int N, int K, const EpiArgs& E) {
;     ...
;         const bool has_next = S.next(ui + 1, nxt);
;         const char* nA = has_next ? (const char*)A + (size_t)nxt.pm * tstep : cA; const char* nB = has_next ? (const char*)Bt + (size_t)nxt.pn * tstep : cB;
;         for (int t = 0; t < nt; t += 2) {
;             const bool last = (t == nt - 2);
;             const char* a1 = cA + (size_t)(t + 1) * kstep;
;             const char* a2 = last ? nA : cA + (size_t)(t + 2) * kstep; const char* b2 = last ? nB : cB + (size_t)(t + 2) * kstep;
;             const char* a3 = a2 + kstep; const char* b3 = b2 + kstep;
;             PG8_LDB(B0, 0, 0); PG8_LDB(B1, 0, 1); PG8_SCHED; PG8_LDA(At, 0, 0); PG8_STAGEA(PG8_SA(1, 1), a1 + hstep);
;             PG8_WAIT_V(8); PG8_WAIT_L(0); PG8_BAR; PG8_MMA(0, 0, At, B0); PG8_MMA(0, 1, At, B1); PG8_BAR; PG8_SCHED;
;             PG8_LDA(At, 0, 1); PG8_STAGEB(PG8_SB(0, 0), b2); PG8_STAGEB(PG8_SB(0, 1), b2 + hstep); PG8_STAGEA(PG8_SA(0, 0), a2);
;             PG8_WAIT_V(8); PG8_WAIT_L(0); PG8_BAR; PG8_MMA(1, 0, At, B0); PG8_MMA(1, 1, At, B1); PG8_BAR; PG8_SCHED;
.LBB0_793:
	v_add_u32_e32 v150, s71, v152
	ds_read_b128 v[156:159], v150
	ds_read_b128 v[160:163], v150 offset:1024
	ds_read_b128 v[164:167], v150 offset:2048
	ds_read_b128 v[168:171], v150 offset:3072
	v_add_u32_e32 v150, s72, v152
	s_add_u32 s40, s14, s38
	ds_read_b128 v[172:175], v150
	ds_read_b128 v[176:179], v150 offset:1024
	ds_read_b128 v[180:183], v150 offset:2048
	ds_read_b128 v[184:187], v150 offset:3072
	s_addc_u32 s41, s15, s39
	s_add_u32 s40, s40, 0x100
	s_addc_u32 s41, s41, 0
	s_add_u32 s79, s77, s38
	s_addc_u32 s80, s78, s39
	s_cmpk_eq_i32 s38, 0x1500
	s_cselect_b32 s43, s37, s41
	s_cselect_b32 s42, s36, s40
	s_cselect_b32 s41, s11, s80
	s_cselect_b32 s40, s10, s79
	v_lshl_add_u64 v[150:151], v[146:147], 0, s[38:39]
	s_add_i32 m0, s55, 0xc000
	ds_read_b128 v[188:191], v154
	ds_read_b128 v[192:195], v154 offset:1024
	ds_read_b128 v[196:199], v154 offset:2048
	ds_read_b128 v[200:203], v154 offset:3072
	ds_read_b128 v[204:207], v154 offset:4096
	ds_read_b128 v[208:211], v154 offset:5120
	ds_read_b128 v[212:215], v154 offset:6144
	ds_read_b128 v[216:219], v154 offset:7168
	global_load_lds_dwordx4 v[150:151], off
	v_lshl_add_u64 v[150:151], v[148:149], 0, s[38:39]
	s_add_i32 m0, s55, 0xe000
	s_nop 0
	global_load_lds_dwordx4 v[150:151], off
	s_waitcnt vmcnt(8)
	s_waitcnt lgkmcnt(0)
	s_barrier
	s_waitcnt lgkmcnt(0)
	v_mfma_f32_16x16x32_bf16 v[126:129], v[156:159], v[188:191], v[126:129]
	v_mfma_f32_16x16x32_bf16 v[122:125], v[164:167], v[188:191], v[122:125]
	v_mfma_f32_16x16x32_bf16 v[118:121], v[156:159], v[196:199], v[118:121]
	v_mfma_f32_16x16x32_bf16 v[114:117], v[164:167], v[196:199], v[114:117]
	v_mfma_f32_16x16x32_bf16 v[110:113], v[156:159], v[204:207], v[110:113]
	v_mfma_f32_16x16x32_bf16 v[106:109], v[164:167], v[204:207], v[106:109]
	v_mfma_f32_16x16x32_bf16 v[102:105], v[156:159], v[212:215], v[102:105]
	v_mfma_f32_16x16x32_bf16 v[98:101], v[164:167], v[212:215], v[98:101]
	v_mfma_f32_16x16x32_bf16 v[126:129], v[160:163], v[192:195], v[126:129]
	v_mfma_f32_16x16x32_bf16 v[122:125], v[168:171], v[192:195], v[122:125]
	v_mfma_f32_16x16x32_bf16 v[118:121], v[160:163], v[200:203], v[118:121]
	v_mfma_f32_16x16x32_bf16 v[114:117], v[168:171], v[200:203], v[114:117]
	v_mfma_f32_16x16x32_bf16 v[110:113], v[160:163], v[208:211], v[110:113]
	v_mfma_f32_16x16x32_bf16 v[106:109], v[168:171], v[208:211], v[106:109]
	v_mfma_f32_16x16x32_bf16 v[102:105], v[160:163], v[216:219], v[102:105]
	v_mfma_f32_16x16x32_bf16 v[98:101], v[168:171], v[216:219], v[98:101]
	v_mfma_f32_16x16x32_bf16 v[94:97], v[172:175], v[188:191], v[94:97]
	v_mfma_f32_16x16x32_bf16 v[90:93], v[180:183], v[188:191], v[90:93]
	v_mfma_f32_16x16x32_bf16 v[86:89], v[172:175], v[196:199], v[86:89]
	v_mfma_f32_16x16x32_bf16 v[82:85], v[180:183], v[196:199], v[82:85]
	v_mfma_f32_16x16x32_bf16 v[78:81], v[172:175], v[204:207], v[78:81]
	v_mfma_f32_16x16x32_bf16 v[74:77], v[180:183], v[204:207], v[74:77]
	v_mfma_f32_16x16x32_bf16 v[70:73], v[172:175], v[212:215], v[70:73]
	v_mfma_f32_16x16x32_bf16 v[66:69], v[180:183], v[212:215], v[66:69]
	v_mfma_f32_16x16x32_bf16 v[94:97], v[176:179], v[192:195], v[94:97]
	v_mfma_f32_16x16x32_bf16 v[90:93], v[184:187], v[192:195], v[90:93]
	v_mfma_f32_16x16x32_bf16 v[86:89], v[176:179], v[200:203], v[86:89]
	v_mfma_f32_16x16x32_bf16 v[82:85], v[184:187], v[200:203], v[82:85]
	v_mfma_f32_16x16x32_bf16 v[78:81], v[176:179], v[208:211], v[78:81]
	v_mfma_f32_16x16x32_bf16 v[74:77], v[184:187], v[208:211], v[74:77]
	v_mfma_f32_16x16x32_bf16 v[70:73], v[176:179], v[216:219], v[70:73]
	v_mfma_f32_16x16x32_bf16 v[66:69], v[184:187], v[216:219], v[66:69]
	s_barrier
	s_add_i32 s79, s71, s54
	v_lshl_add_u64 v[150:151], s[40:41], 0, v[132:133]
	s_mov_b32 m0, s79
	ds_read_b128 v[188:191], v154 offset:16384
	ds_read_b128 v[192:195], v154 offset:17408
	ds_read_b128 v[196:199], v154 offset:18432
	ds_read_b128 v[200:203], v154 offset:19456
	ds_read_b128 v[204:207], v154 offset:20480
	ds_read_b128 v[208:211], v154 offset:21504
	ds_read_b128 v[212:215], v154 offset:22528
	ds_read_b128 v[216:219], v154 offset:23552
	global_load_lds_dwordx4 v[150:151], off
	s_add_i32 m0, s79, 0x2000
	s_add_u32 s80, s40, 0xb0000
	v_lshl_add_u64 v[220:221], s[40:41], 0, v[136:137]
	s_addc_u32 s81, s41, 0
	s_add_i32 s79, s72, s54
	global_load_lds_dwordx4 v[220:221], off
	v_lshl_add_u64 v[222:223], s[80:81], 0, v[132:133]
	s_mov_b32 m0, s79
	v_lshl_add_u64 v[224:225], s[42:43], 0, v[134:135]
	global_load_lds_dwordx4 v[222:223], off
	v_lshl_add_u64 v[222:223], s[80:81], 0, v[136:137]
	s_add_i32 m0, s79, 0x2000
	s_nop 0
	global_load_lds_dwordx4 v[222:223], off
	v_lshl_add_u64 v[222:223], s[42:43], 0, v[130:131]
	s_mov_b32 m0, s55
	s_nop 0
	global_load_lds_dwordx4 v[222:223], off
	s_mov_b32 m0, s56
	s_nop 0
	global_load_lds_dwordx4 v[224:225], off
	s_waitcnt vmcnt(8)
	s_waitcnt lgkmcnt(0)
	s_barrier
; #define PG8_STAGEA(bufoff, gbase) PG8_STAGE_(bufoff, gbase, voffA)
; #define PG8_LDA(dst, b, h) do { _Pragma("unroll") for (int m = 0; m < 4; ++m) _Pragma("unroll") for (int k = 0; k < 2; ++k) dst[m][k] = *(const LAS bf16x8*)(lds + PG8_SA(b, h) + aoff + m * 2048 + k * 1024); } while (0)
; #define PG8_LDB(dst, b, h) do { _Pragma("unroll") for (int n = 0; n < 2; ++n) _Pragma("unroll") for (int k = 0; k < 2; ++k) dst[n][k] = *(const LAS bf16x8*)(lds + PG8_SB(b, h) + boff + n * 2048 + k * 1024); } while (0)
; #define PG8_MMA(ai, bj, At, Bt_) do { __builtin_amdgcn_s_setprio(1); _Pragma("unroll") for (int m = 0; m < 4; ++m) _Pragma("unroll") for (int n = 0; n < 2; ++n) _Pragma("unroll") for (int k = 0; k < 2; ++k) \
;         acc[ai][bj][m][n] = __builtin_amdgcn_mfma_f32_16x16x32_bf16(Bt_[n][k], At[m][k], acc[ai][bj][m][n], 0, 0, 0); __builtin_amdgcn_s_setprio(0); } while (0)
; #define PG8_WAIT_V(n) asm volatile("s_waitcnt vmcnt(" #n ")" ::: "memory")
; #define PG8_WAIT_L(n) asm volatile("s_waitcnt lgkmcnt(" #n ")" ::: "memory")
; #define PG8_BAR __builtin_amdgcn_s_barrier()
; #define PG8_SCHED __builtin_amdgcn_sched_barrier(0)
; template <int EK, int SK = -1>
; __device__ __forceinline__ void gemm_phase(LAS unsigned char* lds, const bf16_t* A, const bf16_t* Bt, int nM, int N, int K, const EpiArgs& E) {
;     ...
;             PG8_WAIT_V(8); PG8_WAIT_L(0); PG8_BAR; PG8_MMA(1, 0, At, B0); PG8_MMA(1, 1, At, B1); PG8_BAR; PG8_SCHED;
;             PG8_LDB(B0, 1, 0); PG8_LDB(B1, 1, 1); PG8_SCHED; PG8_LDA(At, 1, 0); PG8_STAGEA(PG8_SA(0, 1), a2 + hstep);
;             PG8_WAIT_V(8); PG8_WAIT_L(0); PG8_BAR; PG8_MMA(0, 0, At, B0); PG8_MMA(0, 1, At, B1); PG8_BAR; PG8_SCHED;
	s_waitcnt lgkmcnt(0)
	v_mfma_f32_16x16x32_bf16 v[62:65], v[156:159], v[188:191], v[62:65]
	v_mfma_f32_16x16x32_bf16 v[58:61], v[164:167], v[188:191], v[58:61]
	v_mfma_f32_16x16x32_bf16 v[54:57], v[156:159], v[196:199], v[54:57]
	v_mfma_f32_16x16x32_bf16 v[50:53], v[164:167], v[196:199], v[50:53]
	v_mfma_f32_16x16x32_bf16 v[46:49], v[156:159], v[204:207], v[46:49]
	v_mfma_f32_16x16x32_bf16 v[42:45], v[164:167], v[204:207], v[42:45]
	v_mfma_f32_16x16x32_bf16 v[38:41], v[156:159], v[212:215], v[38:41]
	v_mfma_f32_16x16x32_bf16 v[34:37], v[164:167], v[212:215], v[34:37]
	v_mfma_f32_16x16x32_bf16 v[62:65], v[160:163], v[192:195], v[62:65]
	v_mfma_f32_16x16x32_bf16 v[58:61], v[168:171], v[192:195], v[58:61]
	v_mfma_f32_16x16x32_bf16 v[54:57], v[160:163], v[200:203], v[54:57]
	v_mfma_f32_16x16x32_bf16 v[50:53], v[168:171], v[200:203], v[50:53]
	v_mfma_f32_16x16x32_bf16 v[46:49], v[160:163], v[208:211], v[46:49]
	v_mfma_f32_16x16x32_bf16 v[42:45], v[168:171], v[208:211], v[42:45]
	v_mfma_f32_16x16x32_bf16 v[38:41], v[160:163], v[216:219], v[38:41]
	v_mfma_f32_16x16x32_bf16 v[34:37], v[168:171], v[216:219], v[34:37]
	v_mfma_f32_16x16x32_bf16 v[30:33], v[172:175], v[188:191], v[30:33]
	v_mfma_f32_16x16x32_bf16 v[26:29], v[180:183], v[188:191], v[26:29]
	v_mfma_f32_16x16x32_bf16 v[22:25], v[172:175], v[196:199], v[22:25]
	v_mfma_f32_16x16x32_bf16 v[18:21], v[180:183], v[196:199], v[18:21]
	v_mfma_f32_16x16x32_bf16 v[14:17], v[172:175], v[204:207], v[14:17]
	v_mfma_f32_16x16x32_bf16 v[10:13], v[180:183], v[204:207], v[10:13]
	v_mfma_f32_16x16x32_bf16 v[6:9], v[172:175], v[212:215], v[6:9]
	v_mfma_f32_16x16x32_bf16 v[2:5], v[180:183], v[212:215], v[2:5]
	v_mfma_f32_16x16x32_bf16 v[30:33], v[176:179], v[192:195], v[30:33]
	v_mfma_f32_16x16x32_bf16 v[26:29], v[184:187], v[192:195], v[26:29]
	v_mfma_f32_16x16x32_bf16 v[22:25], v[176:179], v[200:203], v[22:25]
	v_mfma_f32_16x16x32_bf16 v[18:21], v[184:187], v[200:203], v[18:21]
	v_mfma_f32_16x16x32_bf16 v[14:17], v[176:179], v[208:211], v[14:17]
	v_mfma_f32_16x16x32_bf16 v[10:13], v[184:187], v[208:211], v[10:13]
	v_mfma_f32_16x16x32_bf16 v[6:9], v[176:179], v[216:219], v[6:9]
	v_mfma_f32_16x16x32_bf16 v[2:5], v[184:187], v[216:219], v[2:5]
	s_barrier
	s_add_i32 s79, 0, 0x18000
	s_add_i32 s80, 0, 0x1c000
	v_add_u32_e32 v168, s79, v152
	v_add_u32_e32 v184, s80, v152
	ds_read_b128 v[156:159], v168
	ds_read_b128 v[160:163], v168 offset:1024
	ds_read_b128 v[164:167], v168 offset:2048
	ds_read_b128 v[168:171], v168 offset:3072
	ds_read_b128 v[172:175], v184
	ds_read_b128 v[176:179], v184 offset:1024
	ds_read_b128 v[180:183], v184 offset:2048
	ds_read_b128 v[184:187], v184 offset:3072
	s_add_u32 s42, s42, 0xb0000
	s_addc_u32 s43, s43, 0
	s_mov_b32 m0, s57
	v_lshl_add_u64 v[226:227], s[42:43], 0, v[130:131]
	ds_read_b128 v[188:191], v154 offset:32768
	ds_read_b128 v[192:195], v154 offset:33792
	ds_read_b128 v[196:199], v154 offset:34816
	ds_read_b128 v[200:203], v154 offset:35840
	ds_read_b128 v[204:207], v154 offset:36864
	ds_read_b128 v[208:211], v154 offset:37888
	ds_read_b128 v[212:215], v154 offset:38912
	ds_read_b128 v[216:219], v154 offset:39936
	global_load_lds_dwordx4 v[226:227], off
	v_lshl_add_u64 v[226:227], s[42:43], 0, v[134:135]
	s_mov_b32 m0, s58
	s_nop 0
	global_load_lds_dwordx4 v[226:227], off
	s_waitcnt vmcnt(8)
	s_waitcnt lgkmcnt(0)
	s_barrier
	s_waitcnt lgkmcnt(0)
	v_mfma_f32_16x16x32_bf16 v[126:129], v[156:159], v[188:191], v[126:129]
	v_mfma_f32_16x16x32_bf16 v[122:125], v[164:167], v[188:191], v[122:125]
	v_mfma_f32_16x16x32_bf16 v[118:121], v[156:159], v[196:199], v[118:121]
	v_mfma_f32_16x16x32_bf16 v[114:117], v[164:167], v[196:199], v[114:117]
	v_mfma_f32_16x16x32_bf16 v[110:113], v[156:159], v[204:207], v[110:113]
	v_mfma_f32_16x16x32_bf16 v[106:109], v[164:167], v[204:207], v[106:109]
	v_mfma_f32_16x16x32_bf16 v[102:105], v[156:159], v[212:215], v[102:105]
	v_mfma_f32_16x16x32_bf16 v[98:101], v[164:167], v[212:215], v[98:101]
	v_mfma_f32_16x16x32_bf16 v[126:129], v[160:163], v[192:195], v[126:129]
	v_mfma_f32_16x16x32_bf16 v[122:125], v[168:171], v[192:195], v[122:125]
	v_mfma_f32_16x16x32_bf16 v[118:121], v[160:163], v[200:203], v[118:121]
	v_mfma_f32_16x16x32_bf16 v[114:117], v[168:171], v[200:203], v[114:117]
	v_mfma_f32_16x16x32_bf16 v[110:113], v[160:163], v[208:211], v[110:113]
	v_mfma_f32_16x16x32_bf16 v[106:109], v[168:171], v[208:211], v[106:109]
	v_mfma_f32_16x16x32_bf16 v[102:105], v[160:163], v[216:219], v[102:105]
	v_mfma_f32_16x16x32_bf16 v[98:101], v[168:171], v[216:219], v[98:101]
	v_mfma_f32_16x16x32_bf16 v[94:97], v[172:175], v[188:191], v[94:97]
	v_mfma_f32_16x16x32_bf16 v[90:93], v[180:183], v[188:191], v[90:93]
	v_mfma_f32_16x16x32_bf16 v[86:89], v[172:175], v[196:199], v[86:89]
	v_mfma_f32_16x16x32_bf16 v[82:85], v[180:183], v[196:199], v[82:85]
	v_mfma_f32_16x16x32_bf16 v[78:81], v[172:175], v[204:207], v[78:81]
	v_mfma_f32_16x16x32_bf16 v[74:77], v[180:183], v[204:207], v[74:77]
	v_mfma_f32_16x16x32_bf16 v[70:73], v[172:175], v[212:215], v[70:73]
	v_mfma_f32_16x16x32_bf16 v[66:69], v[180:183], v[212:215], v[66:69]
	v_mfma_f32_16x16x32_bf16 v[94:97], v[176:179], v[192:195], v[94:97]
	v_mfma_f32_16x16x32_bf16 v[90:93], v[184:187], v[192:195], v[90:93]
	v_mfma_f32_16x16x32_bf16 v[86:89], v[176:179], v[200:203], v[86:89]
	v_mfma_f32_16x16x32_bf16 v[82:85], v[184:187], v[200:203], v[82:85]
	v_mfma_f32_16x16x32_bf16 v[78:81], v[176:179], v[208:211], v[78:81]
	v_mfma_f32_16x16x32_bf16 v[74:77], v[184:187], v[208:211], v[74:77]
	v_mfma_f32_16x16x32_bf16 v[70:73], v[176:179], v[216:219], v[70:73]
	v_mfma_f32_16x16x32_bf16 v[66:69], v[184:187], v[216:219], v[66:69]
	s_barrier
; #define PG8_STAGEA(bufoff, gbase) PG8_STAGE_(bufoff, gbase, voffA)
; #define PG8_STAGEB(bufoff, gbase) PG8_STAGE_(bufoff, gbase, voffB)
; #define PG8_LDA(dst, b, h) do { _Pragma("unroll") for (int m = 0; m < 4; ++m) _Pragma("unroll") for (int k = 0; k < 2; ++k) dst[m][k] = *(const LAS bf16x8*)(lds + PG8_SA(b, h) + aoff + m * 2048 + k * 1024); } while (0)
; #define PG8_MMA(ai, bj, At, Bt_) do { __builtin_amdgcn_s_setprio(1); _Pragma("unroll") for (int m = 0; m < 4; ++m) _Pragma("unroll") for (int n = 0; n < 2; ++n) _Pragma("unroll") for (int k = 0; k < 2; ++k) \
;         acc[ai][bj][m][n] = __builtin_amdgcn_mfma_f32_16x16x32_bf16(Bt_[n][k], At[m][k], acc[ai][bj][m][n], 0, 0, 0); __builtin_amdgcn_s_setprio(0); } while (0)
; #define PG8_WAIT_V(n) asm volatile("s_waitcnt vmcnt(" #n ")" ::: "memory")
; #define PG8_WAIT_L(n) asm volatile("s_waitcnt lgkmcnt(" #n ")" ::: "memory")
; #define PG8_BAR __builtin_amdgcn_s_barrier()
; #define PG8_SCHED __builtin_amdgcn_sched_barrier(0)
; template <int EK, int SK = -1>
; __device__ __forceinline__ void gemm_phase(LAS unsigned char* lds, const bf16_t* A, const bf16_t* Bt, int nM, int N, int K, const EpiArgs& E) {
;     ...
;             PG8_LDA(At, 1, 1); PG8_STAGEB(PG8_SB(1, 0), b3); PG8_STAGEB(PG8_SB(1, 1), b3 + hstep); PG8_STAGEA(PG8_SA(1, 0), a3);
;             PG8_WAIT_V(8); PG8_WAIT_L(0); PG8_BAR; PG8_MMA(1, 0, At, B0); PG8_MMA(1, 1, At, B1); PG8_BAR; PG8_SCHED;
;         }
	s_add_i32 s42, s79, s54
	v_lshl_add_u64 v[150:151], v[150:151], 0, s[22:23]
	s_mov_b32 m0, s42
	ds_read_b128 v[188:191], v154 offset:49152
	ds_read_b128 v[192:195], v154 offset:50176
	ds_read_b128 v[196:199], v154 offset:51200
	ds_read_b128 v[200:203], v154 offset:52224
	ds_read_b128 v[204:207], v154 offset:53248
	ds_read_b128 v[208:211], v154 offset:54272
	ds_read_b128 v[212:215], v154 offset:55296
	ds_read_b128 v[216:219], v154 offset:56320
	global_load_lds_dwordx4 v[150:151], off
	s_add_i32 m0, s42, 0x2000
	s_add_u32 s40, s40, 0xb0080
	v_lshl_add_u64 v[150:151], v[220:221], 0, s[22:23]
	s_addc_u32 s41, s41, 0
	s_add_i32 s42, s80, s54
	global_load_lds_dwordx4 v[150:151], off
	v_lshl_add_u64 v[150:151], s[40:41], 0, v[132:133]
	s_mov_b32 m0, s42
	s_nop 0
	global_load_lds_dwordx4 v[150:151], off
	v_lshl_add_u64 v[150:151], s[40:41], 0, v[136:137]
	s_add_i32 m0, s42, 0x2000
	s_nop 0
	global_load_lds_dwordx4 v[150:151], off
	v_lshl_add_u64 v[150:151], v[222:223], 0, s[22:23]
	s_mov_b32 m0, s69
	s_nop 0
	global_load_lds_dwordx4 v[150:151], off
	v_lshl_add_u64 v[150:151], v[224:225], 0, s[22:23]
	s_mov_b32 m0, s70
	s_nop 0
	global_load_lds_dwordx4 v[150:151], off
	s_waitcnt vmcnt(8)
	s_waitcnt lgkmcnt(0)
	s_barrier
	s_waitcnt lgkmcnt(0)
	v_mfma_f32_16x16x32_bf16 v[62:65], v[156:159], v[188:191], v[62:65]
	v_mfma_f32_16x16x32_bf16 v[58:61], v[164:167], v[188:191], v[58:61]
	v_mfma_f32_16x16x32_bf16 v[54:57], v[156:159], v[196:199], v[54:57]
	v_mfma_f32_16x16x32_bf16 v[50:53], v[164:167], v[196:199], v[50:53]
	v_mfma_f32_16x16x32_bf16 v[46:49], v[156:159], v[204:207], v[46:49]
	v_mfma_f32_16x16x32_bf16 v[42:45], v[164:167], v[204:207], v[42:45]
	v_mfma_f32_16x16x32_bf16 v[38:41], v[156:159], v[212:215], v[38:41]
	v_mfma_f32_16x16x32_bf16 v[34:37], v[164:167], v[212:215], v[34:37]
	v_mfma_f32_16x16x32_bf16 v[62:65], v[160:163], v[192:195], v[62:65]
	v_mfma_f32_16x16x32_bf16 v[58:61], v[168:171], v[192:195], v[58:61]
	v_mfma_f32_16x16x32_bf16 v[54:57], v[160:163], v[200:203], v[54:57]
	v_mfma_f32_16x16x32_bf16 v[50:53], v[168:171], v[200:203], v[50:53]
	v_mfma_f32_16x16x32_bf16 v[46:49], v[160:163], v[208:211], v[46:49]
	v_mfma_f32_16x16x32_bf16 v[42:45], v[168:171], v[208:211], v[42:45]
	v_mfma_f32_16x16x32_bf16 v[38:41], v[160:163], v[216:219], v[38:41]
	v_mfma_f32_16x16x32_bf16 v[34:37], v[168:171], v[216:219], v[34:37]
	v_mfma_f32_16x16x32_bf16 v[30:33], v[172:175], v[188:191], v[30:33]
	v_mfma_f32_16x16x32_bf16 v[26:29], v[180:183], v[188:191], v[26:29]
	v_mfma_f32_16x16x32_bf16 v[22:25], v[172:175], v[196:199], v[22:25]
	v_mfma_f32_16x16x32_bf16 v[18:21], v[180:183], v[196:199], v[18:21]
	v_mfma_f32_16x16x32_bf16 v[14:17], v[172:175], v[204:207], v[14:17]
	v_mfma_f32_16x16x32_bf16 v[10:13], v[180:183], v[204:207], v[10:13]
	v_mfma_f32_16x16x32_bf16 v[6:9], v[172:175], v[212:215], v[6:9]
	v_mfma_f32_16x16x32_bf16 v[2:5], v[180:183], v[212:215], v[2:5]
	v_mfma_f32_16x16x32_bf16 v[30:33], v[176:179], v[192:195], v[30:33]
	v_mfma_f32_16x16x32_bf16 v[26:29], v[184:187], v[192:195], v[26:29]
	v_mfma_f32_16x16x32_bf16 v[22:25], v[176:179], v[200:203], v[22:25]
	v_mfma_f32_16x16x32_bf16 v[18:21], v[184:187], v[200:203], v[18:21]
	v_mfma_f32_16x16x32_bf16 v[14:17], v[176:179], v[208:211], v[14:17]
	v_mfma_f32_16x16x32_bf16 v[10:13], v[184:187], v[208:211], v[10:13]
	v_mfma_f32_16x16x32_bf16 v[6:9], v[176:179], v[216:219], v[6:9]
	v_mfma_f32_16x16x32_bf16 v[2:5], v[184:187], v[216:219], v[2:5]
	s_barrier
	s_add_i32 s20, s20, 2
	s_add_u32 s38, s38, 0x100
	s_addc_u32 s39, s39, 0
	s_cmp_gt_u32 s20, 41
	s_cbranch_scc0 .LBB0_793
	s_and_b64 vcc, exec, s[26:27]
	s_cbranch_vccz .LBB0_796
	s_barrier

; __device__ __forceinline__ unsigned xb_add(unsigned* p, unsigned v) { return __hip_atomic_fetch_add(p, v, __ATOMIC_RELAXED, __HIP_MEMORY_SCOPE_AGENT); }
; __device__ __forceinline__ void xcd_barrier(const XcdBarrier& b) {
;     asm volatile("s_waitcnt vmcnt(0)" ::: "memory");
;     __syncthreads();
;     if (threadIdx.x == 0) {
;         unsigned* bar = b.bar;
;         __builtin_amdgcn_s_waitcnt(0);
;         unsigned nloc = b.st[0], nx = b.st[1];
;         if (nloc == 0u) { xcd_barrier_complete(bar, b.x, nloc, nx); b.st[0] = nloc; b.st[1] = nx; }
;         const unsigned old = xb_add(&bar[XB_XSUB(b.x)], 1u);
;         const unsigned gen = old / nloc;
;         if (old + 1u == (gen + 1u) * nloc) {
.LBB0_817:
	s_cmp_gt_i32 s35, 6
	s_cselect_b64 s[4:5], -1, 0
	s_and_b64 s[6:7], s[12:13], s[4:5]
	s_andn2_b64 vcc, exec, s[6:7]
	s_cbranch_vccnz .LBB0_867
	s_waitcnt vmcnt(0)
	v_cmp_eq_u32_e32 vcc, 0, v0
	s_waitcnt vmcnt(0) lgkmcnt(0)
	s_barrier
	v_readfirstlane_b32 s98, v0
	s_nop 3
	s_lshr_b32 s98, s98, 6
	s_cmp_lg_u32 s98, 1
	s_cbranch_scc1 .Lmy_noinv6
	buffer_inv sc1
	s_waitcnt vmcnt(0)
.Lmy_noinv6:
	s_and_saveexec_b64 s[6:7], vcc
	s_cbranch_execz .LBB0_866
	s_add_i32 s3, 0, 0x20000
	v_mov_b32_e32 v1, s3
	s_waitcnt vmcnt(0) expcnt(0) lgkmcnt(0)
	ds_read_b32 v3, v1
	s_add_i32 s3, 0, 0x20004
	v_mov_b32_e32 v1, s3
	ds_read_b32 v1, v1
	s_waitcnt lgkmcnt(1)
	v_cmp_ne_u32_e32 vcc, 0, v3
	s_cbranch_vccnz .LBB0_834
	s_load_dwordx2 s[12:13], s[0:1], 0xb8
	s_load_dword s3, s[0:1], 0xc0
	s_add_u32 s8, s30, 0xb4b8200
	s_addc_u32 s9, s31, 0
	s_add_u32 s10, s30, 0xb4b8400
	s_waitcnt lgkmcnt(0)
	s_mul_i32 s11, s13, s12
	s_mul_i32 s3, s11, s3
	s_addc_u32 s11, s31, 0
	s_add_u32 s12, s30, 0xb4b8500
	s_addc_u32 s13, s31, 0
	s_add_u32 s14, s30, 0xb4b8600
	s_addc_u32 s15, s31, 0
	s_add_u32 s18, s30, 0xb4b8700
	s_addc_u32 s19, s31, 0
	s_add_u32 s20, s30, 0xb4b8800
	s_addc_u32 s21, s31, 0
	s_add_u32 s22, s30, 0xb4b8900
	s_addc_u32 s23, s31, 0
	s_add_u32 s26, s30, 0xb4b8a00
	s_addc_u32 s27, s31, 0
	s_add_u32 s36, s30, 0xb4b8b00
	s_addc_u32 s37, s31, 0
	s_add_u32 s38, s30, 0xb4b8c00
	s_addc_u32 s39, s31, 0
	s_add_u32 s40, s30, 0xb4b8d00
	s_addc_u32 s41, s31, 0
	s_add_u32 s42, s30, 0xb4b8e00
	s_addc_u32 s43, s31, 0
	s_add_u32 s44, s30, 0xb4b8f00
	s_addc_u32 s45, s31, 0
	s_add_u32 s52, s30, 0xb4b9000
	s_addc_u32 s53, s31, 0
	s_add_u32 s54, s30, 0xb4b9100
	s_addc_u32 s55, s31, 0
	s_add_u32 s56, s30, 0xb4b9200
	s_addc_u32 s57, s31, 0
	s_add_u32 s58, s30, 0xb4b9300
	s_addc_u32 s59, s31, 0
	s_mov_b32 s74, 1
	v_mov_b32_e32 v17, 0
	s_branch .LBB0_822

; #define PG8_STAGEA(bufoff, gbase) PG8_STAGE_(bufoff, gbase, voffA)
; #define PG8_STAGEB(bufoff, gbase) PG8_STAGE_(bufoff, gbase, voffB)
; #define PG8_LDA(dst, b, h) do { _Pragma("unroll") for (int m = 0; m < 4; ++m) _Pragma("unroll") for (int k = 0; k < 2; ++k) dst[m][k] = *(const LAS bf16x8*)(lds + PG8_SA(b, h) + aoff + m * 2048 + k * 1024); } while (0)
; #define PG8_LDB(dst, b, h) do { _Pragma("unroll") for (int n = 0; n < 2; ++n) _Pragma("unroll") for (int k = 0; k < 2; ++k) dst[n][k] = *(const LAS bf16x8*)(lds + PG8_SB(b, h) + boff + n * 2048 + k * 1024); } while (0)
; #define PG8_MMA(ai, bj, At, Bt_) do { __builtin_amdgcn_s_setprio(1); _Pragma("unroll") for (int m = 0; m < 4; ++m) _Pragma("unroll") for (int n = 0; n < 2; ++n) _Pragma("unroll") for (int k = 0; k < 2; ++k) \
;         acc[ai][bj][m][n] = __builtin_amdgcn_mfma_f32_16x16x32_bf16(Bt_[n][k], At[m][k], acc[ai][bj][m][n], 0, 0, 0); __builtin_amdgcn_s_setprio(0); } while (0)
; #define PG8_WAIT_V(n) asm volatile("s_waitcnt vmcnt(" #n ")" ::: "memory")
; #define PG8_WAIT_L(n) asm volatile("s_waitcnt lgkmcnt(" #n ")" ::: "memory")
; #define PG8_BAR __builtin_amdgcn_s_barrier()
; template <int EK, int SK = -1>
; __device__ __forceinline__ void gemm_phase(LAS unsigned char* lds, const bf16_t* A, const bf16_t* Bt, int nM, int N, int K, const EpiArgs& E) {
;     ...
;         const bool has_next = S.next(ui + 1, nxt);
;         const char* nA = has_next ? (const char*)A + (size_t)nxt.pm * tstep : cA; const char* nB = has_next ? (const char*)Bt + (size_t)nxt.pn * tstep : cB;
;         for (int t = 0; t < nt; t += 2) {
;             const bool last = (t == nt - 2);
;             const char* a1 = cA + (size_t)(t + 1) * kstep;
;             const char* a2 = last ? nA : cA + (size_t)(t + 2) * kstep; const char* b2 = last ? nB : cB + (size_t)(t + 2) * kstep;
;             const char* a3 = a2 + kstep; const char* b3 = b2 + kstep;
;             PG8_LDB(B0, 0, 0); PG8_LDB(B1, 0, 1); PG8_SCHED; PG8_LDA(At, 0, 0); PG8_STAGEA(PG8_SA(1, 1), a1 + hstep);
;             PG8_WAIT_V(8); PG8_WAIT_L(0); PG8_BAR; PG8_MMA(0, 0, At, B0); PG8_MMA(0, 1, At, B1); PG8_BAR; PG8_SCHED;
;             PG8_LDA(At, 0, 1); PG8_STAGEB(PG8_SB(0, 0), b2); PG8_STAGEB(PG8_SB(0, 1), b2 + hstep); PG8_STAGEA(PG8_SA(0, 0), a2);
;             PG8_WAIT_V(8); PG8_WAIT_L(0); PG8_BAR; PG8_MMA(1, 0, At, B0); PG8_MMA(1, 1, At, B1); PG8_BAR; PG8_SCHED;
.LBB0_929:
	v_add_u32_e32 v158, s82, v160
	ds_read_b128 v[150:153], v158
	ds_read_b128 v[154:157], v158 offset:1024
	ds_read_b128 v[166:169], v158 offset:2048
	ds_read_b128 v[170:173], v158 offset:3072
	v_add_u32_e32 v158, s83, v160
	s_add_u32 s76, s36, s10
	ds_read_b128 v[174:177], v158
	ds_read_b128 v[178:181], v158 offset:1024
	ds_read_b128 v[182:185], v158 offset:2048
	ds_read_b128 v[186:189], v158 offset:3072
	s_addc_u32 s77, s37, s11
	s_add_u32 s76, s76, 0x100
	s_addc_u32 s77, s77, 0
	s_add_u32 s90, s86, s10
	s_addc_u32 s91, s87, s11
	s_cmpk_eq_i32 s10, 0x700
	s_cselect_b32 s79, s14, s77
	s_cselect_b32 s78, s71, s76
	s_cselect_b32 s77, s69, s91
	s_cselect_b32 s76, s88, s90
	v_lshl_add_u64 v[158:159], v[146:147], 0, s[10:11]
	s_add_i32 m0, s23, 0xc000
	ds_read_b128 v[190:193], v163
	ds_read_b128 v[194:197], v163 offset:1024
	ds_read_b128 v[198:201], v163 offset:2048
	ds_read_b128 v[202:205], v163 offset:3072
	ds_read_b128 v[206:209], v163 offset:4096
	ds_read_b128 v[210:213], v163 offset:5120
	ds_read_b128 v[214:217], v163 offset:6144
	ds_read_b128 v[218:221], v163 offset:7168
	global_load_lds_dwordx4 v[158:159], off
	v_lshl_add_u64 v[158:159], v[148:149], 0, s[10:11]
	s_add_i32 m0, s23, 0xe000
	s_nop 0
	global_load_lds_dwordx4 v[158:159], off
	s_waitcnt vmcnt(8)
	s_waitcnt lgkmcnt(0)
	s_barrier
	s_waitcnt lgkmcnt(0)
	v_mfma_f32_16x16x32_bf16 v[110:113], v[150:153], v[190:193], v[110:113]
	v_mfma_f32_16x16x32_bf16 v[106:109], v[166:169], v[190:193], v[106:109]
	v_mfma_f32_16x16x32_bf16 v[102:105], v[150:153], v[198:201], v[102:105]
	v_mfma_f32_16x16x32_bf16 v[98:101], v[166:169], v[198:201], v[98:101]
	v_mfma_f32_16x16x32_bf16 v[94:97], v[150:153], v[206:209], v[94:97]
	v_mfma_f32_16x16x32_bf16 v[90:93], v[166:169], v[206:209], v[90:93]
	v_mfma_f32_16x16x32_bf16 v[86:89], v[150:153], v[214:217], v[86:89]
	v_mfma_f32_16x16x32_bf16 v[82:85], v[166:169], v[214:217], v[82:85]
	v_mfma_f32_16x16x32_bf16 v[110:113], v[154:157], v[194:197], v[110:113]
	v_mfma_f32_16x16x32_bf16 v[106:109], v[170:173], v[194:197], v[106:109]
	v_mfma_f32_16x16x32_bf16 v[102:105], v[154:157], v[202:205], v[102:105]
	v_mfma_f32_16x16x32_bf16 v[98:101], v[170:173], v[202:205], v[98:101]
	v_mfma_f32_16x16x32_bf16 v[94:97], v[154:157], v[210:213], v[94:97]
	v_mfma_f32_16x16x32_bf16 v[90:93], v[170:173], v[210:213], v[90:93]
	v_mfma_f32_16x16x32_bf16 v[86:89], v[154:157], v[218:221], v[86:89]
	v_mfma_f32_16x16x32_bf16 v[82:85], v[170:173], v[218:221], v[82:85]
	v_mfma_f32_16x16x32_bf16 v[78:81], v[174:177], v[190:193], v[78:81]
	v_mfma_f32_16x16x32_bf16 v[74:77], v[182:185], v[190:193], v[74:77]
	v_mfma_f32_16x16x32_bf16 v[70:73], v[174:177], v[198:201], v[70:73]
	v_mfma_f32_16x16x32_bf16 v[66:69], v[182:185], v[198:201], v[66:69]
	v_mfma_f32_16x16x32_bf16 v[62:65], v[174:177], v[206:209], v[62:65]
	v_mfma_f32_16x16x32_bf16 v[58:61], v[182:185], v[206:209], v[58:61]
	v_mfma_f32_16x16x32_bf16 v[54:57], v[174:177], v[214:217], v[54:57]
	v_mfma_f32_16x16x32_bf16 v[50:53], v[182:185], v[214:217], v[50:53]
	v_mfma_f32_16x16x32_bf16 v[78:81], v[178:181], v[194:197], v[78:81]
	v_mfma_f32_16x16x32_bf16 v[74:77], v[186:189], v[194:197], v[74:77]
	v_mfma_f32_16x16x32_bf16 v[70:73], v[178:181], v[202:205], v[70:73]
	v_mfma_f32_16x16x32_bf16 v[66:69], v[186:189], v[202:205], v[66:69]
	v_mfma_f32_16x16x32_bf16 v[62:65], v[178:181], v[210:213], v[62:65]
	v_mfma_f32_16x16x32_bf16 v[58:61], v[186:189], v[210:213], v[58:61]
	v_mfma_f32_16x16x32_bf16 v[54:57], v[178:181], v[218:221], v[54:57]
	v_mfma_f32_16x16x32_bf16 v[50:53], v[186:189], v[218:221], v[50:53]
	s_barrier
	s_add_i32 s90, s82, s53
	v_lshl_add_u64 v[158:159], s[76:77], 0, v[132:133]
	s_mov_b32 m0, s90
	ds_read_b128 v[190:193], v163 offset:16384
	ds_read_b128 v[194:197], v163 offset:17408
	ds_read_b128 v[198:201], v163 offset:18432
	ds_read_b128 v[202:205], v163 offset:19456
	ds_read_b128 v[206:209], v163 offset:20480
	ds_read_b128 v[210:213], v163 offset:21504
	ds_read_b128 v[214:217], v163 offset:22528
	ds_read_b128 v[218:221], v163 offset:23552
	global_load_lds_dwordx4 v[158:159], off
	s_add_i32 m0, s90, 0x2000
	s_add_u32 s90, s76, 0x40000
	v_lshl_add_u64 v[222:223], s[76:77], 0, v[136:137]
	s_addc_u32 s91, s77, 0
	s_add_i32 s92, s83, s53
	global_load_lds_dwordx4 v[222:223], off
	v_lshl_add_u64 v[224:225], s[90:91], 0, v[132:133]
	s_mov_b32 m0, s92
	v_lshl_add_u64 v[226:227], s[78:79], 0, v[134:135]
	global_load_lds_dwordx4 v[224:225], off
	v_lshl_add_u64 v[224:225], s[90:91], 0, v[136:137]
	s_add_i32 m0, s92, 0x2000
	s_nop 0
	global_load_lds_dwordx4 v[224:225], off
	v_lshl_add_u64 v[224:225], s[78:79], 0, v[130:131]
	s_mov_b32 m0, s23
	s_nop 0
	global_load_lds_dwordx4 v[224:225], off
	s_mov_b32 m0, s27
	s_nop 0
	global_load_lds_dwordx4 v[226:227], off
	s_waitcnt vmcnt(8)
	s_waitcnt lgkmcnt(0)
	s_barrier
; #define PG8_STAGEA(bufoff, gbase) PG8_STAGE_(bufoff, gbase, voffA)
; #define PG8_LDA(dst, b, h) do { _Pragma("unroll") for (int m = 0; m < 4; ++m) _Pragma("unroll") for (int k = 0; k < 2; ++k) dst[m][k] = *(const LAS bf16x8*)(lds + PG8_SA(b, h) + aoff + m * 2048 + k * 1024); } while (0)
; #define PG8_LDB(dst, b, h) do { _Pragma("unroll") for (int n = 0; n < 2; ++n) _Pragma("unroll") for (int k = 0; k < 2; ++k) dst[n][k] = *(const LAS bf16x8*)(lds + PG8_SB(b, h) + boff + n * 2048 + k * 1024); } while (0)
; #define PG8_MMA(ai, bj, At, Bt_) do { __builtin_amdgcn_s_setprio(1); _Pragma("unroll") for (int m = 0; m < 4; ++m) _Pragma("unroll") for (int n = 0; n < 2; ++n) _Pragma("unroll") for (int k = 0; k < 2; ++k) \
;         acc[ai][bj][m][n] = __builtin_amdgcn_mfma_f32_16x16x32_bf16(Bt_[n][k], At[m][k], acc[ai][bj][m][n], 0, 0, 0); __builtin_amdgcn_s_setprio(0); } while (0)
; #define PG8_WAIT_V(n) asm volatile("s_waitcnt vmcnt(" #n ")" ::: "memory")
; #define PG8_WAIT_L(n) asm volatile("s_waitcnt lgkmcnt(" #n ")" ::: "memory")
; #define PG8_BAR __builtin_amdgcn_s_barrier()
; #define PG8_SCHED __builtin_amdgcn_sched_barrier(0)
; template <int EK, int SK = -1>
; __device__ __forceinline__ void gemm_phase(LAS unsigned char* lds, const bf16_t* A, const bf16_t* Bt, int nM, int N, int K, const EpiArgs& E) {
;     ...
;             PG8_WAIT_V(8); PG8_WAIT_L(0); PG8_BAR; PG8_MMA(1, 0, At, B0); PG8_MMA(1, 1, At, B1); PG8_BAR; PG8_SCHED;
;             PG8_LDB(B0, 1, 0); PG8_LDB(B1, 1, 1); PG8_SCHED; PG8_LDA(At, 1, 0); PG8_STAGEA(PG8_SA(0, 1), a2 + hstep);
;             PG8_WAIT_V(8); PG8_WAIT_L(0); PG8_BAR; PG8_MMA(0, 0, At, B0); PG8_MMA(0, 1, At, B1); PG8_BAR; PG8_SCHED;
	s_waitcnt lgkmcnt(0)
	v_mfma_f32_16x16x32_bf16 v[46:49], v[150:153], v[190:193], v[46:49]
	v_mfma_f32_16x16x32_bf16 v[42:45], v[166:169], v[190:193], v[42:45]
	v_mfma_f32_16x16x32_bf16 v[38:41], v[150:153], v[198:201], v[38:41]
	v_mfma_f32_16x16x32_bf16 v[34:37], v[166:169], v[198:201], v[34:37]
	v_mfma_f32_16x16x32_bf16 v[30:33], v[150:153], v[206:209], v[30:33]
	v_mfma_f32_16x16x32_bf16 v[26:29], v[166:169], v[206:209], v[26:29]
	v_mfma_f32_16x16x32_bf16 v[22:25], v[150:153], v[214:217], v[22:25]
	v_mfma_f32_16x16x32_bf16 v[18:21], v[166:169], v[214:217], v[18:21]
	v_mfma_f32_16x16x32_bf16 v[46:49], v[154:157], v[194:197], v[46:49]
	v_mfma_f32_16x16x32_bf16 v[42:45], v[170:173], v[194:197], v[42:45]
	v_mfma_f32_16x16x32_bf16 v[38:41], v[154:157], v[202:205], v[38:41]
	v_mfma_f32_16x16x32_bf16 v[34:37], v[170:173], v[202:205], v[34:37]
	v_mfma_f32_16x16x32_bf16 v[30:33], v[154:157], v[210:213], v[30:33]
	v_mfma_f32_16x16x32_bf16 v[26:29], v[170:173], v[210:213], v[26:29]
	v_mfma_f32_16x16x32_bf16 v[22:25], v[154:157], v[218:221], v[22:25]
	v_mfma_f32_16x16x32_bf16 v[18:21], v[170:173], v[218:221], v[18:21]
	v_mfma_f32_16x16x32_bf16 v[14:17], v[174:177], v[190:193], v[14:17]
	v_mfma_f32_16x16x32_bf16 v[10:13], v[182:185], v[190:193], v[10:13]
	v_mfma_f32_16x16x32_bf16 v[6:9], v[174:177], v[198:201], v[6:9]
	v_mfma_f32_16x16x32_bf16 v[2:5], v[182:185], v[198:201], v[2:5]
	v_mfma_f32_16x16x32_bf16 v[114:117], v[174:177], v[206:209], v[114:117]
	v_mfma_f32_16x16x32_bf16 v[118:121], v[182:185], v[206:209], v[118:121]
	v_mfma_f32_16x16x32_bf16 v[122:125], v[174:177], v[214:217], v[122:125]
	v_mfma_f32_16x16x32_bf16 v[126:129], v[182:185], v[214:217], v[126:129]
	v_mfma_f32_16x16x32_bf16 v[14:17], v[178:181], v[194:197], v[14:17]
	v_mfma_f32_16x16x32_bf16 v[10:13], v[186:189], v[194:197], v[10:13]
	v_mfma_f32_16x16x32_bf16 v[6:9], v[178:181], v[202:205], v[6:9]
	v_mfma_f32_16x16x32_bf16 v[2:5], v[186:189], v[202:205], v[2:5]
	v_mfma_f32_16x16x32_bf16 v[114:117], v[178:181], v[210:213], v[114:117]
	v_mfma_f32_16x16x32_bf16 v[118:121], v[186:189], v[210:213], v[118:121]
	v_mfma_f32_16x16x32_bf16 v[122:125], v[178:181], v[218:221], v[122:125]
	v_mfma_f32_16x16x32_bf16 v[126:129], v[186:189], v[218:221], v[126:129]
	s_barrier
	s_add_i32 s90, 0, 0x18000
	v_add_u32_e32 v165, s90, v160
	s_add_i32 s91, 0, 0x1c000
	ds_read_b128 v[150:153], v165
	ds_read_b128 v[154:157], v165 offset:1024
	ds_read_b128 v[166:169], v165 offset:2048
	ds_read_b128 v[170:173], v165 offset:3072
	v_add_u32_e32 v165, s91, v160
	ds_read_b128 v[174:177], v165
	ds_read_b128 v[178:181], v165 offset:1024
	ds_read_b128 v[182:185], v165 offset:2048
	ds_read_b128 v[186:189], v165 offset:3072
	s_add_u32 s78, s78, 0x40000
	s_addc_u32 s79, s79, 0
	s_mov_b32 m0, s55
	v_lshl_add_u64 v[228:229], s[78:79], 0, v[130:131]
	ds_read_b128 v[190:193], v163 offset:32768
	ds_read_b128 v[194:197], v163 offset:33792
	ds_read_b128 v[198:201], v163 offset:34816
	ds_read_b128 v[202:205], v163 offset:35840
	ds_read_b128 v[206:209], v163 offset:36864
	ds_read_b128 v[210:213], v163 offset:37888
	ds_read_b128 v[214:217], v163 offset:38912
	ds_read_b128 v[218:221], v163 offset:39936
	global_load_lds_dwordx4 v[228:229], off
	v_lshl_add_u64 v[228:229], s[78:79], 0, v[134:135]
	s_mov_b32 m0, s57
	s_nop 0
	global_load_lds_dwordx4 v[228:229], off
	s_waitcnt vmcnt(8)
	s_waitcnt lgkmcnt(0)
	s_barrier
	s_waitcnt lgkmcnt(0)
	v_mfma_f32_16x16x32_bf16 v[110:113], v[150:153], v[190:193], v[110:113]
	v_mfma_f32_16x16x32_bf16 v[106:109], v[166:169], v[190:193], v[106:109]
	v_mfma_f32_16x16x32_bf16 v[102:105], v[150:153], v[198:201], v[102:105]
	v_mfma_f32_16x16x32_bf16 v[98:101], v[166:169], v[198:201], v[98:101]
	v_mfma_f32_16x16x32_bf16 v[94:97], v[150:153], v[206:209], v[94:97]
	v_mfma_f32_16x16x32_bf16 v[90:93], v[166:169], v[206:209], v[90:93]
	v_mfma_f32_16x16x32_bf16 v[86:89], v[150:153], v[214:217], v[86:89]
	v_mfma_f32_16x16x32_bf16 v[82:85], v[166:169], v[214:217], v[82:85]
	v_mfma_f32_16x16x32_bf16 v[110:113], v[154:157], v[194:197], v[110:113]
	v_mfma_f32_16x16x32_bf16 v[106:109], v[170:173], v[194:197], v[106:109]
	v_mfma_f32_16x16x32_bf16 v[102:105], v[154:157], v[202:205], v[102:105]
	v_mfma_f32_16x16x32_bf16 v[98:101], v[170:173], v[202:205], v[98:101]
	v_mfma_f32_16x16x32_bf16 v[94:97], v[154:157], v[210:213], v[94:97]
	v_mfma_f32_16x16x32_bf16 v[90:93], v[170:173], v[210:213], v[90:93]
	v_mfma_f32_16x16x32_bf16 v[86:89], v[154:157], v[218:221], v[86:89]
	v_mfma_f32_16x16x32_bf16 v[82:85], v[170:173], v[218:221], v[82:85]
	v_mfma_f32_16x16x32_bf16 v[78:81], v[174:177], v[190:193], v[78:81]
	v_mfma_f32_16x16x32_bf16 v[74:77], v[182:185], v[190:193], v[74:77]
	v_mfma_f32_16x16x32_bf16 v[70:73], v[174:177], v[198:201], v[70:73]
	v_mfma_f32_16x16x32_bf16 v[66:69], v[182:185], v[198:201], v[66:69]
	v_mfma_f32_16x16x32_bf16 v[62:65], v[174:177], v[206:209], v[62:65]
	v_mfma_f32_16x16x32_bf16 v[58:61], v[182:185], v[206:209], v[58:61]
	v_mfma_f32_16x16x32_bf16 v[54:57], v[174:177], v[214:217], v[54:57]
	v_mfma_f32_16x16x32_bf16 v[50:53], v[182:185], v[214:217], v[50:53]
	v_mfma_f32_16x16x32_bf16 v[78:81], v[178:181], v[194:197], v[78:81]
	v_mfma_f32_16x16x32_bf16 v[74:77], v[186:189], v[194:197], v[74:77]
	v_mfma_f32_16x16x32_bf16 v[70:73], v[178:181], v[202:205], v[70:73]
	v_mfma_f32_16x16x32_bf16 v[66:69], v[186:189], v[202:205], v[66:69]
	v_mfma_f32_16x16x32_bf16 v[62:65], v[178:181], v[210:213], v[62:65]
	v_mfma_f32_16x16x32_bf16 v[58:61], v[186:189], v[210:213], v[58:61]
	v_mfma_f32_16x16x32_bf16 v[54:57], v[178:181], v[218:221], v[54:57]
	v_mfma_f32_16x16x32_bf16 v[50:53], v[186:189], v[218:221], v[50:53]
	s_barrier
; #define PG8_STAGEA(bufoff, gbase) PG8_STAGE_(bufoff, gbase, voffA)
; #define PG8_STAGEB(bufoff, gbase) PG8_STAGE_(bufoff, gbase, voffB)
; #define PG8_LDA(dst, b, h) do { _Pragma("unroll") for (int m = 0; m < 4; ++m) _Pragma("unroll") for (int k = 0; k < 2; ++k) dst[m][k] = *(const LAS bf16x8*)(lds + PG8_SA(b, h) + aoff + m * 2048 + k * 1024); } while (0)
; #define PG8_MMA(ai, bj, At, Bt_) do { __builtin_amdgcn_s_setprio(1); _Pragma("unroll") for (int m = 0; m < 4; ++m) _Pragma("unroll") for (int n = 0; n < 2; ++n) _Pragma("unroll") for (int k = 0; k < 2; ++k) \
;         acc[ai][bj][m][n] = __builtin_amdgcn_mfma_f32_16x16x32_bf16(Bt_[n][k], At[m][k], acc[ai][bj][m][n], 0, 0, 0); __builtin_amdgcn_s_setprio(0); } while (0)
; #define PG8_WAIT_V(n) asm volatile("s_waitcnt vmcnt(" #n ")" ::: "memory")
; #define PG8_WAIT_L(n) asm volatile("s_waitcnt lgkmcnt(" #n ")" ::: "memory")
; #define PG8_BAR __builtin_amdgcn_s_barrier()
; #define PG8_SCHED __builtin_amdgcn_sched_barrier(0)
; template <int EK, int SK = -1>
; __device__ __forceinline__ void gemm_phase(LAS unsigned char* lds, const bf16_t* A, const bf16_t* Bt, int nM, int N, int K, const EpiArgs& E) {
;     ...
;             PG8_LDA(At, 1, 1); PG8_STAGEB(PG8_SB(1, 0), b3); PG8_STAGEB(PG8_SB(1, 1), b3 + hstep); PG8_STAGEA(PG8_SA(1, 0), a3);
;             PG8_WAIT_V(8); PG8_WAIT_L(0); PG8_BAR; PG8_MMA(1, 0, At, B0); PG8_MMA(1, 1, At, B1); PG8_BAR; PG8_SCHED;
;         }
	s_add_i32 s78, s90, s53
	v_lshl_add_u64 v[158:159], v[158:159], 0, s[16:17]
	s_mov_b32 m0, s78
	ds_read_b128 v[190:193], v163 offset:49152
	ds_read_b128 v[194:197], v163 offset:50176
	ds_read_b128 v[198:201], v163 offset:51200
	ds_read_b128 v[202:205], v163 offset:52224
	ds_read_b128 v[206:209], v163 offset:53248
	ds_read_b128 v[210:213], v163 offset:54272
	ds_read_b128 v[214:217], v163 offset:55296
	ds_read_b128 v[218:221], v163 offset:56320
	global_load_lds_dwordx4 v[158:159], off
	s_add_i32 m0, s78, 0x2000
	s_add_u32 s76, s76, 0x40080
	v_lshl_add_u64 v[158:159], v[222:223], 0, s[16:17]
	s_addc_u32 s77, s77, 0
	s_add_i32 s78, s91, s53
	global_load_lds_dwordx4 v[158:159], off
	v_lshl_add_u64 v[158:159], s[76:77], 0, v[132:133]
	s_mov_b32 m0, s78
	s_nop 0
	global_load_lds_dwordx4 v[158:159], off
	v_lshl_add_u64 v[158:159], s[76:77], 0, v[136:137]
	s_add_i32 m0, s78, 0x2000
	s_nop 0
	global_load_lds_dwordx4 v[158:159], off
	v_lshl_add_u64 v[158:159], v[224:225], 0, s[16:17]
	s_mov_b32 m0, s80
	s_nop 0
	global_load_lds_dwordx4 v[158:159], off
	v_lshl_add_u64 v[158:159], v[226:227], 0, s[16:17]
	s_mov_b32 m0, s81
	s_nop 0
	global_load_lds_dwordx4 v[158:159], off
	s_waitcnt vmcnt(8)
	s_waitcnt lgkmcnt(0)
	s_barrier
	s_waitcnt lgkmcnt(0)
	v_mfma_f32_16x16x32_bf16 v[46:49], v[150:153], v[190:193], v[46:49]
	v_mfma_f32_16x16x32_bf16 v[42:45], v[166:169], v[190:193], v[42:45]
	v_mfma_f32_16x16x32_bf16 v[38:41], v[150:153], v[198:201], v[38:41]
	v_mfma_f32_16x16x32_bf16 v[34:37], v[166:169], v[198:201], v[34:37]
	v_mfma_f32_16x16x32_bf16 v[30:33], v[150:153], v[206:209], v[30:33]
	v_mfma_f32_16x16x32_bf16 v[26:29], v[166:169], v[206:209], v[26:29]
	v_mfma_f32_16x16x32_bf16 v[22:25], v[150:153], v[214:217], v[22:25]
	v_mfma_f32_16x16x32_bf16 v[18:21], v[166:169], v[214:217], v[18:21]
	v_mfma_f32_16x16x32_bf16 v[46:49], v[154:157], v[194:197], v[46:49]
	v_mfma_f32_16x16x32_bf16 v[42:45], v[170:173], v[194:197], v[42:45]
	v_mfma_f32_16x16x32_bf16 v[38:41], v[154:157], v[202:205], v[38:41]
	v_mfma_f32_16x16x32_bf16 v[34:37], v[170:173], v[202:205], v[34:37]
	v_mfma_f32_16x16x32_bf16 v[30:33], v[154:157], v[210:213], v[30:33]
	v_mfma_f32_16x16x32_bf16 v[26:29], v[170:173], v[210:213], v[26:29]
	v_mfma_f32_16x16x32_bf16 v[22:25], v[154:157], v[218:221], v[22:25]
	v_mfma_f32_16x16x32_bf16 v[18:21], v[170:173], v[218:221], v[18:21]
	v_mfma_f32_16x16x32_bf16 v[14:17], v[174:177], v[190:193], v[14:17]
	v_mfma_f32_16x16x32_bf16 v[10:13], v[182:185], v[190:193], v[10:13]
	v_mfma_f32_16x16x32_bf16 v[6:9], v[174:177], v[198:201], v[6:9]
	v_mfma_f32_16x16x32_bf16 v[2:5], v[182:185], v[198:201], v[2:5]
	v_mfma_f32_16x16x32_bf16 v[114:117], v[174:177], v[206:209], v[114:117]
	v_mfma_f32_16x16x32_bf16 v[118:121], v[182:185], v[206:209], v[118:121]
	v_mfma_f32_16x16x32_bf16 v[122:125], v[174:177], v[214:217], v[122:125]
	v_mfma_f32_16x16x32_bf16 v[126:129], v[182:185], v[214:217], v[126:129]
	v_mfma_f32_16x16x32_bf16 v[14:17], v[178:181], v[194:197], v[14:17]
	v_mfma_f32_16x16x32_bf16 v[10:13], v[186:189], v[194:197], v[10:13]
	v_mfma_f32_16x16x32_bf16 v[6:9], v[178:181], v[202:205], v[6:9]
	v_mfma_f32_16x16x32_bf16 v[2:5], v[186:189], v[202:205], v[2:5]
	v_mfma_f32_16x16x32_bf16 v[114:117], v[178:181], v[210:213], v[114:117]
	v_mfma_f32_16x16x32_bf16 v[118:121], v[186:189], v[210:213], v[118:121]
	v_mfma_f32_16x16x32_bf16 v[122:125], v[178:181], v[218:221], v[122:125]
	v_mfma_f32_16x16x32_bf16 v[126:129], v[186:189], v[218:221], v[126:129]
	s_barrier
	s_add_i32 s89, s89, 2
	s_add_u32 s10, s10, 0x100
	s_addc_u32 s11, s11, 0
	s_cmp_gt_u32 s89, 13
	s_cbranch_scc0 .LBB0_929
	s_and_b64 vcc, exec, s[38:39]
	s_cbranch_vccz .LBB0_932
	s_barrier

; __device__ __forceinline__ unsigned xb_add(unsigned* p, unsigned v) { return __hip_atomic_fetch_add(p, v, __ATOMIC_RELAXED, __HIP_MEMORY_SCOPE_AGENT); }
; __device__ __forceinline__ void xcd_barrier(const XcdBarrier& b) {
;     asm volatile("s_waitcnt vmcnt(0)" ::: "memory");
;     __syncthreads();
;     if (threadIdx.x == 0) {
;         unsigned* bar = b.bar;
;         __builtin_amdgcn_s_waitcnt(0);
;         unsigned nloc = b.st[0], nx = b.st[1];
;         if (nloc == 0u) { xcd_barrier_complete(bar, b.x, nloc, nx); b.st[0] = nloc; b.st[1] = nx; }
;         const unsigned old = xb_add(&bar[XB_XSUB(b.x)], 1u);
;         const unsigned gen = old / nloc;
;         if (old + 1u == (gen + 1u) * nloc) {
.LBB0_969:
	s_cmp_gt_i32 s35, 7
	s_cselect_b64 s[4:5], -1, 0
	s_and_b64 s[6:7], s[20:21], s[4:5]
	s_andn2_b64 vcc, exec, s[6:7]
	s_cbranch_vccnz .LBB0_1019
	s_waitcnt vmcnt(0)
	v_cmp_eq_u32_e32 vcc, 0, v0
	s_waitcnt vmcnt(0) lgkmcnt(0)
	s_barrier
	v_readfirstlane_b32 s98, v0
	s_nop 3
	s_lshr_b32 s98, s98, 6
	s_cmp_lg_u32 s98, 1
	s_cbranch_scc1 .Lmy_noinv7
	buffer_inv sc1
	s_waitcnt vmcnt(0)
.Lmy_noinv7:
	s_and_saveexec_b64 s[6:7], vcc
	s_cbranch_execz .LBB0_1018
	s_add_i32 s3, 0, 0x20000
	v_mov_b32_e32 v1, s3
	s_waitcnt vmcnt(0) expcnt(0) lgkmcnt(0)
	ds_read_b32 v3, v1
	s_add_i32 s3, 0, 0x20004
	v_mov_b32_e32 v1, s3
	ds_read_b32 v1, v1
	s_waitcnt lgkmcnt(1)
	v_cmp_ne_u32_e32 vcc, 0, v3
	s_cbranch_vccnz .LBB0_986
	s_load_dwordx2 s[12:13], s[0:1], 0xb8
	s_load_dword s3, s[0:1], 0xc0
	s_add_u32 s8, s30, 0xb4b8200
	s_addc_u32 s9, s31, 0
	s_add_u32 s10, s30, 0xb4b8400
	s_waitcnt lgkmcnt(0)
	s_mul_i32 s11, s13, s12
	s_mul_i32 s3, s11, s3
	s_addc_u32 s11, s31, 0
	s_add_u32 s12, s30, 0xb4b8500
	s_addc_u32 s13, s31, 0
	s_add_u32 s14, s30, 0xb4b8600
	s_addc_u32 s15, s31, 0
	s_add_u32 s16, s30, 0xb4b8700
	s_addc_u32 s17, s31, 0
	s_add_u32 s20, s30, 0xb4b8800
	s_addc_u32 s21, s31, 0
	s_add_u32 s22, s30, 0xb4b8900
	s_addc_u32 s23, s31, 0
	s_add_u32 s26, s30, 0xb4b8a00
	s_addc_u32 s27, s31, 0
	s_add_u32 s36, s30, 0xb4b8b00
	s_addc_u32 s37, s31, 0
	s_add_u32 s38, s30, 0xb4b8c00
	s_addc_u32 s39, s31, 0
	s_add_u32 s40, s30, 0xb4b8d00
	s_addc_u32 s41, s31, 0
	s_add_u32 s42, s30, 0xb4b8e00
	s_addc_u32 s43, s31, 0
	s_add_u32 s44, s30, 0xb4b8f00
	s_addc_u32 s45, s31, 0
	s_add_u32 s52, s30, 0xb4b9000
	s_addc_u32 s53, s31, 0
	s_add_u32 s54, s30, 0xb4b9100
	s_addc_u32 s55, s31, 0
	s_add_u32 s56, s30, 0xb4b9200
	s_addc_u32 s57, s31, 0
	s_add_u32 s58, s30, 0xb4b9300
	s_addc_u32 s59, s31, 0
	s_mov_b32 s74, 1
	v_mov_b32_e32 v17, 0
	s_branch .LBB0_974

; __device__ __forceinline__ unsigned xb_add(unsigned* p, unsigned v) { return __hip_atomic_fetch_add(p, v, __ATOMIC_RELAXED, __HIP_MEMORY_SCOPE_AGENT); }
; __device__ __forceinline__ void xcd_barrier(const XcdBarrier& b) {
;     asm volatile("s_waitcnt vmcnt(0)" ::: "memory");
;     __syncthreads();
;     if (threadIdx.x == 0) {
;         unsigned* bar = b.bar;
;         __builtin_amdgcn_s_waitcnt(0);
;         unsigned nloc = b.st[0], nx = b.st[1];
;         if (nloc == 0u) { xcd_barrier_complete(bar, b.x, nloc, nx); b.st[0] = nloc; b.st[1] = nx; }
;         const unsigned old = xb_add(&bar[XB_XSUB(b.x)], 1u);
;         const unsigned gen = old / nloc;
;         if (old + 1u == (gen + 1u) * nloc) {
.LBB0_1040:
	s_cmp_gt_i32 s35, 8
	s_cselect_b64 s[4:5], -1, 0
	s_and_b64 s[6:7], s[6:7], s[4:5]
	s_andn2_b64 vcc, exec, s[6:7]
	s_cbranch_vccnz .LBB0_1090
	s_waitcnt vmcnt(0)
	v_cmp_eq_u32_e32 vcc, 0, v0
	s_waitcnt vmcnt(0) lgkmcnt(0)
	s_barrier
	v_readfirstlane_b32 s98, v0
	s_nop 3
	s_lshr_b32 s98, s98, 6
	s_cmp_lg_u32 s98, 1
	s_cbranch_scc1 .Lmy_noinv8
	buffer_inv sc1
	s_waitcnt vmcnt(0)
.Lmy_noinv8:
	s_and_saveexec_b64 s[6:7], vcc
	s_cbranch_execz .LBB0_1089
	s_add_i32 s3, 0, 0x20000
	v_mov_b32_e32 v1, s3
	s_waitcnt vmcnt(0) expcnt(0) lgkmcnt(0)
	ds_read_b32 v3, v1
	s_add_i32 s3, 0, 0x20004
	v_mov_b32_e32 v1, s3
	ds_read_b32 v1, v1
	s_waitcnt lgkmcnt(1)
	v_cmp_ne_u32_e32 vcc, 0, v3
	s_cbranch_vccnz .LBB0_1057
	s_load_dwordx2 s[12:13], s[0:1], 0xb8
	s_load_dword s3, s[0:1], 0xc0
	s_add_u32 s8, s30, 0xb4b8200
	s_addc_u32 s9, s31, 0
	s_add_u32 s10, s30, 0xb4b8400
	s_waitcnt lgkmcnt(0)
	s_mul_i32 s11, s13, s12
	s_mul_i32 s3, s11, s3
	s_addc_u32 s11, s31, 0
	s_add_u32 s12, s30, 0xb4b8500
	s_addc_u32 s13, s31, 0
	s_add_u32 s14, s30, 0xb4b8600
	s_addc_u32 s15, s31, 0
	s_add_u32 s16, s30, 0xb4b8700
	s_addc_u32 s17, s31, 0
	s_add_u32 s18, s30, 0xb4b8800
	s_addc_u32 s19, s31, 0
	s_add_u32 s20, s30, 0xb4b8900
	s_addc_u32 s21, s31, 0
	s_add_u32 s22, s30, 0xb4b8a00
	s_addc_u32 s23, s31, 0
	s_add_u32 s26, s30, 0xb4b8b00
	s_addc_u32 s27, s31, 0
	s_add_u32 s36, s30, 0xb4b8c00
	s_addc_u32 s37, s31, 0
	s_add_u32 s38, s30, 0xb4b8d00
	s_addc_u32 s39, s31, 0
	s_add_u32 s40, s30, 0xb4b8e00
	s_addc_u32 s41, s31, 0
	s_add_u32 s42, s30, 0xb4b8f00
	s_addc_u32 s43, s31, 0
	s_add_u32 s44, s30, 0xb4b9000
	s_addc_u32 s45, s31, 0
	s_add_u32 s46, s30, 0xb4b9100
	s_addc_u32 s47, s31, 0
	s_add_u32 s48, s30, 0xb4b9200
	s_addc_u32 s49, s31, 0
	s_add_u32 s50, s30, 0xb4b9300
	s_addc_u32 s51, s31, 0
	s_mov_b32 s58, 1
	v_mov_b32_e32 v17, 0
	s_branch .LBB0_1045

; #define PG8_STAGEA(bufoff, gbase) PG8_STAGE_(bufoff, gbase, voffA)
; #define PG8_STAGEB(bufoff, gbase) PG8_STAGE_(bufoff, gbase, voffB)
; #define PG8_LDA(dst, b, h) do { _Pragma("unroll") for (int m = 0; m < 4; ++m) _Pragma("unroll") for (int k = 0; k < 2; ++k) dst[m][k] = *(const LAS bf16x8*)(lds + PG8_SA(b, h) + aoff + m * 2048 + k * 1024); } while (0)
; #define PG8_LDB(dst, b, h) do { _Pragma("unroll") for (int n = 0; n < 2; ++n) _Pragma("unroll") for (int k = 0; k < 2; ++k) dst[n][k] = *(const LAS bf16x8*)(lds + PG8_SB(b, h) + boff + n * 2048 + k * 1024); } while (0)
; #define PG8_MMA(ai, bj, At, Bt_) do { __builtin_amdgcn_s_setprio(1); _Pragma("unroll") for (int m = 0; m < 4; ++m) _Pragma("unroll") for (int n = 0; n < 2; ++n) _Pragma("unroll") for (int k = 0; k < 2; ++k) \
;         acc[ai][bj][m][n] = __builtin_amdgcn_mfma_f32_16x16x32_bf16(Bt_[n][k], At[m][k], acc[ai][bj][m][n], 0, 0, 0); __builtin_amdgcn_s_setprio(0); } while (0)
; #define PG8_WAIT_V(n) asm volatile("s_waitcnt vmcnt(" #n ")" ::: "memory")
; #define PG8_WAIT_L(n) asm volatile("s_waitcnt lgkmcnt(" #n ")" ::: "memory")
; #define PG8_BAR __builtin_amdgcn_s_barrier()
; template <int EK, int SK = -1>
; __device__ __forceinline__ void gemm_phase(LAS unsigned char* lds, const bf16_t* A, const bf16_t* Bt, int nM, int N, int K, const EpiArgs& E) {
;     ...
;         const bool has_next = S.next(ui + 1, nxt);
;         const char* nA = has_next ? (const char*)A + (size_t)nxt.pm * tstep : cA; const char* nB = has_next ? (const char*)Bt + (size_t)nxt.pn * tstep : cB;
;         for (int t = 0; t < nt; t += 2) {
;             const bool last = (t == nt - 2);
;             const char* a1 = cA + (size_t)(t + 1) * kstep;
;             const char* a2 = last ? nA : cA + (size_t)(t + 2) * kstep; const char* b2 = last ? nB : cB + (size_t)(t + 2) * kstep;
;             const char* a3 = a2 + kstep; const char* b3 = b2 + kstep;
;             PG8_LDB(B0, 0, 0); PG8_LDB(B1, 0, 1); PG8_SCHED; PG8_LDA(At, 0, 0); PG8_STAGEA(PG8_SA(1, 1), a1 + hstep);
;             PG8_WAIT_V(8); PG8_WAIT_L(0); PG8_BAR; PG8_MMA(0, 0, At, B0); PG8_MMA(0, 1, At, B1); PG8_BAR; PG8_SCHED;
;             PG8_LDA(At, 0, 1); PG8_STAGEB(PG8_SB(0, 0), b2); PG8_STAGEB(PG8_SB(0, 1), b2 + hstep); PG8_STAGEA(PG8_SA(0, 0), a2);
;             PG8_WAIT_V(8); PG8_WAIT_L(0); PG8_BAR; PG8_MMA(1, 0, At, B0); PG8_MMA(1, 1, At, B1); PG8_BAR; PG8_SCHED;
.LBB0_1120:
	v_add_u32_e32 v150, s69, v152
	ds_read_b128 v[156:159], v150
	ds_read_b128 v[160:163], v150 offset:1024
	ds_read_b128 v[164:167], v150 offset:2048
	ds_read_b128 v[168:171], v150 offset:3072
	v_add_u32_e32 v150, s70, v152
	s_add_u32 s48, s18, s46
	ds_read_b128 v[172:175], v150
	ds_read_b128 v[176:179], v150 offset:1024
	ds_read_b128 v[180:183], v150 offset:2048
	ds_read_b128 v[184:187], v150 offset:3072
	s_addc_u32 s49, s19, s47
	s_add_u32 s48, s48, 0x100
	s_addc_u32 s49, s49, 0
	s_add_u32 s77, s73, s46
	s_addc_u32 s78, s74, s47
	s_cmpk_eq_i32 s46, 0x700
	s_cselect_b32 s51, s22, s49
	s_cselect_b32 s50, s41, s48
	s_cselect_b32 s49, s39, s78
	s_cselect_b32 s48, s75, s77
	v_lshl_add_u64 v[150:151], v[146:147], 0, s[46:47]
	s_add_i32 m0, s15, 0xc000
	ds_read_b128 v[188:191], v154
	ds_read_b128 v[192:195], v154 offset:1024
	ds_read_b128 v[196:199], v154 offset:2048
	ds_read_b128 v[200:203], v154 offset:3072
	ds_read_b128 v[204:207], v154 offset:4096
	ds_read_b128 v[208:211], v154 offset:5120
	ds_read_b128 v[212:215], v154 offset:6144
	ds_read_b128 v[216:219], v154 offset:7168
	global_load_lds_dwordx4 v[150:151], off
	v_lshl_add_u64 v[150:151], v[148:149], 0, s[46:47]
	s_add_i32 m0, s15, 0xe000
	s_nop 0
	global_load_lds_dwordx4 v[150:151], off
	s_waitcnt vmcnt(8)
	s_waitcnt lgkmcnt(0)
	s_barrier
	s_waitcnt lgkmcnt(0)
	v_mfma_f32_16x16x32_bf16 v[126:129], v[156:159], v[188:191], v[126:129]
	v_mfma_f32_16x16x32_bf16 v[122:125], v[164:167], v[188:191], v[122:125]
	v_mfma_f32_16x16x32_bf16 v[118:121], v[156:159], v[196:199], v[118:121]
	v_mfma_f32_16x16x32_bf16 v[114:117], v[164:167], v[196:199], v[114:117]
	v_mfma_f32_16x16x32_bf16 v[110:113], v[156:159], v[204:207], v[110:113]
	v_mfma_f32_16x16x32_bf16 v[106:109], v[164:167], v[204:207], v[106:109]
	v_mfma_f32_16x16x32_bf16 v[102:105], v[156:159], v[212:215], v[102:105]
	v_mfma_f32_16x16x32_bf16 v[98:101], v[164:167], v[212:215], v[98:101]
	v_mfma_f32_16x16x32_bf16 v[126:129], v[160:163], v[192:195], v[126:129]
	v_mfma_f32_16x16x32_bf16 v[122:125], v[168:171], v[192:195], v[122:125]
	v_mfma_f32_16x16x32_bf16 v[118:121], v[160:163], v[200:203], v[118:121]
	v_mfma_f32_16x16x32_bf16 v[114:117], v[168:171], v[200:203], v[114:117]
	v_mfma_f32_16x16x32_bf16 v[110:113], v[160:163], v[208:211], v[110:113]
	v_mfma_f32_16x16x32_bf16 v[106:109], v[168:171], v[208:211], v[106:109]
	v_mfma_f32_16x16x32_bf16 v[102:105], v[160:163], v[216:219], v[102:105]
	v_mfma_f32_16x16x32_bf16 v[98:101], v[168:171], v[216:219], v[98:101]
	v_mfma_f32_16x16x32_bf16 v[94:97], v[172:175], v[188:191], v[94:97]
	v_mfma_f32_16x16x32_bf16 v[90:93], v[180:183], v[188:191], v[90:93]
	v_mfma_f32_16x16x32_bf16 v[86:89], v[172:175], v[196:199], v[86:89]
	v_mfma_f32_16x16x32_bf16 v[82:85], v[180:183], v[196:199], v[82:85]
	v_mfma_f32_16x16x32_bf16 v[78:81], v[172:175], v[204:207], v[78:81]
	v_mfma_f32_16x16x32_bf16 v[74:77], v[180:183], v[204:207], v[74:77]
	v_mfma_f32_16x16x32_bf16 v[70:73], v[172:175], v[212:215], v[70:73]
	v_mfma_f32_16x16x32_bf16 v[66:69], v[180:183], v[212:215], v[66:69]
	v_mfma_f32_16x16x32_bf16 v[94:97], v[176:179], v[192:195], v[94:97]
	v_mfma_f32_16x16x32_bf16 v[90:93], v[184:187], v[192:195], v[90:93]
	v_mfma_f32_16x16x32_bf16 v[86:89], v[176:179], v[200:203], v[86:89]
	v_mfma_f32_16x16x32_bf16 v[82:85], v[184:187], v[200:203], v[82:85]
	v_mfma_f32_16x16x32_bf16 v[78:81], v[176:179], v[208:211], v[78:81]
	v_mfma_f32_16x16x32_bf16 v[74:77], v[184:187], v[208:211], v[74:77]
	v_mfma_f32_16x16x32_bf16 v[70:73], v[176:179], v[216:219], v[70:73]
	v_mfma_f32_16x16x32_bf16 v[66:69], v[184:187], v[216:219], v[66:69]
	s_barrier
	s_add_i32 s77, s69, s54
	v_lshl_add_u64 v[150:151], s[48:49], 0, v[132:133]
	s_mov_b32 m0, s77
	ds_read_b128 v[188:191], v154 offset:16384
	ds_read_b128 v[192:195], v154 offset:17408
	ds_read_b128 v[196:199], v154 offset:18432
	ds_read_b128 v[200:203], v154 offset:19456
	ds_read_b128 v[204:207], v154 offset:20480
	ds_read_b128 v[208:211], v154 offset:21504
	ds_read_b128 v[212:215], v154 offset:22528
	ds_read_b128 v[216:219], v154 offset:23552
	global_load_lds_dwordx4 v[150:151], off
	s_add_i32 m0, s77, 0x2000
	s_add_u32 s78, s48, 0x40000
	v_lshl_add_u64 v[220:221], s[48:49], 0, v[136:137]
	s_addc_u32 s79, s49, 0
	s_add_i32 s77, s70, s54
	global_load_lds_dwordx4 v[220:221], off
	v_lshl_add_u64 v[222:223], s[78:79], 0, v[132:133]
	s_mov_b32 m0, s77
	v_lshl_add_u64 v[224:225], s[50:51], 0, v[134:135]
	global_load_lds_dwordx4 v[222:223], off
	v_lshl_add_u64 v[222:223], s[78:79], 0, v[136:137]
	s_add_i32 m0, s77, 0x2000
	s_nop 0
	global_load_lds_dwordx4 v[222:223], off
	v_lshl_add_u64 v[222:223], s[50:51], 0, v[130:131]
	s_mov_b32 m0, s15
	s_nop 0
	global_load_lds_dwordx4 v[222:223], off
	s_mov_b32 m0, s17
	s_nop 0
	global_load_lds_dwordx4 v[224:225], off
	s_waitcnt vmcnt(8)
	s_waitcnt lgkmcnt(0)
	s_barrier
; #define PG8_STAGEA(bufoff, gbase) PG8_STAGE_(bufoff, gbase, voffA)
; #define PG8_LDA(dst, b, h) do { _Pragma("unroll") for (int m = 0; m < 4; ++m) _Pragma("unroll") for (int k = 0; k < 2; ++k) dst[m][k] = *(const LAS bf16x8*)(lds + PG8_SA(b, h) + aoff + m * 2048 + k * 1024); } while (0)
; #define PG8_LDB(dst, b, h) do { _Pragma("unroll") for (int n = 0; n < 2; ++n) _Pragma("unroll") for (int k = 0; k < 2; ++k) dst[n][k] = *(const LAS bf16x8*)(lds + PG8_SB(b, h) + boff + n * 2048 + k * 1024); } while (0)
; #define PG8_MMA(ai, bj, At, Bt_) do { __builtin_amdgcn_s_setprio(1); _Pragma("unroll") for (int m = 0; m < 4; ++m) _Pragma("unroll") for (int n = 0; n < 2; ++n) _Pragma("unroll") for (int k = 0; k < 2; ++k) \
;         acc[ai][bj][m][n] = __builtin_amdgcn_mfma_f32_16x16x32_bf16(Bt_[n][k], At[m][k], acc[ai][bj][m][n], 0, 0, 0); __builtin_amdgcn_s_setprio(0); } while (0)
; #define PG8_WAIT_V(n) asm volatile("s_waitcnt vmcnt(" #n ")" ::: "memory")
; #define PG8_WAIT_L(n) asm volatile("s_waitcnt lgkmcnt(" #n ")" ::: "memory")
; #define PG8_BAR __builtin_amdgcn_s_barrier()
; #define PG8_SCHED __builtin_amdgcn_sched_barrier(0)
; template <int EK, int SK = -1>
; __device__ __forceinline__ void gemm_phase(LAS unsigned char* lds, const bf16_t* A, const bf16_t* Bt, int nM, int N, int K, const EpiArgs& E) {
;     ...
;             PG8_WAIT_V(8); PG8_WAIT_L(0); PG8_BAR; PG8_MMA(1, 0, At, B0); PG8_MMA(1, 1, At, B1); PG8_BAR; PG8_SCHED;
;             PG8_LDB(B0, 1, 0); PG8_LDB(B1, 1, 1); PG8_SCHED; PG8_LDA(At, 1, 0); PG8_STAGEA(PG8_SA(0, 1), a2 + hstep);
;             PG8_WAIT_V(8); PG8_WAIT_L(0); PG8_BAR; PG8_MMA(0, 0, At, B0); PG8_MMA(0, 1, At, B1); PG8_BAR; PG8_SCHED;
	s_waitcnt lgkmcnt(0)
	v_mfma_f32_16x16x32_bf16 v[62:65], v[156:159], v[188:191], v[62:65]
	v_mfma_f32_16x16x32_bf16 v[58:61], v[164:167], v[188:191], v[58:61]
	v_mfma_f32_16x16x32_bf16 v[54:57], v[156:159], v[196:199], v[54:57]
	v_mfma_f32_16x16x32_bf16 v[50:53], v[164:167], v[196:199], v[50:53]
	v_mfma_f32_16x16x32_bf16 v[46:49], v[156:159], v[204:207], v[46:49]
	v_mfma_f32_16x16x32_bf16 v[42:45], v[164:167], v[204:207], v[42:45]
	v_mfma_f32_16x16x32_bf16 v[38:41], v[156:159], v[212:215], v[38:41]
	v_mfma_f32_16x16x32_bf16 v[34:37], v[164:167], v[212:215], v[34:37]
	v_mfma_f32_16x16x32_bf16 v[62:65], v[160:163], v[192:195], v[62:65]
	v_mfma_f32_16x16x32_bf16 v[58:61], v[168:171], v[192:195], v[58:61]
	v_mfma_f32_16x16x32_bf16 v[54:57], v[160:163], v[200:203], v[54:57]
	v_mfma_f32_16x16x32_bf16 v[50:53], v[168:171], v[200:203], v[50:53]
	v_mfma_f32_16x16x32_bf16 v[46:49], v[160:163], v[208:211], v[46:49]
	v_mfma_f32_16x16x32_bf16 v[42:45], v[168:171], v[208:211], v[42:45]
	v_mfma_f32_16x16x32_bf16 v[38:41], v[160:163], v[216:219], v[38:41]
	v_mfma_f32_16x16x32_bf16 v[34:37], v[168:171], v[216:219], v[34:37]
	v_mfma_f32_16x16x32_bf16 v[30:33], v[172:175], v[188:191], v[30:33]
	v_mfma_f32_16x16x32_bf16 v[26:29], v[180:183], v[188:191], v[26:29]
	v_mfma_f32_16x16x32_bf16 v[22:25], v[172:175], v[196:199], v[22:25]
	v_mfma_f32_16x16x32_bf16 v[18:21], v[180:183], v[196:199], v[18:21]
	v_mfma_f32_16x16x32_bf16 v[14:17], v[172:175], v[204:207], v[14:17]
	v_mfma_f32_16x16x32_bf16 v[10:13], v[180:183], v[204:207], v[10:13]
	v_mfma_f32_16x16x32_bf16 v[6:9], v[172:175], v[212:215], v[6:9]
	v_mfma_f32_16x16x32_bf16 v[2:5], v[180:183], v[212:215], v[2:5]
	v_mfma_f32_16x16x32_bf16 v[30:33], v[176:179], v[192:195], v[30:33]
	v_mfma_f32_16x16x32_bf16 v[26:29], v[184:187], v[192:195], v[26:29]
	v_mfma_f32_16x16x32_bf16 v[22:25], v[176:179], v[200:203], v[22:25]
	v_mfma_f32_16x16x32_bf16 v[18:21], v[184:187], v[200:203], v[18:21]
	v_mfma_f32_16x16x32_bf16 v[14:17], v[176:179], v[208:211], v[14:17]
	v_mfma_f32_16x16x32_bf16 v[10:13], v[184:187], v[208:211], v[10:13]
	v_mfma_f32_16x16x32_bf16 v[6:9], v[176:179], v[216:219], v[6:9]
	v_mfma_f32_16x16x32_bf16 v[2:5], v[184:187], v[216:219], v[2:5]
	s_barrier
	s_add_i32 s77, 0, 0x18000
	s_add_i32 s78, 0, 0x1c000
	v_add_u32_e32 v168, s77, v152
	v_add_u32_e32 v184, s78, v152
	ds_read_b128 v[156:159], v168
	ds_read_b128 v[160:163], v168 offset:1024
	ds_read_b128 v[164:167], v168 offset:2048
	ds_read_b128 v[168:171], v168 offset:3072
	ds_read_b128 v[172:175], v184
	ds_read_b128 v[176:179], v184 offset:1024
	ds_read_b128 v[180:183], v184 offset:2048
	ds_read_b128 v[184:187], v184 offset:3072
	s_add_u32 s50, s50, 0x40000
	s_addc_u32 s51, s51, 0
	s_mov_b32 m0, s55
	v_lshl_add_u64 v[226:227], s[50:51], 0, v[130:131]
	ds_read_b128 v[188:191], v154 offset:32768
	ds_read_b128 v[192:195], v154 offset:33792
	ds_read_b128 v[196:199], v154 offset:34816
	ds_read_b128 v[200:203], v154 offset:35840
	ds_read_b128 v[204:207], v154 offset:36864
	ds_read_b128 v[208:211], v154 offset:37888
	ds_read_b128 v[212:215], v154 offset:38912
	ds_read_b128 v[216:219], v154 offset:39936
	global_load_lds_dwordx4 v[226:227], off
	v_lshl_add_u64 v[226:227], s[50:51], 0, v[134:135]
	s_mov_b32 m0, s56
	s_nop 0
	global_load_lds_dwordx4 v[226:227], off
	s_waitcnt vmcnt(8)
	s_waitcnt lgkmcnt(0)
	s_barrier
	s_waitcnt lgkmcnt(0)
	v_mfma_f32_16x16x32_bf16 v[126:129], v[156:159], v[188:191], v[126:129]
	v_mfma_f32_16x16x32_bf16 v[122:125], v[164:167], v[188:191], v[122:125]
	v_mfma_f32_16x16x32_bf16 v[118:121], v[156:159], v[196:199], v[118:121]
	v_mfma_f32_16x16x32_bf16 v[114:117], v[164:167], v[196:199], v[114:117]
	v_mfma_f32_16x16x32_bf16 v[110:113], v[156:159], v[204:207], v[110:113]
	v_mfma_f32_16x16x32_bf16 v[106:109], v[164:167], v[204:207], v[106:109]
	v_mfma_f32_16x16x32_bf16 v[102:105], v[156:159], v[212:215], v[102:105]
	v_mfma_f32_16x16x32_bf16 v[98:101], v[164:167], v[212:215], v[98:101]
	v_mfma_f32_16x16x32_bf16 v[126:129], v[160:163], v[192:195], v[126:129]
	v_mfma_f32_16x16x32_bf16 v[122:125], v[168:171], v[192:195], v[122:125]
	v_mfma_f32_16x16x32_bf16 v[118:121], v[160:163], v[200:203], v[118:121]
	v_mfma_f32_16x16x32_bf16 v[114:117], v[168:171], v[200:203], v[114:117]
	v_mfma_f32_16x16x32_bf16 v[110:113], v[160:163], v[208:211], v[110:113]
	v_mfma_f32_16x16x32_bf16 v[106:109], v[168:171], v[208:211], v[106:109]
	v_mfma_f32_16x16x32_bf16 v[102:105], v[160:163], v[216:219], v[102:105]
	v_mfma_f32_16x16x32_bf16 v[98:101], v[168:171], v[216:219], v[98:101]
	v_mfma_f32_16x16x32_bf16 v[94:97], v[172:175], v[188:191], v[94:97]
	v_mfma_f32_16x16x32_bf16 v[90:93], v[180:183], v[188:191], v[90:93]
	v_mfma_f32_16x16x32_bf16 v[86:89], v[172:175], v[196:199], v[86:89]
	v_mfma_f32_16x16x32_bf16 v[82:85], v[180:183], v[196:199], v[82:85]
	v_mfma_f32_16x16x32_bf16 v[78:81], v[172:175], v[204:207], v[78:81]
	v_mfma_f32_16x16x32_bf16 v[74:77], v[180:183], v[204:207], v[74:77]
	v_mfma_f32_16x16x32_bf16 v[70:73], v[172:175], v[212:215], v[70:73]
	v_mfma_f32_16x16x32_bf16 v[66:69], v[180:183], v[212:215], v[66:69]
	v_mfma_f32_16x16x32_bf16 v[94:97], v[176:179], v[192:195], v[94:97]
	v_mfma_f32_16x16x32_bf16 v[90:93], v[184:187], v[192:195], v[90:93]
	v_mfma_f32_16x16x32_bf16 v[86:89], v[176:179], v[200:203], v[86:89]
	v_mfma_f32_16x16x32_bf16 v[82:85], v[184:187], v[200:203], v[82:85]
	v_mfma_f32_16x16x32_bf16 v[78:81], v[176:179], v[208:211], v[78:81]
	v_mfma_f32_16x16x32_bf16 v[74:77], v[184:187], v[208:211], v[74:77]
	v_mfma_f32_16x16x32_bf16 v[70:73], v[176:179], v[216:219], v[70:73]
	v_mfma_f32_16x16x32_bf16 v[66:69], v[184:187], v[216:219], v[66:69]
	s_barrier
; #define PG8_STAGEA(bufoff, gbase) PG8_STAGE_(bufoff, gbase, voffA)
; #define PG8_STAGEB(bufoff, gbase) PG8_STAGE_(bufoff, gbase, voffB)
; #define PG8_LDA(dst, b, h) do { _Pragma("unroll") for (int m = 0; m < 4; ++m) _Pragma("unroll") for (int k = 0; k < 2; ++k) dst[m][k] = *(const LAS bf16x8*)(lds + PG8_SA(b, h) + aoff + m * 2048 + k * 1024); } while (0)
; #define PG8_MMA(ai, bj, At, Bt_) do { __builtin_amdgcn_s_setprio(1); _Pragma("unroll") for (int m = 0; m < 4; ++m) _Pragma("unroll") for (int n = 0; n < 2; ++n) _Pragma("unroll") for (int k = 0; k < 2; ++k) \
;         acc[ai][bj][m][n] = __builtin_amdgcn_mfma_f32_16x16x32_bf16(Bt_[n][k], At[m][k], acc[ai][bj][m][n], 0, 0, 0); __builtin_amdgcn_s_setprio(0); } while (0)
; #define PG8_WAIT_V(n) asm volatile("s_waitcnt vmcnt(" #n ")" ::: "memory")
; #define PG8_WAIT_L(n) asm volatile("s_waitcnt lgkmcnt(" #n ")" ::: "memory")
; #define PG8_BAR __builtin_amdgcn_s_barrier()
; #define PG8_SCHED __builtin_amdgcn_sched_barrier(0)
; template <int EK, int SK = -1>
; __device__ __forceinline__ void gemm_phase(LAS unsigned char* lds, const bf16_t* A, const bf16_t* Bt, int nM, int N, int K, const EpiArgs& E) {
;     ...
;             PG8_LDA(At, 1, 1); PG8_STAGEB(PG8_SB(1, 0), b3); PG8_STAGEB(PG8_SB(1, 1), b3 + hstep); PG8_STAGEA(PG8_SA(1, 0), a3);
;             PG8_WAIT_V(8); PG8_WAIT_L(0); PG8_BAR; PG8_MMA(1, 0, At, B0); PG8_MMA(1, 1, At, B1); PG8_BAR; PG8_SCHED;
;         }
	s_add_i32 s50, s77, s54
	v_lshl_add_u64 v[150:151], v[150:151], 0, s[26:27]
	s_mov_b32 m0, s50
	ds_read_b128 v[188:191], v154 offset:49152
	ds_read_b128 v[192:195], v154 offset:50176
	ds_read_b128 v[196:199], v154 offset:51200
	ds_read_b128 v[200:203], v154 offset:52224
	ds_read_b128 v[204:207], v154 offset:53248
	ds_read_b128 v[208:211], v154 offset:54272
	ds_read_b128 v[212:215], v154 offset:55296
	ds_read_b128 v[216:219], v154 offset:56320
	global_load_lds_dwordx4 v[150:151], off
	s_add_i32 m0, s50, 0x2000
	s_add_u32 s48, s48, 0x40080
	v_lshl_add_u64 v[150:151], v[220:221], 0, s[26:27]
	s_addc_u32 s49, s49, 0
	s_add_i32 s50, s78, s54
	global_load_lds_dwordx4 v[150:151], off
	v_lshl_add_u64 v[150:151], s[48:49], 0, v[132:133]
	s_mov_b32 m0, s50
	s_nop 0
	global_load_lds_dwordx4 v[150:151], off
	v_lshl_add_u64 v[150:151], s[48:49], 0, v[136:137]
	s_add_i32 m0, s50, 0x2000
	s_nop 0
	global_load_lds_dwordx4 v[150:151], off
	v_lshl_add_u64 v[150:151], v[222:223], 0, s[26:27]
	s_mov_b32 m0, s59
	s_nop 0
	global_load_lds_dwordx4 v[150:151], off
	v_lshl_add_u64 v[150:151], v[224:225], 0, s[26:27]
	s_mov_b32 m0, s68
	s_nop 0
	global_load_lds_dwordx4 v[150:151], off
	s_waitcnt vmcnt(8)
	s_waitcnt lgkmcnt(0)
	s_barrier
	s_waitcnt lgkmcnt(0)
	v_mfma_f32_16x16x32_bf16 v[62:65], v[156:159], v[188:191], v[62:65]
	v_mfma_f32_16x16x32_bf16 v[58:61], v[164:167], v[188:191], v[58:61]
	v_mfma_f32_16x16x32_bf16 v[54:57], v[156:159], v[196:199], v[54:57]
	v_mfma_f32_16x16x32_bf16 v[50:53], v[164:167], v[196:199], v[50:53]
	v_mfma_f32_16x16x32_bf16 v[46:49], v[156:159], v[204:207], v[46:49]
	v_mfma_f32_16x16x32_bf16 v[42:45], v[164:167], v[204:207], v[42:45]
	v_mfma_f32_16x16x32_bf16 v[38:41], v[156:159], v[212:215], v[38:41]
	v_mfma_f32_16x16x32_bf16 v[34:37], v[164:167], v[212:215], v[34:37]
	v_mfma_f32_16x16x32_bf16 v[62:65], v[160:163], v[192:195], v[62:65]
	v_mfma_f32_16x16x32_bf16 v[58:61], v[168:171], v[192:195], v[58:61]
	v_mfma_f32_16x16x32_bf16 v[54:57], v[160:163], v[200:203], v[54:57]
	v_mfma_f32_16x16x32_bf16 v[50:53], v[168:171], v[200:203], v[50:53]
	v_mfma_f32_16x16x32_bf16 v[46:49], v[160:163], v[208:211], v[46:49]
	v_mfma_f32_16x16x32_bf16 v[42:45], v[168:171], v[208:211], v[42:45]
	v_mfma_f32_16x16x32_bf16 v[38:41], v[160:163], v[216:219], v[38:41]
	v_mfma_f32_16x16x32_bf16 v[34:37], v[168:171], v[216:219], v[34:37]
	v_mfma_f32_16x16x32_bf16 v[30:33], v[172:175], v[188:191], v[30:33]
	v_mfma_f32_16x16x32_bf16 v[26:29], v[180:183], v[188:191], v[26:29]
	v_mfma_f32_16x16x32_bf16 v[22:25], v[172:175], v[196:199], v[22:25]
	v_mfma_f32_16x16x32_bf16 v[18:21], v[180:183], v[196:199], v[18:21]
	v_mfma_f32_16x16x32_bf16 v[14:17], v[172:175], v[204:207], v[14:17]
	v_mfma_f32_16x16x32_bf16 v[10:13], v[180:183], v[204:207], v[10:13]
	v_mfma_f32_16x16x32_bf16 v[6:9], v[172:175], v[212:215], v[6:9]
	v_mfma_f32_16x16x32_bf16 v[2:5], v[180:183], v[212:215], v[2:5]
	v_mfma_f32_16x16x32_bf16 v[30:33], v[176:179], v[192:195], v[30:33]
	v_mfma_f32_16x16x32_bf16 v[26:29], v[184:187], v[192:195], v[26:29]
	v_mfma_f32_16x16x32_bf16 v[22:25], v[176:179], v[200:203], v[22:25]
	v_mfma_f32_16x16x32_bf16 v[18:21], v[184:187], v[200:203], v[18:21]
	v_mfma_f32_16x16x32_bf16 v[14:17], v[176:179], v[208:211], v[14:17]
	v_mfma_f32_16x16x32_bf16 v[10:13], v[184:187], v[208:211], v[10:13]
	v_mfma_f32_16x16x32_bf16 v[6:9], v[176:179], v[216:219], v[6:9]
	v_mfma_f32_16x16x32_bf16 v[2:5], v[184:187], v[216:219], v[2:5]
	s_barrier
	s_add_i32 s76, s76, 2
	s_add_u32 s46, s46, 0x100
	s_addc_u32 s47, s47, 0
	s_cmp_gt_u32 s76, 13
	s_cbranch_scc0 .LBB0_1120
	s_and_b64 vcc, exec, s[36:37]
	s_cbranch_vccz .LBB0_1123
	s_barrier

; __device__ __forceinline__ unsigned xb_add(unsigned* p, unsigned v) { return __hip_atomic_fetch_add(p, v, __ATOMIC_RELAXED, __HIP_MEMORY_SCOPE_AGENT); }
; __device__ __forceinline__ void xcd_barrier(const XcdBarrier& b) {
;     asm volatile("s_waitcnt vmcnt(0)" ::: "memory");
;     __syncthreads();
;     if (threadIdx.x == 0) {
;         unsigned* bar = b.bar;
;         __builtin_amdgcn_s_waitcnt(0);
;         unsigned nloc = b.st[0], nx = b.st[1];
;         if (nloc == 0u) { xcd_barrier_complete(bar, b.x, nloc, nx); b.st[0] = nloc; b.st[1] = nx; }
;         const unsigned old = xb_add(&bar[XB_XSUB(b.x)], 1u);
;         const unsigned gen = old / nloc;
;         if (old + 1u == (gen + 1u) * nloc) {
.LBB0_1144:
	s_cmp_gt_i32 s35, 9
	s_cselect_b64 s[4:5], -1, 0
	s_and_b64 s[6:7], s[10:11], s[4:5]
	s_andn2_b64 vcc, exec, s[6:7]
	s_cbranch_vccnz .LBB0_1194
	s_waitcnt vmcnt(0)
	v_cmp_eq_u32_e32 vcc, 0, v0
	s_waitcnt vmcnt(0) lgkmcnt(0)
	s_barrier
	v_readfirstlane_b32 s98, v0
	s_nop 3
	s_lshr_b32 s98, s98, 6
	s_cmp_lg_u32 s98, 1
	s_cbranch_scc1 .Lmy_noinv9
	buffer_inv sc1
	s_waitcnt vmcnt(0)
.Lmy_noinv9:
	s_and_saveexec_b64 s[6:7], vcc
	s_cbranch_execz .LBB0_1193
	s_add_i32 s3, 0, 0x20000
	v_mov_b32_e32 v1, s3
	s_waitcnt vmcnt(0) expcnt(0) lgkmcnt(0)
	ds_read_b32 v3, v1
	s_add_i32 s3, 0, 0x20004
	v_mov_b32_e32 v1, s3
	ds_read_b32 v1, v1
	s_waitcnt lgkmcnt(1)
	v_cmp_ne_u32_e32 vcc, 0, v3
	s_cbranch_vccnz .LBB0_1161
	s_load_dwordx2 s[14:15], s[0:1], 0xb8
	s_load_dword s3, s[0:1], 0xc0
	s_add_u32 s8, s30, 0xb4b8200
	s_addc_u32 s9, s31, 0
	s_add_u32 s10, s30, 0xb4b8400
	s_waitcnt lgkmcnt(0)
	s_mul_i32 s11, s15, s14
	s_mul_i32 s3, s11, s3
	s_addc_u32 s11, s31, 0
	s_add_u32 s14, s30, 0xb4b8500
	s_addc_u32 s15, s31, 0
	s_add_u32 s16, s30, 0xb4b8600
	s_addc_u32 s17, s31, 0
	s_add_u32 s18, s30, 0xb4b8700
	s_addc_u32 s19, s31, 0
	s_add_u32 s20, s30, 0xb4b8800
	s_addc_u32 s21, s31, 0
	s_add_u32 s22, s30, 0xb4b8900
	s_addc_u32 s23, s31, 0
	s_add_u32 s26, s30, 0xb4b8a00
	s_addc_u32 s27, s31, 0
	s_add_u32 s36, s30, 0xb4b8b00
	s_addc_u32 s37, s31, 0
	s_add_u32 s38, s30, 0xb4b8c00
	s_addc_u32 s39, s31, 0
	s_add_u32 s40, s30, 0xb4b8d00
	s_addc_u32 s41, s31, 0
	s_add_u32 s42, s30, 0xb4b8e00
	s_addc_u32 s43, s31, 0
	s_add_u32 s44, s30, 0xb4b8f00
	s_addc_u32 s45, s31, 0
	s_add_u32 s46, s30, 0xb4b9000
	s_addc_u32 s47, s31, 0
	s_add_u32 s48, s30, 0xb4b9100
	s_addc_u32 s49, s31, 0
	s_add_u32 s50, s30, 0xb4b9200
	s_addc_u32 s51, s31, 0
	s_add_u32 s52, s30, 0xb4b9300
	s_addc_u32 s53, s31, 0
	s_mov_b32 s66, 1
	v_mov_b32_e32 v17, 0
	s_branch .LBB0_1149

; #define PG8_STAGEA(bufoff, gbase) PG8_STAGE_(bufoff, gbase, voffA)
; #define PG8_STAGEB(bufoff, gbase) PG8_STAGE_(bufoff, gbase, voffB)
; #define PG8_LDA(dst, b, h) do { _Pragma("unroll") for (int m = 0; m < 4; ++m) _Pragma("unroll") for (int k = 0; k < 2; ++k) dst[m][k] = *(const LAS bf16x8*)(lds + PG8_SA(b, h) + aoff + m * 2048 + k * 1024); } while (0)
; #define PG8_LDB(dst, b, h) do { _Pragma("unroll") for (int n = 0; n < 2; ++n) _Pragma("unroll") for (int k = 0; k < 2; ++k) dst[n][k] = *(const LAS bf16x8*)(lds + PG8_SB(b, h) + boff + n * 2048 + k * 1024); } while (0)
; #define PG8_MMA(ai, bj, At, Bt_) do { __builtin_amdgcn_s_setprio(1); _Pragma("unroll") for (int m = 0; m < 4; ++m) _Pragma("unroll") for (int n = 0; n < 2; ++n) _Pragma("unroll") for (int k = 0; k < 2; ++k) \
;         acc[ai][bj][m][n] = __builtin_amdgcn_mfma_f32_16x16x32_bf16(Bt_[n][k], At[m][k], acc[ai][bj][m][n], 0, 0, 0); __builtin_amdgcn_s_setprio(0); } while (0)
; #define PG8_WAIT_V(n) asm volatile("s_waitcnt vmcnt(" #n ")" ::: "memory")
; #define PG8_WAIT_L(n) asm volatile("s_waitcnt lgkmcnt(" #n ")" ::: "memory")
; #define PG8_BAR __builtin_amdgcn_s_barrier()
; template <int EK, int SK = -1>
; __device__ __forceinline__ void gemm_phase(LAS unsigned char* lds, const bf16_t* A, const bf16_t* Bt, int nM, int N, int K, const EpiArgs& E) {
;     ...
;         const bool has_next = S.next(ui + 1, nxt);
;         const char* nA = has_next ? (const char*)A + (size_t)nxt.pm * tstep : cA; const char* nB = has_next ? (const char*)Bt + (size_t)nxt.pn * tstep : cB;
;         for (int t = 0; t < nt; t += 2) {
;             const bool last = (t == nt - 2);
;             const char* a1 = cA + (size_t)(t + 1) * kstep;
;             const char* a2 = last ? nA : cA + (size_t)(t + 2) * kstep; const char* b2 = last ? nB : cB + (size_t)(t + 2) * kstep;
;             const char* a3 = a2 + kstep; const char* b3 = b2 + kstep;
;             PG8_LDB(B0, 0, 0); PG8_LDB(B1, 0, 1); PG8_SCHED; PG8_LDA(At, 0, 0); PG8_STAGEA(PG8_SA(1, 1), a1 + hstep);
;             PG8_WAIT_V(8); PG8_WAIT_L(0); PG8_BAR; PG8_MMA(0, 0, At, B0); PG8_MMA(0, 1, At, B1); PG8_BAR; PG8_SCHED;
;             PG8_LDA(At, 0, 1); PG8_STAGEB(PG8_SB(0, 0), b2); PG8_STAGEB(PG8_SB(0, 1), b2 + hstep); PG8_STAGEA(PG8_SA(0, 0), a2);
;             PG8_WAIT_V(8); PG8_WAIT_L(0); PG8_BAR; PG8_MMA(1, 0, At, B0); PG8_MMA(1, 1, At, B1); PG8_BAR; PG8_SCHED;
.LBB0_1245:
	v_add_u32_e32 v154, s54, v156
	ds_read_b128 v[150:153], v154
	ds_read_b128 v[160:163], v154 offset:1024
	ds_read_b128 v[164:167], v154 offset:2048
	ds_read_b128 v[168:171], v154 offset:3072
	v_add_u32_e32 v154, s55, v156
	s_add_u32 s42, s20, s40
	ds_read_b128 v[172:175], v154
	ds_read_b128 v[176:179], v154 offset:1024
	ds_read_b128 v[180:183], v154 offset:2048
	ds_read_b128 v[184:187], v154 offset:3072
	s_addc_u32 s43, s21, s41
	s_add_u32 s42, s42, 0x100
	s_addc_u32 s43, s43, 0
	s_add_u32 s70, s59, s40
	s_addc_u32 s71, s66, s41
	s_cmpk_eq_i32 s40, 0x700
	s_cselect_b32 s45, s27, s43
	s_cselect_b32 s44, s67, s42
	s_cselect_b32 s43, s23, s71
	s_cselect_b32 s42, s68, s70
	v_lshl_add_u64 v[154:155], v[146:147], 0, s[40:41]
	s_add_i32 m0, s17, 0xc000
	ds_read_b128 v[188:191], v159
	ds_read_b128 v[192:195], v159 offset:1024
	ds_read_b128 v[196:199], v159 offset:2048
	ds_read_b128 v[200:203], v159 offset:3072
	ds_read_b128 v[204:207], v159 offset:4096
	ds_read_b128 v[208:211], v159 offset:5120
	ds_read_b128 v[212:215], v159 offset:6144
	ds_read_b128 v[216:219], v159 offset:7168
	global_load_lds_dwordx4 v[154:155], off
	v_lshl_add_u64 v[154:155], v[148:149], 0, s[40:41]
	s_add_i32 m0, s17, 0xe000
	s_nop 0
	global_load_lds_dwordx4 v[154:155], off
	s_waitcnt vmcnt(8)
	s_waitcnt lgkmcnt(0)
	s_barrier
	s_waitcnt lgkmcnt(0)
	v_mfma_f32_16x16x32_bf16 v[110:113], v[150:153], v[188:191], v[110:113]
	v_mfma_f32_16x16x32_bf16 v[106:109], v[164:167], v[188:191], v[106:109]
	v_mfma_f32_16x16x32_bf16 v[102:105], v[150:153], v[196:199], v[102:105]
	v_mfma_f32_16x16x32_bf16 v[98:101], v[164:167], v[196:199], v[98:101]
	v_mfma_f32_16x16x32_bf16 v[94:97], v[150:153], v[204:207], v[94:97]
	v_mfma_f32_16x16x32_bf16 v[90:93], v[164:167], v[204:207], v[90:93]
	v_mfma_f32_16x16x32_bf16 v[86:89], v[150:153], v[212:215], v[86:89]
	v_mfma_f32_16x16x32_bf16 v[82:85], v[164:167], v[212:215], v[82:85]
	v_mfma_f32_16x16x32_bf16 v[110:113], v[160:163], v[192:195], v[110:113]
	v_mfma_f32_16x16x32_bf16 v[106:109], v[168:171], v[192:195], v[106:109]
	v_mfma_f32_16x16x32_bf16 v[102:105], v[160:163], v[200:203], v[102:105]
	v_mfma_f32_16x16x32_bf16 v[98:101], v[168:171], v[200:203], v[98:101]
	v_mfma_f32_16x16x32_bf16 v[94:97], v[160:163], v[208:211], v[94:97]
	v_mfma_f32_16x16x32_bf16 v[90:93], v[168:171], v[208:211], v[90:93]
	v_mfma_f32_16x16x32_bf16 v[86:89], v[160:163], v[216:219], v[86:89]
	v_mfma_f32_16x16x32_bf16 v[82:85], v[168:171], v[216:219], v[82:85]
	v_mfma_f32_16x16x32_bf16 v[78:81], v[172:175], v[188:191], v[78:81]
	v_mfma_f32_16x16x32_bf16 v[74:77], v[180:183], v[188:191], v[74:77]
	v_mfma_f32_16x16x32_bf16 v[70:73], v[172:175], v[196:199], v[70:73]
	v_mfma_f32_16x16x32_bf16 v[66:69], v[180:183], v[196:199], v[66:69]
	v_mfma_f32_16x16x32_bf16 v[62:65], v[172:175], v[204:207], v[62:65]
	v_mfma_f32_16x16x32_bf16 v[58:61], v[180:183], v[204:207], v[58:61]
	v_mfma_f32_16x16x32_bf16 v[54:57], v[172:175], v[212:215], v[54:57]
	v_mfma_f32_16x16x32_bf16 v[50:53], v[180:183], v[212:215], v[50:53]
	v_mfma_f32_16x16x32_bf16 v[78:81], v[176:179], v[192:195], v[78:81]
	v_mfma_f32_16x16x32_bf16 v[74:77], v[184:187], v[192:195], v[74:77]
	v_mfma_f32_16x16x32_bf16 v[70:73], v[176:179], v[200:203], v[70:73]
	v_mfma_f32_16x16x32_bf16 v[66:69], v[184:187], v[200:203], v[66:69]
	v_mfma_f32_16x16x32_bf16 v[62:65], v[176:179], v[208:211], v[62:65]
	v_mfma_f32_16x16x32_bf16 v[58:61], v[184:187], v[208:211], v[58:61]
	v_mfma_f32_16x16x32_bf16 v[54:57], v[176:179], v[216:219], v[54:57]
	v_mfma_f32_16x16x32_bf16 v[50:53], v[184:187], v[216:219], v[50:53]
	s_barrier
	s_add_i32 s70, s54, s49
	v_lshl_add_u64 v[154:155], s[42:43], 0, v[132:133]
	s_mov_b32 m0, s70
	ds_read_b128 v[188:191], v159 offset:16384
	ds_read_b128 v[192:195], v159 offset:17408
	ds_read_b128 v[196:199], v159 offset:18432
	ds_read_b128 v[200:203], v159 offset:19456
	ds_read_b128 v[204:207], v159 offset:20480
	ds_read_b128 v[208:211], v159 offset:21504
	ds_read_b128 v[212:215], v159 offset:22528
	ds_read_b128 v[216:219], v159 offset:23552
	global_load_lds_dwordx4 v[154:155], off
	s_add_i32 m0, s70, 0x2000
	s_add_u32 s70, s42, 0x40000
	v_lshl_add_u64 v[220:221], s[42:43], 0, v[136:137]
	s_addc_u32 s71, s43, 0
	s_add_i32 s72, s55, s49
	global_load_lds_dwordx4 v[220:221], off
	v_lshl_add_u64 v[222:223], s[70:71], 0, v[132:133]
	s_mov_b32 m0, s72
	v_lshl_add_u64 v[224:225], s[44:45], 0, v[134:135]
	global_load_lds_dwordx4 v[222:223], off
	v_lshl_add_u64 v[222:223], s[70:71], 0, v[136:137]
	s_add_i32 m0, s72, 0x2000
	s_nop 0
	global_load_lds_dwordx4 v[222:223], off
	v_lshl_add_u64 v[222:223], s[44:45], 0, v[130:131]
	s_mov_b32 m0, s17
	s_nop 0
	global_load_lds_dwordx4 v[222:223], off
	s_mov_b32 m0, s19
	s_nop 0
	global_load_lds_dwordx4 v[224:225], off
	s_waitcnt vmcnt(8)
	s_waitcnt lgkmcnt(0)
	s_barrier
; #define PG8_STAGEA(bufoff, gbase) PG8_STAGE_(bufoff, gbase, voffA)
; #define PG8_LDA(dst, b, h) do { _Pragma("unroll") for (int m = 0; m < 4; ++m) _Pragma("unroll") for (int k = 0; k < 2; ++k) dst[m][k] = *(const LAS bf16x8*)(lds + PG8_SA(b, h) + aoff + m * 2048 + k * 1024); } while (0)
; #define PG8_LDB(dst, b, h) do { _Pragma("unroll") for (int n = 0; n < 2; ++n) _Pragma("unroll") for (int k = 0; k < 2; ++k) dst[n][k] = *(const LAS bf16x8*)(lds + PG8_SB(b, h) + boff + n * 2048 + k * 1024); } while (0)
; #define PG8_MMA(ai, bj, At, Bt_) do { __builtin_amdgcn_s_setprio(1); _Pragma("unroll") for (int m = 0; m < 4; ++m) _Pragma("unroll") for (int n = 0; n < 2; ++n) _Pragma("unroll") for (int k = 0; k < 2; ++k) \
;         acc[ai][bj][m][n] = __builtin_amdgcn_mfma_f32_16x16x32_bf16(Bt_[n][k], At[m][k], acc[ai][bj][m][n], 0, 0, 0); __builtin_amdgcn_s_setprio(0); } while (0)
; #define PG8_WAIT_V(n) asm volatile("s_waitcnt vmcnt(" #n ")" ::: "memory")
; #define PG8_WAIT_L(n) asm volatile("s_waitcnt lgkmcnt(" #n ")" ::: "memory")
; #define PG8_BAR __builtin_amdgcn_s_barrier()
; #define PG8_SCHED __builtin_amdgcn_sched_barrier(0)
; template <int EK, int SK = -1>
; __device__ __forceinline__ void gemm_phase(LAS unsigned char* lds, const bf16_t* A, const bf16_t* Bt, int nM, int N, int K, const EpiArgs& E) {
;     ...
;             PG8_WAIT_V(8); PG8_WAIT_L(0); PG8_BAR; PG8_MMA(1, 0, At, B0); PG8_MMA(1, 1, At, B1); PG8_BAR; PG8_SCHED;
;             PG8_LDB(B0, 1, 0); PG8_LDB(B1, 1, 1); PG8_SCHED; PG8_LDA(At, 1, 0); PG8_STAGEA(PG8_SA(0, 1), a2 + hstep);
;             PG8_WAIT_V(8); PG8_WAIT_L(0); PG8_BAR; PG8_MMA(0, 0, At, B0); PG8_MMA(0, 1, At, B1); PG8_BAR; PG8_SCHED;
	s_waitcnt lgkmcnt(0)
	v_mfma_f32_16x16x32_bf16 v[46:49], v[150:153], v[188:191], v[46:49]
	v_mfma_f32_16x16x32_bf16 v[42:45], v[164:167], v[188:191], v[42:45]
	v_mfma_f32_16x16x32_bf16 v[38:41], v[150:153], v[196:199], v[38:41]
	v_mfma_f32_16x16x32_bf16 v[34:37], v[164:167], v[196:199], v[34:37]
	v_mfma_f32_16x16x32_bf16 v[30:33], v[150:153], v[204:207], v[30:33]
	v_mfma_f32_16x16x32_bf16 v[26:29], v[164:167], v[204:207], v[26:29]
	v_mfma_f32_16x16x32_bf16 v[22:25], v[150:153], v[212:215], v[22:25]
	v_mfma_f32_16x16x32_bf16 v[18:21], v[164:167], v[212:215], v[18:21]
	v_mfma_f32_16x16x32_bf16 v[46:49], v[160:163], v[192:195], v[46:49]
	v_mfma_f32_16x16x32_bf16 v[42:45], v[168:171], v[192:195], v[42:45]
	v_mfma_f32_16x16x32_bf16 v[38:41], v[160:163], v[200:203], v[38:41]
	v_mfma_f32_16x16x32_bf16 v[34:37], v[168:171], v[200:203], v[34:37]
	v_mfma_f32_16x16x32_bf16 v[30:33], v[160:163], v[208:211], v[30:33]
	v_mfma_f32_16x16x32_bf16 v[26:29], v[168:171], v[208:211], v[26:29]
	v_mfma_f32_16x16x32_bf16 v[22:25], v[160:163], v[216:219], v[22:25]
	v_mfma_f32_16x16x32_bf16 v[18:21], v[168:171], v[216:219], v[18:21]
	v_mfma_f32_16x16x32_bf16 v[14:17], v[172:175], v[188:191], v[14:17]
	v_mfma_f32_16x16x32_bf16 v[10:13], v[180:183], v[188:191], v[10:13]
	v_mfma_f32_16x16x32_bf16 v[6:9], v[172:175], v[196:199], v[6:9]
	v_mfma_f32_16x16x32_bf16 v[2:5], v[180:183], v[196:199], v[2:5]
	v_mfma_f32_16x16x32_bf16 v[114:117], v[172:175], v[204:207], v[114:117]
	v_mfma_f32_16x16x32_bf16 v[118:121], v[180:183], v[204:207], v[118:121]
	v_mfma_f32_16x16x32_bf16 v[122:125], v[172:175], v[212:215], v[122:125]
	v_mfma_f32_16x16x32_bf16 v[126:129], v[180:183], v[212:215], v[126:129]
	v_mfma_f32_16x16x32_bf16 v[14:17], v[176:179], v[192:195], v[14:17]
	v_mfma_f32_16x16x32_bf16 v[10:13], v[184:187], v[192:195], v[10:13]
	v_mfma_f32_16x16x32_bf16 v[6:9], v[176:179], v[200:203], v[6:9]
	v_mfma_f32_16x16x32_bf16 v[2:5], v[184:187], v[200:203], v[2:5]
	v_mfma_f32_16x16x32_bf16 v[114:117], v[176:179], v[208:211], v[114:117]
	v_mfma_f32_16x16x32_bf16 v[118:121], v[184:187], v[208:211], v[118:121]
	v_mfma_f32_16x16x32_bf16 v[122:125], v[176:179], v[216:219], v[122:125]
	v_mfma_f32_16x16x32_bf16 v[126:129], v[184:187], v[216:219], v[126:129]
	s_barrier
	s_add_i32 s70, 0, 0x18000
	s_add_i32 s71, 0, 0x1c000
	v_add_u32_e32 v168, s70, v156
	v_add_u32_e32 v184, s71, v156
	ds_read_b128 v[150:153], v168
	ds_read_b128 v[160:163], v168 offset:1024
	ds_read_b128 v[164:167], v168 offset:2048
	ds_read_b128 v[168:171], v168 offset:3072
	ds_read_b128 v[172:175], v184
	ds_read_b128 v[176:179], v184 offset:1024
	ds_read_b128 v[180:183], v184 offset:2048
	ds_read_b128 v[184:187], v184 offset:3072
	s_add_u32 s44, s44, 0x40000
	s_addc_u32 s45, s45, 0
	s_mov_b32 m0, s50
	v_lshl_add_u64 v[226:227], s[44:45], 0, v[130:131]
	ds_read_b128 v[188:191], v159 offset:32768
	ds_read_b128 v[192:195], v159 offset:33792
	ds_read_b128 v[196:199], v159 offset:34816
	ds_read_b128 v[200:203], v159 offset:35840
	ds_read_b128 v[204:207], v159 offset:36864
	ds_read_b128 v[208:211], v159 offset:37888
	ds_read_b128 v[212:215], v159 offset:38912
	ds_read_b128 v[216:219], v159 offset:39936
	global_load_lds_dwordx4 v[226:227], off
	v_lshl_add_u64 v[226:227], s[44:45], 0, v[134:135]
	s_mov_b32 m0, s51
	s_nop 0
	global_load_lds_dwordx4 v[226:227], off
	s_waitcnt vmcnt(8)
	s_waitcnt lgkmcnt(0)
	s_barrier
	s_waitcnt lgkmcnt(0)
	v_mfma_f32_16x16x32_bf16 v[110:113], v[150:153], v[188:191], v[110:113]
	v_mfma_f32_16x16x32_bf16 v[106:109], v[164:167], v[188:191], v[106:109]
	v_mfma_f32_16x16x32_bf16 v[102:105], v[150:153], v[196:199], v[102:105]
	v_mfma_f32_16x16x32_bf16 v[98:101], v[164:167], v[196:199], v[98:101]
	v_mfma_f32_16x16x32_bf16 v[94:97], v[150:153], v[204:207], v[94:97]
	v_mfma_f32_16x16x32_bf16 v[90:93], v[164:167], v[204:207], v[90:93]
	v_mfma_f32_16x16x32_bf16 v[86:89], v[150:153], v[212:215], v[86:89]
	v_mfma_f32_16x16x32_bf16 v[82:85], v[164:167], v[212:215], v[82:85]
	v_mfma_f32_16x16x32_bf16 v[110:113], v[160:163], v[192:195], v[110:113]
	v_mfma_f32_16x16x32_bf16 v[106:109], v[168:171], v[192:195], v[106:109]
	v_mfma_f32_16x16x32_bf16 v[102:105], v[160:163], v[200:203], v[102:105]
	v_mfma_f32_16x16x32_bf16 v[98:101], v[168:171], v[200:203], v[98:101]
	v_mfma_f32_16x16x32_bf16 v[94:97], v[160:163], v[208:211], v[94:97]
	v_mfma_f32_16x16x32_bf16 v[90:93], v[168:171], v[208:211], v[90:93]
	v_mfma_f32_16x16x32_bf16 v[86:89], v[160:163], v[216:219], v[86:89]
	v_mfma_f32_16x16x32_bf16 v[82:85], v[168:171], v[216:219], v[82:85]
	v_mfma_f32_16x16x32_bf16 v[78:81], v[172:175], v[188:191], v[78:81]
	v_mfma_f32_16x16x32_bf16 v[74:77], v[180:183], v[188:191], v[74:77]
	v_mfma_f32_16x16x32_bf16 v[70:73], v[172:175], v[196:199], v[70:73]
	v_mfma_f32_16x16x32_bf16 v[66:69], v[180:183], v[196:199], v[66:69]
	v_mfma_f32_16x16x32_bf16 v[62:65], v[172:175], v[204:207], v[62:65]
	v_mfma_f32_16x16x32_bf16 v[58:61], v[180:183], v[204:207], v[58:61]
	v_mfma_f32_16x16x32_bf16 v[54:57], v[172:175], v[212:215], v[54:57]
	v_mfma_f32_16x16x32_bf16 v[50:53], v[180:183], v[212:215], v[50:53]
	v_mfma_f32_16x16x32_bf16 v[78:81], v[176:179], v[192:195], v[78:81]
	v_mfma_f32_16x16x32_bf16 v[74:77], v[184:187], v[192:195], v[74:77]
	v_mfma_f32_16x16x32_bf16 v[70:73], v[176:179], v[200:203], v[70:73]
	v_mfma_f32_16x16x32_bf16 v[66:69], v[184:187], v[200:203], v[66:69]
	v_mfma_f32_16x16x32_bf16 v[62:65], v[176:179], v[208:211], v[62:65]
	v_mfma_f32_16x16x32_bf16 v[58:61], v[184:187], v[208:211], v[58:61]
	v_mfma_f32_16x16x32_bf16 v[54:57], v[176:179], v[216:219], v[54:57]
	v_mfma_f32_16x16x32_bf16 v[50:53], v[184:187], v[216:219], v[50:53]
	s_barrier
; #define PG8_STAGEA(bufoff, gbase) PG8_STAGE_(bufoff, gbase, voffA)
; #define PG8_STAGEB(bufoff, gbase) PG8_STAGE_(bufoff, gbase, voffB)
; #define PG8_LDA(dst, b, h) do { _Pragma("unroll") for (int m = 0; m < 4; ++m) _Pragma("unroll") for (int k = 0; k < 2; ++k) dst[m][k] = *(const LAS bf16x8*)(lds + PG8_SA(b, h) + aoff + m * 2048 + k * 1024); } while (0)
; #define PG8_MMA(ai, bj, At, Bt_) do { __builtin_amdgcn_s_setprio(1); _Pragma("unroll") for (int m = 0; m < 4; ++m) _Pragma("unroll") for (int n = 0; n < 2; ++n) _Pragma("unroll") for (int k = 0; k < 2; ++k) \
;         acc[ai][bj][m][n] = __builtin_amdgcn_mfma_f32_16x16x32_bf16(Bt_[n][k], At[m][k], acc[ai][bj][m][n], 0, 0, 0); __builtin_amdgcn_s_setprio(0); } while (0)
; #define PG8_WAIT_V(n) asm volatile("s_waitcnt vmcnt(" #n ")" ::: "memory")
; #define PG8_WAIT_L(n) asm volatile("s_waitcnt lgkmcnt(" #n ")" ::: "memory")
; #define PG8_BAR __builtin_amdgcn_s_barrier()
; #define PG8_SCHED __builtin_amdgcn_sched_barrier(0)
; template <int EK, int SK = -1>
; __device__ __forceinline__ void gemm_phase(LAS unsigned char* lds, const bf16_t* A, const bf16_t* Bt, int nM, int N, int K, const EpiArgs& E) {
;     ...
;             PG8_LDA(At, 1, 1); PG8_STAGEB(PG8_SB(1, 0), b3); PG8_STAGEB(PG8_SB(1, 1), b3 + hstep); PG8_STAGEA(PG8_SA(1, 0), a3);
;             PG8_WAIT_V(8); PG8_WAIT_L(0); PG8_BAR; PG8_MMA(1, 0, At, B0); PG8_MMA(1, 1, At, B1); PG8_BAR; PG8_SCHED;
;         }
	s_add_i32 s44, s70, s49
	v_lshl_add_u64 v[154:155], v[154:155], 0, s[10:11]
	s_mov_b32 m0, s44
	ds_read_b128 v[188:191], v159 offset:49152
	ds_read_b128 v[192:195], v159 offset:50176
	ds_read_b128 v[196:199], v159 offset:51200
	ds_read_b128 v[200:203], v159 offset:52224
	ds_read_b128 v[204:207], v159 offset:53248
	ds_read_b128 v[208:211], v159 offset:54272
	ds_read_b128 v[212:215], v159 offset:55296
	ds_read_b128 v[216:219], v159 offset:56320
	global_load_lds_dwordx4 v[154:155], off
	s_add_i32 m0, s44, 0x2000
	s_add_u32 s42, s42, 0x40080
	v_lshl_add_u64 v[154:155], v[220:221], 0, s[10:11]
	s_addc_u32 s43, s43, 0
	s_add_i32 s44, s71, s49
	global_load_lds_dwordx4 v[154:155], off
	v_lshl_add_u64 v[154:155], s[42:43], 0, v[132:133]
	s_mov_b32 m0, s44
	s_nop 0
	global_load_lds_dwordx4 v[154:155], off
	v_lshl_add_u64 v[154:155], s[42:43], 0, v[136:137]
	s_add_i32 m0, s44, 0x2000
	s_nop 0
	global_load_lds_dwordx4 v[154:155], off
	v_lshl_add_u64 v[154:155], v[222:223], 0, s[10:11]
	s_mov_b32 m0, s52
	s_nop 0
	global_load_lds_dwordx4 v[154:155], off
	v_lshl_add_u64 v[154:155], v[224:225], 0, s[10:11]
	s_mov_b32 m0, s53
	s_nop 0
	global_load_lds_dwordx4 v[154:155], off
	s_waitcnt vmcnt(8)
	s_waitcnt lgkmcnt(0)
	s_barrier
	s_waitcnt lgkmcnt(0)
	v_mfma_f32_16x16x32_bf16 v[46:49], v[150:153], v[188:191], v[46:49]
	v_mfma_f32_16x16x32_bf16 v[42:45], v[164:167], v[188:191], v[42:45]
	v_mfma_f32_16x16x32_bf16 v[38:41], v[150:153], v[196:199], v[38:41]
	v_mfma_f32_16x16x32_bf16 v[34:37], v[164:167], v[196:199], v[34:37]
	v_mfma_f32_16x16x32_bf16 v[30:33], v[150:153], v[204:207], v[30:33]
	v_mfma_f32_16x16x32_bf16 v[26:29], v[164:167], v[204:207], v[26:29]
	v_mfma_f32_16x16x32_bf16 v[22:25], v[150:153], v[212:215], v[22:25]
	v_mfma_f32_16x16x32_bf16 v[18:21], v[164:167], v[212:215], v[18:21]
	v_mfma_f32_16x16x32_bf16 v[46:49], v[160:163], v[192:195], v[46:49]
	v_mfma_f32_16x16x32_bf16 v[42:45], v[168:171], v[192:195], v[42:45]
	v_mfma_f32_16x16x32_bf16 v[38:41], v[160:163], v[200:203], v[38:41]
	v_mfma_f32_16x16x32_bf16 v[34:37], v[168:171], v[200:203], v[34:37]
	v_mfma_f32_16x16x32_bf16 v[30:33], v[160:163], v[208:211], v[30:33]
	v_mfma_f32_16x16x32_bf16 v[26:29], v[168:171], v[208:211], v[26:29]
	v_mfma_f32_16x16x32_bf16 v[22:25], v[160:163], v[216:219], v[22:25]
	v_mfma_f32_16x16x32_bf16 v[18:21], v[168:171], v[216:219], v[18:21]
	v_mfma_f32_16x16x32_bf16 v[14:17], v[172:175], v[188:191], v[14:17]
	v_mfma_f32_16x16x32_bf16 v[10:13], v[180:183], v[188:191], v[10:13]
	v_mfma_f32_16x16x32_bf16 v[6:9], v[172:175], v[196:199], v[6:9]
	v_mfma_f32_16x16x32_bf16 v[2:5], v[180:183], v[196:199], v[2:5]
	v_mfma_f32_16x16x32_bf16 v[114:117], v[172:175], v[204:207], v[114:117]
	v_mfma_f32_16x16x32_bf16 v[118:121], v[180:183], v[204:207], v[118:121]
	v_mfma_f32_16x16x32_bf16 v[122:125], v[172:175], v[212:215], v[122:125]
	v_mfma_f32_16x16x32_bf16 v[126:129], v[180:183], v[212:215], v[126:129]
	v_mfma_f32_16x16x32_bf16 v[14:17], v[176:179], v[192:195], v[14:17]
	v_mfma_f32_16x16x32_bf16 v[10:13], v[184:187], v[192:195], v[10:13]
	v_mfma_f32_16x16x32_bf16 v[6:9], v[176:179], v[200:203], v[6:9]
	v_mfma_f32_16x16x32_bf16 v[2:5], v[184:187], v[200:203], v[2:5]
	v_mfma_f32_16x16x32_bf16 v[114:117], v[176:179], v[208:211], v[114:117]
	v_mfma_f32_16x16x32_bf16 v[118:121], v[184:187], v[208:211], v[118:121]
	v_mfma_f32_16x16x32_bf16 v[122:125], v[176:179], v[216:219], v[122:125]
	v_mfma_f32_16x16x32_bf16 v[126:129], v[184:187], v[216:219], v[126:129]
	s_barrier
	s_add_i32 s69, s69, 2
	s_add_u32 s40, s40, 0x100
	s_addc_u32 s41, s41, 0
	s_cmp_gt_u32 s69, 13
	s_cbranch_scc0 .LBB0_1245
	s_and_b64 vcc, exec, s[12:13]
	s_cbranch_vccz .LBB0_1248
	s_barrier

; __device__ __forceinline__ unsigned xb_add(unsigned* p, unsigned v) { return __hip_atomic_fetch_add(p, v, __ATOMIC_RELAXED, __HIP_MEMORY_SCOPE_AGENT); }
; __device__ __forceinline__ void xcd_barrier(const XcdBarrier& b) {
;     asm volatile("s_waitcnt vmcnt(0)" ::: "memory");
;     __syncthreads();
;     if (threadIdx.x == 0) {
;         unsigned* bar = b.bar;
;         __builtin_amdgcn_s_waitcnt(0);
;         unsigned nloc = b.st[0], nx = b.st[1];
;         if (nloc == 0u) { xcd_barrier_complete(bar, b.x, nloc, nx); b.st[0] = nloc; b.st[1] = nx; }
;         const unsigned old = xb_add(&bar[XB_XSUB(b.x)], 1u);
;         const unsigned gen = old / nloc;
;         if (old + 1u == (gen + 1u) * nloc) {
.LBB0_1253:
	s_cmp_gt_i32 s35, 10
	s_cselect_b64 s[4:5], -1, 0
	s_and_b64 s[6:7], s[14:15], s[4:5]
	s_andn2_b64 vcc, exec, s[6:7]
	s_cbranch_vccnz .LBB0_1303
	s_waitcnt vmcnt(0)
	v_cmp_eq_u32_e32 vcc, 0, v0
	s_waitcnt vmcnt(0) lgkmcnt(0)
	s_barrier
	v_readfirstlane_b32 s98, v0
	s_nop 3
	s_lshr_b32 s98, s98, 6
	s_cmp_lg_u32 s98, 1
	s_cbranch_scc1 .Lmy_noinv10
	buffer_inv sc1
	s_waitcnt vmcnt(0)

; #define PG8_STAGEA(bufoff, gbase) PG8_STAGE_(bufoff, gbase, voffA)
; #define PG8_STAGEB(bufoff, gbase) PG8_STAGE_(bufoff, gbase, voffB)
; #define PG8_LDA(dst, b, h) do { _Pragma("unroll") for (int m = 0; m < 4; ++m) _Pragma("unroll") for (int k = 0; k < 2; ++k) dst[m][k] = *(const LAS bf16x8*)(lds + PG8_SA(b, h) + aoff + m * 2048 + k * 1024); } while (0)
; #define PG8_LDB(dst, b, h) do { _Pragma("unroll") for (int n = 0; n < 2; ++n) _Pragma("unroll") for (int k = 0; k < 2; ++k) dst[n][k] = *(const LAS bf16x8*)(lds + PG8_SB(b, h) + boff + n * 2048 + k * 1024); } while (0)
; #define PG8_MMA(ai, bj, At, Bt_) do { __builtin_amdgcn_s_setprio(1); _Pragma("unroll") for (int m = 0; m < 4; ++m) _Pragma("unroll") for (int n = 0; n < 2; ++n) _Pragma("unroll") for (int k = 0; k < 2; ++k) \
;         acc[ai][bj][m][n] = __builtin_amdgcn_mfma_f32_16x16x32_bf16(Bt_[n][k], At[m][k], acc[ai][bj][m][n], 0, 0, 0); __builtin_amdgcn_s_setprio(0); } while (0)
; #define PG8_WAIT_V(n) asm volatile("s_waitcnt vmcnt(" #n ")" ::: "memory")
; #define PG8_WAIT_L(n) asm volatile("s_waitcnt lgkmcnt(" #n ")" ::: "memory")
; #define PG8_BAR __builtin_amdgcn_s_barrier()
; #define PG8_SCHED __builtin_amdgcn_sched_barrier(0)
; template <int EK, int SK = -1>
; __device__ __forceinline__ void gemm_phase(LAS unsigned char* lds, const bf16_t* A, const bf16_t* Bt, int nM, int N, int K, const EpiArgs& E) {
;     ...
;         for (int t = 0; t < nt; t += 2) {
;             const bool last = (t == nt - 2);
;             const char* a1 = cA + (size_t)(t + 1) * kstep;
;             const char* a2 = last ? nA : cA + (size_t)(t + 2) * kstep; const char* b2 = last ? nB : cB + (size_t)(t + 2) * kstep;
;             const char* a3 = a2 + kstep; const char* b3 = b2 + kstep;
;             PG8_LDB(B0, 0, 0); PG8_LDB(B1, 0, 1); PG8_SCHED; PG8_LDA(At, 0, 0); PG8_STAGEA(PG8_SA(1, 1), a1 + hstep);
;             PG8_WAIT_V(8); PG8_WAIT_L(0); PG8_BAR; PG8_MMA(0, 0, At, B0); PG8_MMA(0, 1, At, B1); PG8_BAR; PG8_SCHED;
;             PG8_LDA(At, 0, 1); PG8_STAGEB(PG8_SB(0, 0), b2); PG8_STAGEB(PG8_SB(0, 1), b2 + hstep); PG8_STAGEA(PG8_SA(0, 0), a2);
;             PG8_WAIT_V(8); PG8_WAIT_L(0); PG8_BAR; PG8_MMA(1, 0, At, B0); PG8_MMA(1, 1, At, B1); PG8_BAR; PG8_SCHED;
.LBB0_1338:
	v_add_u32_e32 v150, s67, v152
	ds_read_b128 v[156:159], v150
	ds_read_b128 v[160:163], v150 offset:1024
	ds_read_b128 v[164:167], v150 offset:2048
	ds_read_b128 v[168:171], v150 offset:3072
	v_add_u32_e32 v150, s68, v152
	s_add_u32 s44, s20, s42
	ds_read_b128 v[172:175], v150
	ds_read_b128 v[176:179], v150 offset:1024
	ds_read_b128 v[180:183], v150 offset:2048
	ds_read_b128 v[184:187], v150 offset:3072
	s_addc_u32 s45, s21, s43
	s_add_u32 s44, s44, 0x100
	s_addc_u32 s45, s45, 0
	s_add_u32 s75, s73, s42
	s_addc_u32 s76, s74, s43
	s_cmpk_eq_i32 s42, 0x1500
	s_cselect_b32 s47, s41, s45
	s_cselect_b32 s46, s40, s44
	s_cselect_b32 s45, s9, s76
	s_cselect_b32 s44, s8, s75
	v_lshl_add_u64 v[150:151], v[146:147], 0, s[42:43]
	s_add_i32 m0, s53, 0xc000
	ds_read_b128 v[188:191], v154
	ds_read_b128 v[192:195], v154 offset:1024
	ds_read_b128 v[196:199], v154 offset:2048
	ds_read_b128 v[200:203], v154 offset:3072
	ds_read_b128 v[204:207], v154 offset:4096
	ds_read_b128 v[208:211], v154 offset:5120
	ds_read_b128 v[212:215], v154 offset:6144
	ds_read_b128 v[216:219], v154 offset:7168
	global_load_lds_dwordx4 v[150:151], off
	v_lshl_add_u64 v[150:151], v[148:149], 0, s[42:43]
	s_add_i32 m0, s53, 0xe000
	s_nop 0
	global_load_lds_dwordx4 v[150:151], off
	s_waitcnt vmcnt(8)
	s_waitcnt lgkmcnt(0)
	s_barrier
	s_waitcnt lgkmcnt(0)
	v_mfma_f32_16x16x32_bf16 v[126:129], v[156:159], v[188:191], v[126:129]
	v_mfma_f32_16x16x32_bf16 v[122:125], v[164:167], v[188:191], v[122:125]
	v_mfma_f32_16x16x32_bf16 v[118:121], v[156:159], v[196:199], v[118:121]
	v_mfma_f32_16x16x32_bf16 v[114:117], v[164:167], v[196:199], v[114:117]
	v_mfma_f32_16x16x32_bf16 v[110:113], v[156:159], v[204:207], v[110:113]
	v_mfma_f32_16x16x32_bf16 v[106:109], v[164:167], v[204:207], v[106:109]
	v_mfma_f32_16x16x32_bf16 v[102:105], v[156:159], v[212:215], v[102:105]
	v_mfma_f32_16x16x32_bf16 v[98:101], v[164:167], v[212:215], v[98:101]
	v_mfma_f32_16x16x32_bf16 v[126:129], v[160:163], v[192:195], v[126:129]
	v_mfma_f32_16x16x32_bf16 v[122:125], v[168:171], v[192:195], v[122:125]
	v_mfma_f32_16x16x32_bf16 v[118:121], v[160:163], v[200:203], v[118:121]
	v_mfma_f32_16x16x32_bf16 v[114:117], v[168:171], v[200:203], v[114:117]
	v_mfma_f32_16x16x32_bf16 v[110:113], v[160:163], v[208:211], v[110:113]
	v_mfma_f32_16x16x32_bf16 v[106:109], v[168:171], v[208:211], v[106:109]
	v_mfma_f32_16x16x32_bf16 v[102:105], v[160:163], v[216:219], v[102:105]
	v_mfma_f32_16x16x32_bf16 v[98:101], v[168:171], v[216:219], v[98:101]
	v_mfma_f32_16x16x32_bf16 v[94:97], v[172:175], v[188:191], v[94:97]
	v_mfma_f32_16x16x32_bf16 v[90:93], v[180:183], v[188:191], v[90:93]
	v_mfma_f32_16x16x32_bf16 v[86:89], v[172:175], v[196:199], v[86:89]
	v_mfma_f32_16x16x32_bf16 v[82:85], v[180:183], v[196:199], v[82:85]
	v_mfma_f32_16x16x32_bf16 v[78:81], v[172:175], v[204:207], v[78:81]
	v_mfma_f32_16x16x32_bf16 v[74:77], v[180:183], v[204:207], v[74:77]
	v_mfma_f32_16x16x32_bf16 v[70:73], v[172:175], v[212:215], v[70:73]
	v_mfma_f32_16x16x32_bf16 v[66:69], v[180:183], v[212:215], v[66:69]
	v_mfma_f32_16x16x32_bf16 v[94:97], v[176:179], v[192:195], v[94:97]
	v_mfma_f32_16x16x32_bf16 v[90:93], v[184:187], v[192:195], v[90:93]
	v_mfma_f32_16x16x32_bf16 v[86:89], v[176:179], v[200:203], v[86:89]
	v_mfma_f32_16x16x32_bf16 v[82:85], v[184:187], v[200:203], v[82:85]
	v_mfma_f32_16x16x32_bf16 v[78:81], v[176:179], v[208:211], v[78:81]
	v_mfma_f32_16x16x32_bf16 v[74:77], v[184:187], v[208:211], v[74:77]
	v_mfma_f32_16x16x32_bf16 v[70:73], v[176:179], v[216:219], v[70:73]
	v_mfma_f32_16x16x32_bf16 v[66:69], v[184:187], v[216:219], v[66:69]
	s_barrier
	s_add_i32 s75, s67, s52
	v_lshl_add_u64 v[150:151], s[44:45], 0, v[132:133]
	s_mov_b32 m0, s75
	ds_read_b128 v[188:191], v154 offset:16384
	ds_read_b128 v[192:195], v154 offset:17408
	ds_read_b128 v[196:199], v154 offset:18432
	ds_read_b128 v[200:203], v154 offset:19456
	ds_read_b128 v[204:207], v154 offset:20480
	ds_read_b128 v[208:211], v154 offset:21504
	ds_read_b128 v[212:215], v154 offset:22528
	ds_read_b128 v[216:219], v154 offset:23552
	global_load_lds_dwordx4 v[150:151], off
	s_add_i32 m0, s75, 0x2000
	s_add_u32 s76, s44, 0xb0000
	v_lshl_add_u64 v[220:221], s[44:45], 0, v[136:137]
	s_addc_u32 s77, s45, 0
	s_add_i32 s75, s68, s52
	global_load_lds_dwordx4 v[220:221], off
	v_lshl_add_u64 v[222:223], s[76:77], 0, v[132:133]
	s_mov_b32 m0, s75
	v_lshl_add_u64 v[224:225], s[46:47], 0, v[134:135]
	global_load_lds_dwordx4 v[222:223], off
	v_lshl_add_u64 v[222:223], s[76:77], 0, v[136:137]
	s_add_i32 m0, s75, 0x2000
	s_nop 0
	global_load_lds_dwordx4 v[222:223], off
	v_lshl_add_u64 v[222:223], s[46:47], 0, v[130:131]
	s_mov_b32 m0, s53
	s_nop 0
	global_load_lds_dwordx4 v[222:223], off
	s_mov_b32 m0, s54
	s_nop 0
	global_load_lds_dwordx4 v[224:225], off
	s_waitcnt vmcnt(8)
	s_waitcnt lgkmcnt(0)
	s_barrier
; #define PG8_STAGEA(bufoff, gbase) PG8_STAGE_(bufoff, gbase, voffA)
; #define PG8_STAGEB(bufoff, gbase) PG8_STAGE_(bufoff, gbase, voffB)
; #define PG8_LDA(dst, b, h) do { _Pragma("unroll") for (int m = 0; m < 4; ++m) _Pragma("unroll") for (int k = 0; k < 2; ++k) dst[m][k] = *(const LAS bf16x8*)(lds + PG8_SA(b, h) + aoff + m * 2048 + k * 1024); } while (0)
; #define PG8_LDB(dst, b, h) do { _Pragma("unroll") for (int n = 0; n < 2; ++n) _Pragma("unroll") for (int k = 0; k < 2; ++k) dst[n][k] = *(const LAS bf16x8*)(lds + PG8_SB(b, h) + boff + n * 2048 + k * 1024); } while (0)
; #define PG8_MMA(ai, bj, At, Bt_) do { __builtin_amdgcn_s_setprio(1); _Pragma("unroll") for (int m = 0; m < 4; ++m) _Pragma("unroll") for (int n = 0; n < 2; ++n) _Pragma("unroll") for (int k = 0; k < 2; ++k) \
;         acc[ai][bj][m][n] = __builtin_amdgcn_mfma_f32_16x16x32_bf16(Bt_[n][k], At[m][k], acc[ai][bj][m][n], 0, 0, 0); __builtin_amdgcn_s_setprio(0); } while (0)
; #define PG8_WAIT_V(n) asm volatile("s_waitcnt vmcnt(" #n ")" ::: "memory")
; #define PG8_WAIT_L(n) asm volatile("s_waitcnt lgkmcnt(" #n ")" ::: "memory")
; #define PG8_BAR __builtin_amdgcn_s_barrier()
; #define PG8_SCHED __builtin_amdgcn_sched_barrier(0)
; template <int EK, int SK = -1>
; __device__ __forceinline__ void gemm_phase(LAS unsigned char* lds, const bf16_t* A, const bf16_t* Bt, int nM, int N, int K, const EpiArgs& E) {
;     ...
;             PG8_WAIT_V(8); PG8_WAIT_L(0); PG8_BAR; PG8_MMA(1, 0, At, B0); PG8_MMA(1, 1, At, B1); PG8_BAR; PG8_SCHED;
;             PG8_LDB(B0, 1, 0); PG8_LDB(B1, 1, 1); PG8_SCHED; PG8_LDA(At, 1, 0); PG8_STAGEA(PG8_SA(0, 1), a2 + hstep);
;             PG8_WAIT_V(8); PG8_WAIT_L(0); PG8_BAR; PG8_MMA(0, 0, At, B0); PG8_MMA(0, 1, At, B1); PG8_BAR; PG8_SCHED;
;             PG8_LDA(At, 1, 1); PG8_STAGEB(PG8_SB(1, 0), b3); PG8_STAGEB(PG8_SB(1, 1), b3 + hstep); PG8_STAGEA(PG8_SA(1, 0), a3);
	s_waitcnt lgkmcnt(0)
	v_mfma_f32_16x16x32_bf16 v[62:65], v[156:159], v[188:191], v[62:65]
	v_mfma_f32_16x16x32_bf16 v[58:61], v[164:167], v[188:191], v[58:61]
	v_mfma_f32_16x16x32_bf16 v[54:57], v[156:159], v[196:199], v[54:57]
	v_mfma_f32_16x16x32_bf16 v[50:53], v[164:167], v[196:199], v[50:53]
	v_mfma_f32_16x16x32_bf16 v[46:49], v[156:159], v[204:207], v[46:49]
	v_mfma_f32_16x16x32_bf16 v[42:45], v[164:167], v[204:207], v[42:45]
	v_mfma_f32_16x16x32_bf16 v[38:41], v[156:159], v[212:215], v[38:41]
	v_mfma_f32_16x16x32_bf16 v[34:37], v[164:167], v[212:215], v[34:37]
	v_mfma_f32_16x16x32_bf16 v[62:65], v[160:163], v[192:195], v[62:65]
	v_mfma_f32_16x16x32_bf16 v[58:61], v[168:171], v[192:195], v[58:61]
	v_mfma_f32_16x16x32_bf16 v[54:57], v[160:163], v[200:203], v[54:57]
	v_mfma_f32_16x16x32_bf16 v[50:53], v[168:171], v[200:203], v[50:53]
	v_mfma_f32_16x16x32_bf16 v[46:49], v[160:163], v[208:211], v[46:49]
	v_mfma_f32_16x16x32_bf16 v[42:45], v[168:171], v[208:211], v[42:45]
	v_mfma_f32_16x16x32_bf16 v[38:41], v[160:163], v[216:219], v[38:41]
	v_mfma_f32_16x16x32_bf16 v[34:37], v[168:171], v[216:219], v[34:37]
	v_mfma_f32_16x16x32_bf16 v[30:33], v[172:175], v[188:191], v[30:33]
	v_mfma_f32_16x16x32_bf16 v[26:29], v[180:183], v[188:191], v[26:29]
	v_mfma_f32_16x16x32_bf16 v[22:25], v[172:175], v[196:199], v[22:25]
	v_mfma_f32_16x16x32_bf16 v[18:21], v[180:183], v[196:199], v[18:21]
	v_mfma_f32_16x16x32_bf16 v[14:17], v[172:175], v[204:207], v[14:17]
	v_mfma_f32_16x16x32_bf16 v[10:13], v[180:183], v[204:207], v[10:13]
	v_mfma_f32_16x16x32_bf16 v[6:9], v[172:175], v[212:215], v[6:9]
	v_mfma_f32_16x16x32_bf16 v[2:5], v[180:183], v[212:215], v[2:5]
	v_mfma_f32_16x16x32_bf16 v[30:33], v[176:179], v[192:195], v[30:33]
	v_mfma_f32_16x16x32_bf16 v[26:29], v[184:187], v[192:195], v[26:29]
	v_mfma_f32_16x16x32_bf16 v[22:25], v[176:179], v[200:203], v[22:25]
	v_mfma_f32_16x16x32_bf16 v[18:21], v[184:187], v[200:203], v[18:21]
	v_mfma_f32_16x16x32_bf16 v[14:17], v[176:179], v[208:211], v[14:17]
	v_mfma_f32_16x16x32_bf16 v[10:13], v[184:187], v[208:211], v[10:13]
	v_mfma_f32_16x16x32_bf16 v[6:9], v[176:179], v[216:219], v[6:9]
	v_mfma_f32_16x16x32_bf16 v[2:5], v[184:187], v[216:219], v[2:5]
	s_barrier
	s_add_i32 s75, 0, 0x18000
	s_add_i32 s76, 0, 0x1c000
	v_add_u32_e32 v168, s75, v152
	v_add_u32_e32 v184, s76, v152
	ds_read_b128 v[156:159], v168
	ds_read_b128 v[160:163], v168 offset:1024
	ds_read_b128 v[164:167], v168 offset:2048
	ds_read_b128 v[168:171], v168 offset:3072
	ds_read_b128 v[172:175], v184
	ds_read_b128 v[176:179], v184 offset:1024
	ds_read_b128 v[180:183], v184 offset:2048
	ds_read_b128 v[184:187], v184 offset:3072
	s_add_u32 s46, s46, 0xb0000
	s_addc_u32 s47, s47, 0
	s_mov_b32 m0, s55
	v_lshl_add_u64 v[226:227], s[46:47], 0, v[130:131]
	ds_read_b128 v[188:191], v154 offset:32768
	ds_read_b128 v[192:195], v154 offset:33792
	ds_read_b128 v[196:199], v154 offset:34816
	ds_read_b128 v[200:203], v154 offset:35840
	ds_read_b128 v[204:207], v154 offset:36864
	ds_read_b128 v[208:211], v154 offset:37888
	ds_read_b128 v[212:215], v154 offset:38912
	ds_read_b128 v[216:219], v154 offset:39936
	global_load_lds_dwordx4 v[226:227], off
	v_lshl_add_u64 v[226:227], s[46:47], 0, v[134:135]
	s_mov_b32 m0, s56
	s_nop 0
	global_load_lds_dwordx4 v[226:227], off
	s_waitcnt vmcnt(8)
	s_waitcnt lgkmcnt(0)
	s_barrier
	s_waitcnt lgkmcnt(0)
	v_mfma_f32_16x16x32_bf16 v[126:129], v[156:159], v[188:191], v[126:129]
	v_mfma_f32_16x16x32_bf16 v[122:125], v[164:167], v[188:191], v[122:125]
	v_mfma_f32_16x16x32_bf16 v[118:121], v[156:159], v[196:199], v[118:121]
	v_mfma_f32_16x16x32_bf16 v[114:117], v[164:167], v[196:199], v[114:117]
	v_mfma_f32_16x16x32_bf16 v[110:113], v[156:159], v[204:207], v[110:113]
	v_mfma_f32_16x16x32_bf16 v[106:109], v[164:167], v[204:207], v[106:109]
	v_mfma_f32_16x16x32_bf16 v[102:105], v[156:159], v[212:215], v[102:105]
	v_mfma_f32_16x16x32_bf16 v[98:101], v[164:167], v[212:215], v[98:101]
	v_mfma_f32_16x16x32_bf16 v[126:129], v[160:163], v[192:195], v[126:129]
	v_mfma_f32_16x16x32_bf16 v[122:125], v[168:171], v[192:195], v[122:125]
	v_mfma_f32_16x16x32_bf16 v[118:121], v[160:163], v[200:203], v[118:121]
	v_mfma_f32_16x16x32_bf16 v[114:117], v[168:171], v[200:203], v[114:117]
	v_mfma_f32_16x16x32_bf16 v[110:113], v[160:163], v[208:211], v[110:113]
	v_mfma_f32_16x16x32_bf16 v[106:109], v[168:171], v[208:211], v[106:109]
	v_mfma_f32_16x16x32_bf16 v[102:105], v[160:163], v[216:219], v[102:105]
	v_mfma_f32_16x16x32_bf16 v[98:101], v[168:171], v[216:219], v[98:101]
	v_mfma_f32_16x16x32_bf16 v[94:97], v[172:175], v[188:191], v[94:97]
	v_mfma_f32_16x16x32_bf16 v[90:93], v[180:183], v[188:191], v[90:93]
	v_mfma_f32_16x16x32_bf16 v[86:89], v[172:175], v[196:199], v[86:89]
	v_mfma_f32_16x16x32_bf16 v[82:85], v[180:183], v[196:199], v[82:85]
	v_mfma_f32_16x16x32_bf16 v[78:81], v[172:175], v[204:207], v[78:81]
	v_mfma_f32_16x16x32_bf16 v[74:77], v[180:183], v[204:207], v[74:77]
	v_mfma_f32_16x16x32_bf16 v[70:73], v[172:175], v[212:215], v[70:73]
	v_mfma_f32_16x16x32_bf16 v[66:69], v[180:183], v[212:215], v[66:69]
	v_mfma_f32_16x16x32_bf16 v[94:97], v[176:179], v[192:195], v[94:97]
	v_mfma_f32_16x16x32_bf16 v[90:93], v[184:187], v[192:195], v[90:93]
	v_mfma_f32_16x16x32_bf16 v[86:89], v[176:179], v[200:203], v[86:89]
	v_mfma_f32_16x16x32_bf16 v[82:85], v[184:187], v[200:203], v[82:85]
	v_mfma_f32_16x16x32_bf16 v[78:81], v[176:179], v[208:211], v[78:81]
	v_mfma_f32_16x16x32_bf16 v[74:77], v[184:187], v[208:211], v[74:77]
	v_mfma_f32_16x16x32_bf16 v[70:73], v[176:179], v[216:219], v[70:73]
	v_mfma_f32_16x16x32_bf16 v[66:69], v[184:187], v[216:219], v[66:69]
	s_barrier
; #define PG8_STAGEA(bufoff, gbase) PG8_STAGE_(bufoff, gbase, voffA)
; #define PG8_STAGEB(bufoff, gbase) PG8_STAGE_(bufoff, gbase, voffB)
; #define PG8_LDA(dst, b, h) do { _Pragma("unroll") for (int m = 0; m < 4; ++m) _Pragma("unroll") for (int k = 0; k < 2; ++k) dst[m][k] = *(const LAS bf16x8*)(lds + PG8_SA(b, h) + aoff + m * 2048 + k * 1024); } while (0)
; #define PG8_MMA(ai, bj, At, Bt_) do { __builtin_amdgcn_s_setprio(1); _Pragma("unroll") for (int m = 0; m < 4; ++m) _Pragma("unroll") for (int n = 0; n < 2; ++n) _Pragma("unroll") for (int k = 0; k < 2; ++k) \
;         acc[ai][bj][m][n] = __builtin_amdgcn_mfma_f32_16x16x32_bf16(Bt_[n][k], At[m][k], acc[ai][bj][m][n], 0, 0, 0); __builtin_amdgcn_s_setprio(0); } while (0)
; #define PG8_WAIT_V(n) asm volatile("s_waitcnt vmcnt(" #n ")" ::: "memory")
; #define PG8_WAIT_L(n) asm volatile("s_waitcnt lgkmcnt(" #n ")" ::: "memory")
; #define PG8_BAR __builtin_amdgcn_s_barrier()
; #define PG8_SCHED __builtin_amdgcn_sched_barrier(0)
; template <int EK, int SK = -1>
; __device__ __forceinline__ void gemm_phase(LAS unsigned char* lds, const bf16_t* A, const bf16_t* Bt, int nM, int N, int K, const EpiArgs& E) {
;     ...
;             PG8_LDA(At, 1, 1); PG8_STAGEB(PG8_SB(1, 0), b3); PG8_STAGEB(PG8_SB(1, 1), b3 + hstep); PG8_STAGEA(PG8_SA(1, 0), a3);
;             PG8_WAIT_V(8); PG8_WAIT_L(0); PG8_BAR; PG8_MMA(1, 0, At, B0); PG8_MMA(1, 1, At, B1); PG8_BAR; PG8_SCHED;
;         }
;         if (wr == 0) PG8_BAR;
	s_add_i32 s46, s75, s52
	v_lshl_add_u64 v[150:151], v[150:151], 0, s[36:37]
	s_mov_b32 m0, s46
	ds_read_b128 v[188:191], v154 offset:49152
	ds_read_b128 v[192:195], v154 offset:50176
	ds_read_b128 v[196:199], v154 offset:51200
	ds_read_b128 v[200:203], v154 offset:52224
	ds_read_b128 v[204:207], v154 offset:53248
	ds_read_b128 v[208:211], v154 offset:54272
	ds_read_b128 v[212:215], v154 offset:55296
	ds_read_b128 v[216:219], v154 offset:56320
	global_load_lds_dwordx4 v[150:151], off
	s_add_i32 m0, s46, 0x2000
	s_add_u32 s44, s44, 0xb0080
	v_lshl_add_u64 v[150:151], v[220:221], 0, s[36:37]
	s_addc_u32 s45, s45, 0
	s_add_i32 s46, s76, s52
	global_load_lds_dwordx4 v[150:151], off
	v_lshl_add_u64 v[150:151], s[44:45], 0, v[132:133]
	s_mov_b32 m0, s46
	s_nop 0
	global_load_lds_dwordx4 v[150:151], off
	v_lshl_add_u64 v[150:151], s[44:45], 0, v[136:137]
	s_add_i32 m0, s46, 0x2000
	s_nop 0
	global_load_lds_dwordx4 v[150:151], off
	v_lshl_add_u64 v[150:151], v[222:223], 0, s[36:37]
	s_mov_b32 m0, s59
	s_nop 0
	global_load_lds_dwordx4 v[150:151], off
	v_lshl_add_u64 v[150:151], v[224:225], 0, s[36:37]
	s_mov_b32 m0, s66
	s_nop 0
	global_load_lds_dwordx4 v[150:151], off
	s_waitcnt vmcnt(8)
	s_waitcnt lgkmcnt(0)
	s_barrier
	s_waitcnt lgkmcnt(0)
	v_mfma_f32_16x16x32_bf16 v[62:65], v[156:159], v[188:191], v[62:65]
	v_mfma_f32_16x16x32_bf16 v[58:61], v[164:167], v[188:191], v[58:61]
	v_mfma_f32_16x16x32_bf16 v[54:57], v[156:159], v[196:199], v[54:57]
	v_mfma_f32_16x16x32_bf16 v[50:53], v[164:167], v[196:199], v[50:53]
	v_mfma_f32_16x16x32_bf16 v[46:49], v[156:159], v[204:207], v[46:49]
	v_mfma_f32_16x16x32_bf16 v[42:45], v[164:167], v[204:207], v[42:45]
	v_mfma_f32_16x16x32_bf16 v[38:41], v[156:159], v[212:215], v[38:41]
	v_mfma_f32_16x16x32_bf16 v[34:37], v[164:167], v[212:215], v[34:37]
	v_mfma_f32_16x16x32_bf16 v[62:65], v[160:163], v[192:195], v[62:65]
	v_mfma_f32_16x16x32_bf16 v[58:61], v[168:171], v[192:195], v[58:61]
	v_mfma_f32_16x16x32_bf16 v[54:57], v[160:163], v[200:203], v[54:57]
	v_mfma_f32_16x16x32_bf16 v[50:53], v[168:171], v[200:203], v[50:53]
	v_mfma_f32_16x16x32_bf16 v[46:49], v[160:163], v[208:211], v[46:49]
	v_mfma_f32_16x16x32_bf16 v[42:45], v[168:171], v[208:211], v[42:45]
	v_mfma_f32_16x16x32_bf16 v[38:41], v[160:163], v[216:219], v[38:41]
	v_mfma_f32_16x16x32_bf16 v[34:37], v[168:171], v[216:219], v[34:37]
	v_mfma_f32_16x16x32_bf16 v[30:33], v[172:175], v[188:191], v[30:33]
	v_mfma_f32_16x16x32_bf16 v[26:29], v[180:183], v[188:191], v[26:29]
	v_mfma_f32_16x16x32_bf16 v[22:25], v[172:175], v[196:199], v[22:25]
	v_mfma_f32_16x16x32_bf16 v[18:21], v[180:183], v[196:199], v[18:21]
	v_mfma_f32_16x16x32_bf16 v[14:17], v[172:175], v[204:207], v[14:17]
	v_mfma_f32_16x16x32_bf16 v[10:13], v[180:183], v[204:207], v[10:13]
	v_mfma_f32_16x16x32_bf16 v[6:9], v[172:175], v[212:215], v[6:9]
	v_mfma_f32_16x16x32_bf16 v[2:5], v[180:183], v[212:215], v[2:5]
	v_mfma_f32_16x16x32_bf16 v[30:33], v[176:179], v[192:195], v[30:33]
	v_mfma_f32_16x16x32_bf16 v[26:29], v[184:187], v[192:195], v[26:29]
	v_mfma_f32_16x16x32_bf16 v[22:25], v[176:179], v[200:203], v[22:25]
	v_mfma_f32_16x16x32_bf16 v[18:21], v[184:187], v[200:203], v[18:21]
	v_mfma_f32_16x16x32_bf16 v[14:17], v[176:179], v[208:211], v[14:17]
	v_mfma_f32_16x16x32_bf16 v[10:13], v[184:187], v[208:211], v[10:13]
	v_mfma_f32_16x16x32_bf16 v[6:9], v[176:179], v[216:219], v[6:9]
	v_mfma_f32_16x16x32_bf16 v[2:5], v[184:187], v[216:219], v[2:5]
	s_barrier
	s_add_i32 s26, s26, 2
	s_add_u32 s42, s42, 0x100
	s_addc_u32 s43, s43, 0
	s_cmp_gt_u32 s26, 41
	s_cbranch_scc0 .LBB0_1338
	s_and_b64 vcc, exec, s[38:39]
	s_cbranch_vccz .LBB0_1341
	s_barrier

; #define PG8_STAGEA(bufoff, gbase) PG8_STAGE_(bufoff, gbase, voffA)
; #define PG8_STAGEB(bufoff, gbase) PG8_STAGE_(bufoff, gbase, voffB)
; #define PG8_LDA(dst, b, h) do { _Pragma("unroll") for (int m = 0; m < 4; ++m) _Pragma("unroll") for (int k = 0; k < 2; ++k) dst[m][k] = *(const LAS bf16x8*)(lds + PG8_SA(b, h) + aoff + m * 2048 + k * 1024); } while (0)
; #define PG8_LDB(dst, b, h) do { _Pragma("unroll") for (int n = 0; n < 2; ++n) _Pragma("unroll") for (int k = 0; k < 2; ++k) dst[n][k] = *(const LAS bf16x8*)(lds + PG8_SB(b, h) + boff + n * 2048 + k * 1024); } while (0)
; #define PG8_MMA(ai, bj, At, Bt_) do { __builtin_amdgcn_s_setprio(1); _Pragma("unroll") for (int m = 0; m < 4; ++m) _Pragma("unroll") for (int n = 0; n < 2; ++n) _Pragma("unroll") for (int k = 0; k < 2; ++k) \
;         acc[ai][bj][m][n] = __builtin_amdgcn_mfma_f32_16x16x32_bf16(Bt_[n][k], At[m][k], acc[ai][bj][m][n], 0, 0, 0); __builtin_amdgcn_s_setprio(0); } while (0)
; #define PG8_WAIT_V(n) asm volatile("s_waitcnt vmcnt(" #n ")" ::: "memory")
; #define PG8_WAIT_L(n) asm volatile("s_waitcnt lgkmcnt(" #n ")" ::: "memory")
; #define PG8_BAR __builtin_amdgcn_s_barrier()
; #define PG8_SCHED __builtin_amdgcn_sched_barrier(0)
; template <int EK, int SK = -1>
; __device__ __forceinline__ void gemm_phase(LAS unsigned char* lds, const bf16_t* A, const bf16_t* Bt, int nM, int N, int K, const EpiArgs& E) {
;     ...
;         for (int t = 0; t < nt; t += 2) {
;             const bool last = (t == nt - 2);
;             const char* a1 = cA + (size_t)(t + 1) * kstep;
;             const char* a2 = last ? nA : cA + (size_t)(t + 2) * kstep; const char* b2 = last ? nB : cB + (size_t)(t + 2) * kstep;
;             const char* a3 = a2 + kstep; const char* b3 = b2 + kstep;
;             PG8_LDB(B0, 0, 0); PG8_LDB(B1, 0, 1); PG8_SCHED; PG8_LDA(At, 0, 0); PG8_STAGEA(PG8_SA(1, 1), a1 + hstep);
;             PG8_WAIT_V(8); PG8_WAIT_L(0); PG8_BAR; PG8_MMA(0, 0, At, B0); PG8_MMA(0, 1, At, B1); PG8_BAR; PG8_SCHED;
;             PG8_LDA(At, 0, 1); PG8_STAGEB(PG8_SB(0, 0), b2); PG8_STAGEB(PG8_SB(0, 1), b2 + hstep); PG8_STAGEA(PG8_SA(0, 0), a2);
;             PG8_WAIT_V(8); PG8_WAIT_L(0); PG8_BAR; PG8_MMA(1, 0, At, B0); PG8_MMA(1, 1, At, B1); PG8_BAR; PG8_SCHED;
.LBB0_1401:
	v_add_u32_e32 v168, s66, v154
	v_add_u32_e32 v184, s67, v154
	s_add_u32 s42, s20, s40
	ds_read_b128 v[156:159], v168
	ds_read_b128 v[160:163], v168 offset:1024
	ds_read_b128 v[164:167], v168 offset:2048
	ds_read_b128 v[168:171], v168 offset:3072
	ds_read_b128 v[172:175], v184
	ds_read_b128 v[176:179], v184 offset:1024
	ds_read_b128 v[180:183], v184 offset:2048
	ds_read_b128 v[184:187], v184 offset:3072
	s_addc_u32 s43, s21, s41
	s_add_u32 s42, s42, 0x100
	s_addc_u32 s43, s43, 0
	s_add_u32 s73, s37, s40
	s_addc_u32 s74, s71, s41
	s_cmpk_eq_i32 s40, 0x1500
	s_cselect_b32 s45, s7, s43
	s_cselect_b32 s44, s6, s42
	s_cselect_b32 s43, s39, s74
	s_cselect_b32 s42, s38, s73
	v_lshl_add_u64 v[220:221], v[146:147], 0, s[40:41]
	s_add_i32 m0, s53, 0xc000
	ds_read_b128 v[188:191], v155
	ds_read_b128 v[192:195], v155 offset:1024
	ds_read_b128 v[196:199], v155 offset:2048
	ds_read_b128 v[200:203], v155 offset:3072
	ds_read_b128 v[204:207], v155 offset:4096
	ds_read_b128 v[208:211], v155 offset:5120
	ds_read_b128 v[212:215], v155 offset:6144
	ds_read_b128 v[216:219], v155 offset:7168
	global_load_lds_dwordx4 v[220:221], off
	v_lshl_add_u64 v[220:221], v[148:149], 0, s[40:41]
	s_add_i32 m0, s53, 0xe000
	s_nop 0
	global_load_lds_dwordx4 v[220:221], off
	s_waitcnt vmcnt(8)
	s_waitcnt lgkmcnt(0)
	s_barrier
	s_waitcnt lgkmcnt(0)
	v_mfma_f32_16x16x32_bf16 v[126:129], v[156:159], v[188:191], v[126:129]
	v_mfma_f32_16x16x32_bf16 v[122:125], v[164:167], v[188:191], v[122:125]
	v_mfma_f32_16x16x32_bf16 v[110:113], v[156:159], v[196:199], v[110:113]
	v_mfma_f32_16x16x32_bf16 v[106:109], v[164:167], v[196:199], v[106:109]
	v_mfma_f32_16x16x32_bf16 v[94:97], v[156:159], v[204:207], v[94:97]
	v_mfma_f32_16x16x32_bf16 v[90:93], v[164:167], v[204:207], v[90:93]
	v_mfma_f32_16x16x32_bf16 v[78:81], v[156:159], v[212:215], v[78:81]
	v_mfma_f32_16x16x32_bf16 v[74:77], v[164:167], v[212:215], v[74:77]
	v_mfma_f32_16x16x32_bf16 v[126:129], v[160:163], v[192:195], v[126:129]
	v_mfma_f32_16x16x32_bf16 v[122:125], v[168:171], v[192:195], v[122:125]
	v_mfma_f32_16x16x32_bf16 v[110:113], v[160:163], v[200:203], v[110:113]
	v_mfma_f32_16x16x32_bf16 v[106:109], v[168:171], v[200:203], v[106:109]
	v_mfma_f32_16x16x32_bf16 v[94:97], v[160:163], v[208:211], v[94:97]
	v_mfma_f32_16x16x32_bf16 v[90:93], v[168:171], v[208:211], v[90:93]
	v_mfma_f32_16x16x32_bf16 v[78:81], v[160:163], v[216:219], v[78:81]
	v_mfma_f32_16x16x32_bf16 v[74:77], v[168:171], v[216:219], v[74:77]
	v_mfma_f32_16x16x32_bf16 v[118:121], v[172:175], v[188:191], v[118:121]
	v_mfma_f32_16x16x32_bf16 v[114:117], v[180:183], v[188:191], v[114:117]
	v_mfma_f32_16x16x32_bf16 v[102:105], v[172:175], v[196:199], v[102:105]
	v_mfma_f32_16x16x32_bf16 v[98:101], v[180:183], v[196:199], v[98:101]
	v_mfma_f32_16x16x32_bf16 v[86:89], v[172:175], v[204:207], v[86:89]
	v_mfma_f32_16x16x32_bf16 v[82:85], v[180:183], v[204:207], v[82:85]
	v_mfma_f32_16x16x32_bf16 v[70:73], v[172:175], v[212:215], v[70:73]
	v_mfma_f32_16x16x32_bf16 v[66:69], v[180:183], v[212:215], v[66:69]
	v_mfma_f32_16x16x32_bf16 v[118:121], v[176:179], v[192:195], v[118:121]
	v_mfma_f32_16x16x32_bf16 v[114:117], v[184:187], v[192:195], v[114:117]
	v_mfma_f32_16x16x32_bf16 v[102:105], v[176:179], v[200:203], v[102:105]
	v_mfma_f32_16x16x32_bf16 v[98:101], v[184:187], v[200:203], v[98:101]
	v_mfma_f32_16x16x32_bf16 v[86:89], v[176:179], v[208:211], v[86:89]
	v_mfma_f32_16x16x32_bf16 v[82:85], v[184:187], v[208:211], v[82:85]
	v_mfma_f32_16x16x32_bf16 v[70:73], v[176:179], v[216:219], v[70:73]
	v_mfma_f32_16x16x32_bf16 v[66:69], v[184:187], v[216:219], v[66:69]
	s_barrier
	s_add_i32 s73, s66, s52
	v_lshl_add_u64 v[220:221], s[42:43], 0, v[132:133]
	s_mov_b32 m0, s73
	ds_read_b128 v[188:191], v155 offset:16384
	ds_read_b128 v[192:195], v155 offset:17408
	ds_read_b128 v[196:199], v155 offset:18432
	ds_read_b128 v[200:203], v155 offset:19456
	ds_read_b128 v[204:207], v155 offset:20480
	ds_read_b128 v[208:211], v155 offset:21504
	ds_read_b128 v[212:215], v155 offset:22528
	ds_read_b128 v[216:219], v155 offset:23552
	global_load_lds_dwordx4 v[220:221], off
	s_add_i32 m0, s73, 0x2000
	s_add_u32 s74, s42, 0xb0000
	v_lshl_add_u64 v[222:223], s[42:43], 0, v[136:137]
	s_addc_u32 s75, s43, 0
	s_add_i32 s73, s67, s52
	global_load_lds_dwordx4 v[222:223], off
	v_lshl_add_u64 v[224:225], s[74:75], 0, v[132:133]
	s_mov_b32 m0, s73
	v_lshl_add_u64 v[226:227], s[44:45], 0, v[134:135]
	global_load_lds_dwordx4 v[224:225], off
	v_lshl_add_u64 v[224:225], s[74:75], 0, v[136:137]
	s_add_i32 m0, s73, 0x2000
	s_nop 0
	global_load_lds_dwordx4 v[224:225], off
	v_lshl_add_u64 v[224:225], s[44:45], 0, v[130:131]
	s_mov_b32 m0, s53
	s_nop 0
	global_load_lds_dwordx4 v[224:225], off
	s_mov_b32 m0, s54
	s_nop 0
	global_load_lds_dwordx4 v[226:227], off
	s_waitcnt vmcnt(8)
	s_waitcnt lgkmcnt(0)
	s_barrier
; #define PG8_STAGEA(bufoff, gbase) PG8_STAGE_(bufoff, gbase, voffA)
; #define PG8_STAGEB(bufoff, gbase) PG8_STAGE_(bufoff, gbase, voffB)
; #define PG8_LDA(dst, b, h) do { _Pragma("unroll") for (int m = 0; m < 4; ++m) _Pragma("unroll") for (int k = 0; k < 2; ++k) dst[m][k] = *(const LAS bf16x8*)(lds + PG8_SA(b, h) + aoff + m * 2048 + k * 1024); } while (0)
; #define PG8_LDB(dst, b, h) do { _Pragma("unroll") for (int n = 0; n < 2; ++n) _Pragma("unroll") for (int k = 0; k < 2; ++k) dst[n][k] = *(const LAS bf16x8*)(lds + PG8_SB(b, h) + boff + n * 2048 + k * 1024); } while (0)
; #define PG8_MMA(ai, bj, At, Bt_) do { __builtin_amdgcn_s_setprio(1); _Pragma("unroll") for (int m = 0; m < 4; ++m) _Pragma("unroll") for (int n = 0; n < 2; ++n) _Pragma("unroll") for (int k = 0; k < 2; ++k) \
;         acc[ai][bj][m][n] = __builtin_amdgcn_mfma_f32_16x16x32_bf16(Bt_[n][k], At[m][k], acc[ai][bj][m][n], 0, 0, 0); __builtin_amdgcn_s_setprio(0); } while (0)
; #define PG8_WAIT_V(n) asm volatile("s_waitcnt vmcnt(" #n ")" ::: "memory")
; #define PG8_WAIT_L(n) asm volatile("s_waitcnt lgkmcnt(" #n ")" ::: "memory")
; #define PG8_BAR __builtin_amdgcn_s_barrier()
; #define PG8_SCHED __builtin_amdgcn_sched_barrier(0)
; template <int EK, int SK = -1>
; __device__ __forceinline__ void gemm_phase(LAS unsigned char* lds, const bf16_t* A, const bf16_t* Bt, int nM, int N, int K, const EpiArgs& E) {
;     ...
;             PG8_WAIT_V(8); PG8_WAIT_L(0); PG8_BAR; PG8_MMA(1, 0, At, B0); PG8_MMA(1, 1, At, B1); PG8_BAR; PG8_SCHED;
;             PG8_LDB(B0, 1, 0); PG8_LDB(B1, 1, 1); PG8_SCHED; PG8_LDA(At, 1, 0); PG8_STAGEA(PG8_SA(0, 1), a2 + hstep);
;             PG8_WAIT_V(8); PG8_WAIT_L(0); PG8_BAR; PG8_MMA(0, 0, At, B0); PG8_MMA(0, 1, At, B1); PG8_BAR; PG8_SCHED;
;             PG8_LDA(At, 1, 1); PG8_STAGEB(PG8_SB(1, 0), b3); PG8_STAGEB(PG8_SB(1, 1), b3 + hstep); PG8_STAGEA(PG8_SA(1, 0), a3);
	s_waitcnt lgkmcnt(0)
	v_mfma_f32_16x16x32_bf16 v[62:65], v[156:159], v[188:191], v[62:65]
	v_mfma_f32_16x16x32_bf16 v[58:61], v[164:167], v[188:191], v[58:61]
	v_mfma_f32_16x16x32_bf16 v[46:49], v[156:159], v[196:199], v[46:49]
	v_mfma_f32_16x16x32_bf16 v[42:45], v[164:167], v[196:199], v[42:45]
	v_mfma_f32_16x16x32_bf16 v[30:33], v[156:159], v[204:207], v[30:33]
	v_mfma_f32_16x16x32_bf16 v[26:29], v[164:167], v[204:207], v[26:29]
	v_mfma_f32_16x16x32_bf16 v[14:17], v[156:159], v[212:215], v[14:17]
	v_mfma_f32_16x16x32_bf16 v[10:13], v[164:167], v[212:215], v[10:13]
	v_mfma_f32_16x16x32_bf16 v[62:65], v[160:163], v[192:195], v[62:65]
	v_mfma_f32_16x16x32_bf16 v[58:61], v[168:171], v[192:195], v[58:61]
	v_mfma_f32_16x16x32_bf16 v[46:49], v[160:163], v[200:203], v[46:49]
	v_mfma_f32_16x16x32_bf16 v[42:45], v[168:171], v[200:203], v[42:45]
	v_mfma_f32_16x16x32_bf16 v[30:33], v[160:163], v[208:211], v[30:33]
	v_mfma_f32_16x16x32_bf16 v[26:29], v[168:171], v[208:211], v[26:29]
	v_mfma_f32_16x16x32_bf16 v[14:17], v[160:163], v[216:219], v[14:17]
	v_mfma_f32_16x16x32_bf16 v[10:13], v[168:171], v[216:219], v[10:13]
	v_mfma_f32_16x16x32_bf16 v[54:57], v[172:175], v[188:191], v[54:57]
	v_mfma_f32_16x16x32_bf16 v[50:53], v[180:183], v[188:191], v[50:53]
	v_mfma_f32_16x16x32_bf16 v[38:41], v[172:175], v[196:199], v[38:41]
	v_mfma_f32_16x16x32_bf16 v[34:37], v[180:183], v[196:199], v[34:37]
	v_mfma_f32_16x16x32_bf16 v[22:25], v[172:175], v[204:207], v[22:25]
	v_mfma_f32_16x16x32_bf16 v[18:21], v[180:183], v[204:207], v[18:21]
	v_mfma_f32_16x16x32_bf16 v[6:9], v[172:175], v[212:215], v[6:9]
	v_mfma_f32_16x16x32_bf16 v[2:5], v[180:183], v[212:215], v[2:5]
	v_mfma_f32_16x16x32_bf16 v[54:57], v[176:179], v[192:195], v[54:57]
	v_mfma_f32_16x16x32_bf16 v[50:53], v[184:187], v[192:195], v[50:53]
	v_mfma_f32_16x16x32_bf16 v[38:41], v[176:179], v[200:203], v[38:41]
	v_mfma_f32_16x16x32_bf16 v[34:37], v[184:187], v[200:203], v[34:37]
	v_mfma_f32_16x16x32_bf16 v[22:25], v[176:179], v[208:211], v[22:25]
	v_mfma_f32_16x16x32_bf16 v[18:21], v[184:187], v[208:211], v[18:21]
	v_mfma_f32_16x16x32_bf16 v[6:9], v[176:179], v[216:219], v[6:9]
	v_mfma_f32_16x16x32_bf16 v[2:5], v[184:187], v[216:219], v[2:5]
	s_barrier
	s_add_i32 s73, 0, 0x18000
	s_add_i32 s74, 0, 0x1c000
	v_add_u32_e32 v168, s73, v154
	v_add_u32_e32 v184, s74, v154
	ds_read_b128 v[156:159], v168
	ds_read_b128 v[160:163], v168 offset:1024
	ds_read_b128 v[164:167], v168 offset:2048
	ds_read_b128 v[168:171], v168 offset:3072
	ds_read_b128 v[172:175], v184
	ds_read_b128 v[176:179], v184 offset:1024
	ds_read_b128 v[180:183], v184 offset:2048
	ds_read_b128 v[184:187], v184 offset:3072
	s_add_u32 s44, s44, 0xb0000
	s_addc_u32 s45, s45, 0
	s_mov_b32 m0, s55
	v_lshl_add_u64 v[228:229], s[44:45], 0, v[130:131]
	ds_read_b128 v[188:191], v155 offset:32768
	ds_read_b128 v[192:195], v155 offset:33792
	ds_read_b128 v[196:199], v155 offset:34816
	ds_read_b128 v[200:203], v155 offset:35840
	ds_read_b128 v[204:207], v155 offset:36864
	ds_read_b128 v[208:211], v155 offset:37888
	ds_read_b128 v[212:215], v155 offset:38912
	ds_read_b128 v[216:219], v155 offset:39936
	global_load_lds_dwordx4 v[228:229], off
	v_lshl_add_u64 v[228:229], s[44:45], 0, v[134:135]
	s_mov_b32 m0, s56
	s_nop 0
	global_load_lds_dwordx4 v[228:229], off
	s_waitcnt vmcnt(8)
	s_waitcnt lgkmcnt(0)
	s_barrier
	s_waitcnt lgkmcnt(0)
	v_mfma_f32_16x16x32_bf16 v[126:129], v[156:159], v[188:191], v[126:129]
	v_mfma_f32_16x16x32_bf16 v[122:125], v[164:167], v[188:191], v[122:125]
	v_mfma_f32_16x16x32_bf16 v[110:113], v[156:159], v[196:199], v[110:113]
	v_mfma_f32_16x16x32_bf16 v[106:109], v[164:167], v[196:199], v[106:109]
	v_mfma_f32_16x16x32_bf16 v[94:97], v[156:159], v[204:207], v[94:97]
	v_mfma_f32_16x16x32_bf16 v[90:93], v[164:167], v[204:207], v[90:93]
	v_mfma_f32_16x16x32_bf16 v[78:81], v[156:159], v[212:215], v[78:81]
	v_mfma_f32_16x16x32_bf16 v[74:77], v[164:167], v[212:215], v[74:77]
	v_mfma_f32_16x16x32_bf16 v[126:129], v[160:163], v[192:195], v[126:129]
	v_mfma_f32_16x16x32_bf16 v[122:125], v[168:171], v[192:195], v[122:125]
	v_mfma_f32_16x16x32_bf16 v[110:113], v[160:163], v[200:203], v[110:113]
	v_mfma_f32_16x16x32_bf16 v[106:109], v[168:171], v[200:203], v[106:109]
	v_mfma_f32_16x16x32_bf16 v[94:97], v[160:163], v[208:211], v[94:97]
	v_mfma_f32_16x16x32_bf16 v[90:93], v[168:171], v[208:211], v[90:93]
	v_mfma_f32_16x16x32_bf16 v[78:81], v[160:163], v[216:219], v[78:81]
	v_mfma_f32_16x16x32_bf16 v[74:77], v[168:171], v[216:219], v[74:77]
	v_mfma_f32_16x16x32_bf16 v[118:121], v[172:175], v[188:191], v[118:121]
	v_mfma_f32_16x16x32_bf16 v[114:117], v[180:183], v[188:191], v[114:117]
	v_mfma_f32_16x16x32_bf16 v[102:105], v[172:175], v[196:199], v[102:105]
	v_mfma_f32_16x16x32_bf16 v[98:101], v[180:183], v[196:199], v[98:101]
	v_mfma_f32_16x16x32_bf16 v[86:89], v[172:175], v[204:207], v[86:89]
	v_mfma_f32_16x16x32_bf16 v[82:85], v[180:183], v[204:207], v[82:85]
	v_mfma_f32_16x16x32_bf16 v[70:73], v[172:175], v[212:215], v[70:73]
	v_mfma_f32_16x16x32_bf16 v[66:69], v[180:183], v[212:215], v[66:69]
	v_mfma_f32_16x16x32_bf16 v[118:121], v[176:179], v[192:195], v[118:121]
	v_mfma_f32_16x16x32_bf16 v[114:117], v[184:187], v[192:195], v[114:117]
	v_mfma_f32_16x16x32_bf16 v[102:105], v[176:179], v[200:203], v[102:105]
	v_mfma_f32_16x16x32_bf16 v[98:101], v[184:187], v[200:203], v[98:101]
	v_mfma_f32_16x16x32_bf16 v[86:89], v[176:179], v[208:211], v[86:89]
	v_mfma_f32_16x16x32_bf16 v[82:85], v[184:187], v[208:211], v[82:85]
	v_mfma_f32_16x16x32_bf16 v[70:73], v[176:179], v[216:219], v[70:73]
	v_mfma_f32_16x16x32_bf16 v[66:69], v[184:187], v[216:219], v[66:69]
	s_barrier
; #define PG8_STAGEA(bufoff, gbase) PG8_STAGE_(bufoff, gbase, voffA)
; #define PG8_STAGEB(bufoff, gbase) PG8_STAGE_(bufoff, gbase, voffB)
; #define PG8_LDA(dst, b, h) do { _Pragma("unroll") for (int m = 0; m < 4; ++m) _Pragma("unroll") for (int k = 0; k < 2; ++k) dst[m][k] = *(const LAS bf16x8*)(lds + PG8_SA(b, h) + aoff + m * 2048 + k * 1024); } while (0)
; #define PG8_MMA(ai, bj, At, Bt_) do { __builtin_amdgcn_s_setprio(1); _Pragma("unroll") for (int m = 0; m < 4; ++m) _Pragma("unroll") for (int n = 0; n < 2; ++n) _Pragma("unroll") for (int k = 0; k < 2; ++k) \
;         acc[ai][bj][m][n] = __builtin_amdgcn_mfma_f32_16x16x32_bf16(Bt_[n][k], At[m][k], acc[ai][bj][m][n], 0, 0, 0); __builtin_amdgcn_s_setprio(0); } while (0)
; #define PG8_WAIT_V(n) asm volatile("s_waitcnt vmcnt(" #n ")" ::: "memory")
; #define PG8_WAIT_L(n) asm volatile("s_waitcnt lgkmcnt(" #n ")" ::: "memory")
; #define PG8_BAR __builtin_amdgcn_s_barrier()
; #define PG8_SCHED __builtin_amdgcn_sched_barrier(0)
; template <int EK, int SK = -1>
; __device__ __forceinline__ void gemm_phase(LAS unsigned char* lds, const bf16_t* A, const bf16_t* Bt, int nM, int N, int K, const EpiArgs& E) {
;     ...
;             PG8_LDA(At, 1, 1); PG8_STAGEB(PG8_SB(1, 0), b3); PG8_STAGEB(PG8_SB(1, 1), b3 + hstep); PG8_STAGEA(PG8_SA(1, 0), a3);
;             PG8_WAIT_V(8); PG8_WAIT_L(0); PG8_BAR; PG8_MMA(1, 0, At, B0); PG8_MMA(1, 1, At, B1); PG8_BAR; PG8_SCHED;
;         }
;         if (wr == 0) PG8_BAR;
	s_add_i32 s44, s73, s52
	v_lshl_add_u64 v[220:221], v[220:221], 0, s[22:23]
	s_mov_b32 m0, s44
	ds_read_b128 v[188:191], v155 offset:49152
	ds_read_b128 v[192:195], v155 offset:50176
	ds_read_b128 v[196:199], v155 offset:51200
	ds_read_b128 v[200:203], v155 offset:52224
	ds_read_b128 v[204:207], v155 offset:53248
	ds_read_b128 v[208:211], v155 offset:54272
	ds_read_b128 v[212:215], v155 offset:55296
	ds_read_b128 v[216:219], v155 offset:56320
	global_load_lds_dwordx4 v[220:221], off
	s_add_i32 m0, s44, 0x2000
	s_add_u32 s42, s42, 0xb0080
	v_lshl_add_u64 v[220:221], v[222:223], 0, s[22:23]
	s_addc_u32 s43, s43, 0
	s_add_i32 s44, s74, s52
	global_load_lds_dwordx4 v[220:221], off
	v_lshl_add_u64 v[220:221], s[42:43], 0, v[132:133]
	s_mov_b32 m0, s44
	s_nop 0
	global_load_lds_dwordx4 v[220:221], off
	v_lshl_add_u64 v[220:221], s[42:43], 0, v[136:137]
	s_add_i32 m0, s44, 0x2000
	s_nop 0
	global_load_lds_dwordx4 v[220:221], off
	v_lshl_add_u64 v[220:221], v[224:225], 0, s[22:23]
	s_mov_b32 m0, s58
	s_nop 0
	global_load_lds_dwordx4 v[220:221], off
	v_lshl_add_u64 v[220:221], v[226:227], 0, s[22:23]
	s_mov_b32 m0, s59
	s_nop 0
	global_load_lds_dwordx4 v[220:221], off
	s_waitcnt vmcnt(8)
	s_waitcnt lgkmcnt(0)
	s_barrier
	s_waitcnt lgkmcnt(0)
	v_mfma_f32_16x16x32_bf16 v[62:65], v[156:159], v[188:191], v[62:65]
	v_mfma_f32_16x16x32_bf16 v[58:61], v[164:167], v[188:191], v[58:61]
	v_mfma_f32_16x16x32_bf16 v[46:49], v[156:159], v[196:199], v[46:49]
	v_mfma_f32_16x16x32_bf16 v[42:45], v[164:167], v[196:199], v[42:45]
	v_mfma_f32_16x16x32_bf16 v[30:33], v[156:159], v[204:207], v[30:33]
	v_mfma_f32_16x16x32_bf16 v[26:29], v[164:167], v[204:207], v[26:29]
	v_mfma_f32_16x16x32_bf16 v[14:17], v[156:159], v[212:215], v[14:17]
	v_mfma_f32_16x16x32_bf16 v[10:13], v[164:167], v[212:215], v[10:13]
	v_mfma_f32_16x16x32_bf16 v[62:65], v[160:163], v[192:195], v[62:65]
	v_mfma_f32_16x16x32_bf16 v[58:61], v[168:171], v[192:195], v[58:61]
	v_mfma_f32_16x16x32_bf16 v[46:49], v[160:163], v[200:203], v[46:49]
	v_mfma_f32_16x16x32_bf16 v[42:45], v[168:171], v[200:203], v[42:45]
	v_mfma_f32_16x16x32_bf16 v[30:33], v[160:163], v[208:211], v[30:33]
	v_mfma_f32_16x16x32_bf16 v[26:29], v[168:171], v[208:211], v[26:29]
	v_mfma_f32_16x16x32_bf16 v[14:17], v[160:163], v[216:219], v[14:17]
	v_mfma_f32_16x16x32_bf16 v[10:13], v[168:171], v[216:219], v[10:13]
	v_mfma_f32_16x16x32_bf16 v[54:57], v[172:175], v[188:191], v[54:57]
	v_mfma_f32_16x16x32_bf16 v[50:53], v[180:183], v[188:191], v[50:53]
	v_mfma_f32_16x16x32_bf16 v[38:41], v[172:175], v[196:199], v[38:41]
	v_mfma_f32_16x16x32_bf16 v[34:37], v[180:183], v[196:199], v[34:37]
	v_mfma_f32_16x16x32_bf16 v[22:25], v[172:175], v[204:207], v[22:25]
	v_mfma_f32_16x16x32_bf16 v[18:21], v[180:183], v[204:207], v[18:21]
	v_mfma_f32_16x16x32_bf16 v[6:9], v[172:175], v[212:215], v[6:9]
	v_mfma_f32_16x16x32_bf16 v[2:5], v[180:183], v[212:215], v[2:5]
	v_mfma_f32_16x16x32_bf16 v[54:57], v[176:179], v[192:195], v[54:57]
	v_mfma_f32_16x16x32_bf16 v[50:53], v[184:187], v[192:195], v[50:53]
	v_mfma_f32_16x16x32_bf16 v[38:41], v[176:179], v[200:203], v[38:41]
	v_mfma_f32_16x16x32_bf16 v[34:37], v[184:187], v[200:203], v[34:37]
	v_mfma_f32_16x16x32_bf16 v[22:25], v[176:179], v[208:211], v[22:25]
	v_mfma_f32_16x16x32_bf16 v[18:21], v[184:187], v[208:211], v[18:21]
	v_mfma_f32_16x16x32_bf16 v[6:9], v[176:179], v[216:219], v[6:9]
	v_mfma_f32_16x16x32_bf16 v[2:5], v[184:187], v[216:219], v[2:5]
	s_barrier
	s_add_i32 s72, s72, 2
	s_add_u32 s40, s40, 0x100
	s_addc_u32 s41, s41, 0
	s_cmp_gt_u32 s72, 41
	s_cbranch_scc0 .LBB0_1401
	s_and_b64 vcc, exec, s[26:27]
	s_cbranch_vccz .LBB0_1404
	s_barrier

; __global__ void __launch_bounds__(512, 2) mega_fwd(Params p) {
;     extern __shared__ __attribute__((aligned(16))) unsigned char lds_raw[];
	.amdhsa_kernel _Z8mega_fwd6Params
		.amdhsa_group_segment_fixed_size 0
		.amdhsa_private_segment_fixed_size 0
		.amdhsa_kernarg_size 440
		.amdhsa_user_sgpr_count 2
		.amdhsa_user_sgpr_dispatch_ptr 0
		.amdhsa_user_sgpr_queue_ptr 0
		.amdhsa_user_sgpr_kernarg_segment_ptr 1
		.amdhsa_user_sgpr_dispatch_id 0
		.amdhsa_user_sgpr_kernarg_preload_length 0
		.amdhsa_user_sgpr_kernarg_preload_offset 0
		.amdhsa_user_sgpr_private_segment_size 0
		.amdhsa_uses_dynamic_stack 0
		.amdhsa_enable_private_segment 0
		.amdhsa_system_sgpr_workgroup_id_x 1
		.amdhsa_system_sgpr_workgroup_id_y 0
		.amdhsa_system_sgpr_workgroup_id_z 0
		.amdhsa_system_sgpr_workgroup_info 0
		.amdhsa_system_vgpr_workitem_id 0
		.amdhsa_next_free_vgpr 232
		.amdhsa_next_free_sgpr 100
		.amdhsa_accum_offset 232
		.amdhsa_reserve_vcc 1
		.amdhsa_float_round_mode_32 0
		.amdhsa_float_round_mode_16_64 0
		.amdhsa_float_denorm_mode_32 3
		.amdhsa_float_denorm_mode_16_64 3
		.amdhsa_dx10_clamp 1
		.amdhsa_ieee_mode 1
		.amdhsa_fp16_overflow 0
		.amdhsa_tg_split 0
		.amdhsa_exception_fp_ieee_invalid_op 0
		.amdhsa_exception_fp_denorm_src 0
		.amdhsa_exception_fp_ieee_div_zero 0
		.amdhsa_exception_fp_ieee_overflow 0
		.amdhsa_exception_fp_ieee_underflow 0
		.amdhsa_exception_fp_ieee_inexact 0
		.amdhsa_exception_int_div_zero 0
	.end_amdhsa_kernel

; __global__ void __launch_bounds__(512, 2) mega_fwd(Params p) {
amdhsa.kernels:
  - .agpr_count:     0
    .args:
      - .offset:         0
        .size:           184
        .value_kind:     by_value
      - .offset:         184
        .size:           4
        .value_kind:     hidden_block_count_x
      - .offset:         188
        .size:           4
        .value_kind:     hidden_block_count_y
      - .offset:         192
        .size:           4
        .value_kind:     hidden_block_count_z
      - .offset:         196
        .size:           2
        .value_kind:     hidden_group_size_x
      - .offset:         198
        .size:           2
        .value_kind:     hidden_group_size_y
      - .offset:         200
        .size:           2
        .value_kind:     hidden_group_size_z
      - .offset:         202
        .size:           2
        .value_kind:     hidden_remainder_x
      - .offset:         204
        .size:           2
        .value_kind:     hidden_remainder_y
      - .offset:         206
        .size:           2
        .value_kind:     hidden_remainder_z
      - .offset:         224
        .size:           8
        .value_kind:     hidden_global_offset_x
      - .offset:         232
        .size:           8
        .value_kind:     hidden_global_offset_y
      - .offset:         240
        .size:           8
        .value_kind:     hidden_global_offset_z
      - .offset:         248
        .size:           2
        .value_kind:     hidden_grid_dims
      - .offset:         304
        .size:           4
        .value_kind:     hidden_dynamic_lds_size
    .group_segment_fixed_size: 0
    .kernarg_segment_align: 8
    .kernarg_segment_size: 440
    .language:       OpenCL C
    .language_version:
      - 2
      - 0
    .max_flat_workgroup_size: 512
    .name:           _Z8mega_fwd6Params
    .private_segment_fixed_size: 0
    .sgpr_count:     106
    .sgpr_spill_count: 0
    .symbol:         _Z8mega_fwd6Params.kd
    .uniform_work_group_size: 1
    .uses_dynamic_stack: false
    .vgpr_count:     232
    .vgpr_spill_count: 0
    .wavefront_size: 64
